# adds EpiLru x-load hoist, p2_prep row-loop load batching and removal of the merge-phase per-unit vmcnt(0) drain on top of the conv_weights version
# baseline (speedup 1.0000x reference)
; __device__ __forceinline__ float bf2f(bf16_t h) { return __uint_as_float(((unsigned)h) << 16); }
; __device__ __forceinline__ void p2_prep(PP P, int l, unsigned char* ws, int gw, int ngw, int tid_) {
;     ...
;         for (int u = 0; u < 4; ++u) { const int m = M - 1 - (mb + u * ngw); const bf16_t* ua = UA + (size_t)m * 768;
;             q4[u] = (u32x4){0u, 0u, 0u, 0u}; k4[u] = (u32x4){0u, 0u, 0u, 0u}; x1[u] = 0.f; x2[u] = 0.f; dtr[u] = 0.f; cc[u] = (f32x2){0.f, 0.f};
;             if (lane < 48) q4[u] = *(const u32x4*)(ua + lane * 8);
;             if (lane < 32) k4[u] = *(const u32x4*)(ua + 384 + lane * 8);
;             if (lane < 16) { x1[u] = bf2f(ua[640 + lane]); x2[u] = bf2f(ua[656 + lane]); cc[u] = CS[(size_t)m * 16 + lane]; }
;             if (lane < 8) dtr[u] = bf2f(ua[672 + lane]); }
.LBB0_381:
	s_or_b64 exec, exec, s[16:17]
	s_ashr_i32 s1, s0, 31
	v_mov_b32_e32 v69, 0
	v_lshlrev_b32_e32 v70, 1, v34
	v_mov_b32_e32 v56, 0
	v_mov_b32_e32 v57, 0
	v_mov_b32_e32 v58, 0
	v_mov_b32_e32 v59, 0
	s_and_saveexec_b64 s[16:17], s[8:9]
	s_cbranch_execz .LBB0_383
	s_lshl_b64 s[28:29], s[0:1], 7
	v_lshl_add_u64 v[2:3], v[36:37], 0, s[28:29]
	s_waitcnt lgkmcnt(0)
	global_load_ushort v76, v70, s[14:15] offset:1280
	global_load_ushort v77, v70, s[14:15] offset:1312
	global_load_dwordx2 v[56:57], v[2:3], off
	s_nop 0
.LBB0_383:
	s_or_b64 exec, exec, s[16:17]
	s_and_saveexec_b64 s[16:17], s[10:11]
	s_cbranch_execz .LBB0_385
	global_load_ushort v78, v70, s[14:15] offset:1344
	s_nop 0
.LBB0_385:
	s_or_b64 exec, exec, s[16:17]
	s_and_saveexec_b64 s[16:17], s[10:11]
	global_load_dword v85, v[40:41], off
	s_or_b64 exec, exec, s[16:17]
	v_readlane_b32 s14, v255, 9
	s_add_i32 s40, s14, s0
	s_mul_i32 s14, s40, 0x600
	s_mul_hi_i32 s15, s40, 0x600
	s_add_u32 s14, s31, s14
	s_addc_u32 s15, s36, s15
	v_mov_b32_e32 v18, 0
	v_mov_b32_e32 v22, 0
	v_mov_b32_e32 v23, 0
	v_mov_b32_e32 v24, 0
	v_mov_b32_e32 v25, 0
	s_and_saveexec_b64 s[16:17], vcc
	s_cbranch_execz .LBB0_387
	global_load_dwordx4 v[22:25], v44, s[14:15]

; __device__ __forceinline__ float bf2f(bf16_t h) { return __uint_as_float(((unsigned)h) << 16); }
; __device__ __forceinline__ void p2_prep(PP P, int l, unsigned char* ws, int gw, int ngw, int tid_) {
;     ...
;         for (int u = 0; u < 4; ++u) { const int m = M - 1 - (mb + u * ngw); const bf16_t* ua = UA + (size_t)m * 768;
;             q4[u] = (u32x4){0u, 0u, 0u, 0u}; k4[u] = (u32x4){0u, 0u, 0u, 0u}; x1[u] = 0.f; x2[u] = 0.f; dtr[u] = 0.f; cc[u] = (f32x2){0.f, 0.f};
;             if (lane < 48) q4[u] = *(const u32x4*)(ua + lane * 8);
;             if (lane < 32) k4[u] = *(const u32x4*)(ua + 384 + lane * 8);
;             if (lane < 16) { x1[u] = bf2f(ua[640 + lane]); x2[u] = bf2f(ua[656 + lane]); cc[u] = CS[(size_t)m * 16 + lane]; }
;             if (lane < 8) dtr[u] = bf2f(ua[672 + lane]); }
.LBB0_389:
	s_or_b64 exec, exec, s[16:17]
	s_ashr_i32 s41, s40, 31
	v_mov_b32_e32 v68, 0
	v_mov_b32_e32 v52, 0
	v_mov_b32_e32 v53, 0
	v_mov_b32_e32 v54, 0
	v_mov_b32_e32 v55, 0
	s_and_saveexec_b64 s[16:17], s[8:9]
	s_cbranch_execz .LBB0_391
	s_lshl_b64 s[28:29], s[40:41], 7
	v_lshl_add_u64 v[2:3], v[36:37], 0, s[28:29]
	s_waitcnt lgkmcnt(0)
	global_load_ushort v79, v70, s[14:15] offset:1280
	global_load_ushort v80, v70, s[14:15] offset:1312
	global_load_dwordx2 v[52:53], v[2:3], off
	s_nop 0
.LBB0_391:
	s_or_b64 exec, exec, s[16:17]
	s_and_saveexec_b64 s[16:17], s[10:11]
	s_cbranch_execz .LBB0_393
	global_load_ushort v81, v70, s[14:15] offset:1344
	s_nop 0

; __device__ __forceinline__ float bf2f(bf16_t h) { return __uint_as_float(((unsigned)h) << 16); }
; __device__ __forceinline__ void p2_prep(PP P, int l, unsigned char* ws, int gw, int ngw, int tid_) {
;     ...
;         for (int u = 0; u < 4; ++u) { const int m = M - 1 - (mb + u * ngw); const bf16_t* ua = UA + (size_t)m * 768;
;             q4[u] = (u32x4){0u, 0u, 0u, 0u}; k4[u] = (u32x4){0u, 0u, 0u, 0u}; x1[u] = 0.f; x2[u] = 0.f; dtr[u] = 0.f; cc[u] = (f32x2){0.f, 0.f};
;             if (lane < 48) q4[u] = *(const u32x4*)(ua + lane * 8);
;             if (lane < 32) k4[u] = *(const u32x4*)(ua + 384 + lane * 8);
;             if (lane < 16) { x1[u] = bf2f(ua[640 + lane]); x2[u] = bf2f(ua[656 + lane]); cc[u] = CS[(size_t)m * 16 + lane]; }
;             if (lane < 8) dtr[u] = bf2f(ua[672 + lane]); }
.LBB0_397:
	s_or_b64 exec, exec, s[16:17]
	s_ashr_i32 s39, s38, 31
	v_mov_b32_e32 v67, 0
	v_mov_b32_e32 v48, 0
	v_mov_b32_e32 v49, 0
	v_mov_b32_e32 v50, 0
	v_mov_b32_e32 v51, 0
	s_and_saveexec_b64 s[16:17], s[8:9]
	s_cbranch_execz .LBB0_399
	s_lshl_b64 s[28:29], s[38:39], 7
	v_lshl_add_u64 v[2:3], v[36:37], 0, s[28:29]
	s_waitcnt lgkmcnt(0)
	global_load_ushort v82, v70, s[14:15] offset:1280
	global_load_ushort v83, v70, s[14:15] offset:1312
	global_load_dwordx2 v[48:49], v[2:3], off
	s_nop 0
.LBB0_399:
	s_or_b64 exec, exec, s[16:17]
	s_and_saveexec_b64 s[16:17], s[10:11]
	s_cbranch_execz .LBB0_401
	global_load_ushort v84, v70, s[14:15] offset:1344
	s_nop 0

; __device__ __forceinline__ void unpack8(u32x4 w, f32x4& a, f32x4& b) { a = (f32x4){bflo(w.x), bfhi(w.x), bflo(w.y), bfhi(w.y)}; b = (f32x4){bflo(w.z), bfhi(w.z), bflo(w.w), bfhi(w.w)}; }
; __device__ __forceinline__ void p2_prep(PP P, int l, unsigned char* ws, int gw, int ngw, int tid_) {
;     ...
;         for (int u = 0; u < 4; ++u) { const int m = M - 1 - (mb + u * ngw);
;             f32x4 a, b; unpack8(q4[u], a, b); float s = (a[0]*a[0]+a[1]*a[1])+(a[2]*a[2]+a[3]*a[3])+(b[0]*b[0]+b[1]*b[1])+(b[2]*b[2]+b[3]*b[3]);
;             unpack8(k4[u], a, b); float s2 = (a[0]*a[0]+a[1]*a[1])+(a[2]*a[2]+a[3]*a[3])+(b[0]*b[0]+b[1]*b[1])+(b[2]*b[2]+b[3]*b[3]);
;             s = wave_sum(s); s2 = wave_sum(s2);
;             if (lane == 0) { RSQ[m] = rsqrtf(s * (1.f / 384.f) + EPS); RSKV[m] = rsqrtf(s2 * (1.f / 256.f) + EPS); }
.LBB0_409:
	s_or_b64 exec, exec, s[16:17]
	s_waitcnt vmcnt(0)
	s_and_saveexec_b64 s[16:17], s[8:9]
	v_lshlrev_b32_e32 v58, 16, v76
	v_lshlrev_b32_e32 v59, 16, v77
	v_lshlrev_b32_e32 v54, 16, v79
	v_lshlrev_b32_e32 v55, 16, v80
	v_lshlrev_b32_e32 v50, 16, v82
	v_lshlrev_b32_e32 v51, 16, v83
	s_or_b64 exec, exec, s[16:17]
	s_and_saveexec_b64 s[16:17], s[10:11]
	v_lshlrev_b32_e32 v69, 16, v78
	v_lshlrev_b32_e32 v68, 16, v81
	v_lshlrev_b32_e32 v67, 16, v84
	s_or_b64 exec, exec, s[16:17]
	v_and_b32_e32 v73, 0xffff0000, v30
	v_and_b32_e32 v72, 0xffff0000, v26
	v_lshlrev_b32_e32 v70, 16, v26
	v_lshlrev_b32_e32 v71, 16, v30
	v_pk_mul_f32 v[72:73], v[72:73], v[72:73]
	v_and_b32_e32 v30, 0xffff0000, v27
	v_pk_fma_f32 v[70:71], v[70:71], v[70:71], v[72:73]
	v_lshlrev_b32_e32 v73, 16, v31
	v_and_b32_e32 v31, 0xffff0000, v31
	v_lshlrev_b32_e32 v72, 16, v27
	v_pk_mul_f32 v[26:27], v[30:31], v[30:31]
	v_lshlrev_b32_e32 v30, 16, v28
	v_pk_fma_f32 v[26:27], v[72:73], v[72:73], v[26:27]
	v_and_b32_e32 v73, 0xffff0000, v32
	v_and_b32_e32 v72, 0xffff0000, v28
	v_lshlrev_b32_e32 v31, 16, v32
	v_pk_mul_f32 v[72:73], v[72:73], v[72:73]
	v_lshlrev_b32_e32 v74, 16, v29
	v_lshlrev_b32_e32 v75, 16, v33
	v_and_b32_e32 v33, 0xffff0000, v33
	v_and_b32_e32 v32, 0xffff0000, v29
	v_pk_add_f32 v[26:27], v[70:71], v[26:27]
	v_pk_fma_f32 v[28:29], v[30:31], v[30:31], v[72:73]
	s_nop 0
	v_pk_add_f32 v[26:27], v[28:29], v[26:27]
	v_pk_mul_f32 v[28:29], v[32:33], v[32:33]
	s_nop 0
	v_pk_fma_f32 v[28:29], v[74:75], v[74:75], v[28:29]
	s_nop 0
	v_pk_add_f32 v[26:27], v[28:29], v[26:27]
	ds_bpermute_b32 v29, v60, v27
	ds_bpermute_b32 v28, v60, v26
	s_waitcnt lgkmcnt(0)
	v_pk_add_f32 v[26:27], v[26:27], v[28:29]
	ds_bpermute_b32 v29, v61, v27
	ds_bpermute_b32 v28, v61, v26
	s_waitcnt lgkmcnt(0)
	v_pk_add_f32 v[26:27], v[26:27], v[28:29]
	ds_bpermute_b32 v29, v62, v27
	ds_bpermute_b32 v28, v62, v26
	s_waitcnt lgkmcnt(0)
	v_pk_add_f32 v[26:27], v[26:27], v[28:29]
	ds_bpermute_b32 v29, v63, v27
	ds_bpermute_b32 v28, v63, v26
	s_waitcnt lgkmcnt(0)
	v_pk_add_f32 v[26:27], v[26:27], v[28:29]
	ds_bpermute_b32 v29, v64, v27
	ds_bpermute_b32 v28, v64, v26
	s_waitcnt lgkmcnt(0)
	v_pk_add_f32 v[26:27], v[26:27], v[28:29]
	ds_bpermute_b32 v29, v65, v27
	ds_bpermute_b32 v28, v65, v26
	s_and_saveexec_b64 s[42:43], s[12:13]
	s_cbranch_execz .LBB0_412
	s_mov_b32 s14, 0x3b800000
	s_waitcnt lgkmcnt(0)
	v_pk_add_f32 v[26:27], v[26:27], v[28:29]
	s_mov_b32 s15, 0x3b2aaaab
	v_pk_fma_f32 v[26:27], v[26:27], s[14:15], v[248:249] op_sel_hi:[1,1,0]
	s_mov_b32 s16, 0x800000
	v_mul_f32_e32 v28, 0x4b800000, v27
	v_cmp_gt_f32_e64 s[14:15], s16, v27
	v_cmp_gt_f32_e64 s[16:17], s16, v26
	s_lshl_b64 s[50:51], s[0:1], 2
	v_cndmask_b32_e64 v27, v27, v28, s[14:15]
	v_rsq_f32_e32 v27, v27
	v_mul_f32_e32 v28, 0x4b800000, v26
	v_cndmask_b32_e64 v26, v26, v28, s[16:17]
	v_rsq_f32_e32 v26, v26
	s_add_u32 s52, s44, s50
	v_mul_f32_e32 v28, 0x45800000, v27
	s_addc_u32 s53, s45, s51
	v_cndmask_b32_e64 v27, v27, v28, s[14:15]
	global_store_dword v1, v27, s[52:53]
	v_readlane_b32 s52, v255, 33
	v_mul_f32_e32 v27, 0x45800000, v26
	s_add_u32 s14, s46, s50
	v_readlane_b32 s53, v255, 34
	v_cndmask_b32_e64 v26, v26, v27, s[16:17]
	s_addc_u32 s15, s47, s51
	global_store_dword v1, v26, s[14:15]
	s_or_b64 exec, exec, s[42:43]
	s_and_saveexec_b64 s[14:15], s[8:9]
	s_cbranch_execnz .LBB0_413

; __device__ __forceinline__ void p2_prep(PP P, int l, unsigned char* ws, int gw, int ngw, int tid_) {
;     ...
;             if (lane < 8) { const float v = dtr[u] + dtb[lane]; DTF[(size_t)m * 8 + lane] = v > 20.f ? v : log1pf(__expf(v)); } }
.LBB0_414:
	v_mov_b32_e32 v26, v85
	s_mov_b32 s14, 0x41a00000
	s_nop 0
	v_add_f32_e32 v26, v69, v26
	v_cmp_nlt_f32_e64 s[14:15], s14, v26
	s_and_saveexec_b64 s[42:43], s[14:15]
	s_cbranch_execz .LBB0_416
	v_mul_f32_e32 v26, 0x3fb8aa3b, v26
	v_exp_f32_e32 v69, v26
	s_waitcnt lgkmcnt(0)
	v_add_f32_e32 v28, 1.0, v69
	v_frexp_mant_f32_e32 v30, v28
	v_cvt_f64_f32_e32 v[26:27], v28
	v_frexp_exp_i32_f64_e32 v26, v[26:27]
	v_cmp_gt_f32_e64 s[14:15], s62, v30
	v_add_f32_e32 v29, -1.0, v28
	v_sub_f32_e32 v31, v29, v28
	v_subbrev_co_u32_e64 v56, s[14:15], 0, v26, s[14:15]
	v_sub_u32_e32 v26, 0, v56
	v_sub_f32_e32 v29, v69, v29
	v_add_f32_e32 v31, 1.0, v31
	v_ldexp_f32 v27, v28, v26
	v_add_f32_e32 v29, v29, v31
	v_add_f32_e32 v28, -1.0, v27
	v_add_f32_e32 v30, 1.0, v27
	v_ldexp_f32 v26, v29, v26
	v_add_f32_e32 v29, 1.0, v28
	v_add_f32_e32 v31, -1.0, v30
	v_sub_f32_e32 v29, v27, v29
	v_sub_f32_e32 v27, v27, v31
	v_add_f32_e32 v29, v26, v29
	v_add_f32_e32 v26, v26, v27
	v_add_f32_e32 v57, v30, v26
	v_rcp_f32_e32 v59, v57
	v_sub_f32_e32 v27, v57, v30
	v_sub_f32_e32 v58, v26, v27
	v_add_f32_e32 v27, v28, v29
	v_mul_f32_e32 v71, v27, v59
	v_sub_f32_e32 v26, v27, v28
	v_mul_f32_e32 v28, v57, v71
	v_fma_f32 v30, v71, v57, -v28
	v_fmac_f32_e32 v30, v71, v58
	v_sub_f32_e32 v70, v29, v26
	v_add_f32_e32 v26, v28, v30
	v_sub_f32_e32 v29, v27, v26
	v_pk_add_f32 v[32:33], v[26:27], v[28:29] neg_lo:[0,1] neg_hi:[0,1]
	v_mov_b32_e32 v31, v26
	v_pk_add_f32 v[26:27], v[32:33], v[30:31] neg_lo:[0,1] neg_hi:[0,1]
	s_mov_b32 s14, 0x7f800000
	v_add_f32_e32 v27, v70, v27
	v_add_f32_e32 v26, v26, v27
	v_add_f32_e32 v27, v29, v26
	v_mul_f32_e32 v70, v59, v27
	v_mul_f32_e32 v28, v57, v70
	v_fma_f32 v30, v70, v57, -v28
	v_fmac_f32_e32 v30, v70, v58
	v_sub_f32_e32 v29, v29, v27
	v_add_f32_e32 v57, v26, v29
	v_add_f32_e32 v26, v28, v30
	v_sub_f32_e32 v29, v27, v26
	v_pk_add_f32 v[32:33], v[26:27], v[28:29] neg_lo:[0,1] neg_hi:[0,1]
	v_mov_b32_e32 v31, v26
	v_pk_add_f32 v[26:27], v[32:33], v[30:31] neg_lo:[0,1] neg_hi:[0,1]
	v_cmp_neq_f32_e64 s[14:15], s14, v69
	v_add_f32_e32 v27, v57, v27
	v_add_f32_e32 v26, v26, v27
	v_add_f32_e32 v27, v71, v70
	v_add_f32_e32 v26, v29, v26
	v_sub_f32_e32 v28, v27, v71
	v_mul_f32_e32 v26, v59, v26
	v_sub_f32_e32 v28, v70, v28
	v_add_f32_e32 v28, v28, v26
	v_add_f32_e32 v30, v27, v28
	v_mul_f32_e32 v31, v30, v30
	v_fmamk_f32 v26, v31, 0x3e9b6dac, v233
	v_fmaak_f32 v197, v31, v26, 0x3f2aaada
	v_cvt_f32_i32_e32 v26, v56
	v_sub_f32_e32 v27, v30, v27
	v_sub_f32_e32 v27, v28, v27
	v_ldexp_f32 v32, v27, 1
	v_mul_f32_e32 v27, v30, v31
	v_ldexp_f32 v29, v30, 1
	v_pk_mul_f32 v[30:31], v[26:27], v[196:197]
	s_nop 0
	v_fma_f32 v28, v26, s94, -v30
	v_fmac_f32_e32 v28, 0xb102e308, v26
	v_pk_add_f32 v[26:27], v[30:31], v[28:29]
	s_nop 0
	v_sub_f32_e32 v29, v27, v29
	v_sub_f32_e32 v29, v31, v29
	v_add_f32_e32 v33, v32, v29
	v_mov_b32_e32 v32, v30
	v_pk_add_f32 v[30:31], v[26:27], v[30:31] neg_lo:[0,1] neg_hi:[0,1]
	v_pk_add_f32 v[56:57], v[26:27], v[32:33]
	v_mov_b32_e32 v29, v26
	v_mov_b32_e32 v31, v57
	v_pk_add_f32 v[58:59], v[28:29], v[30:31] neg_lo:[0,1] neg_hi:[0,1]
	v_pk_add_f32 v[28:29], v[28:29], v[30:31]
	v_mov_b32_e32 v32, v33
	v_pk_add_f32 v[30:31], v[28:29], v[26:27] op_sel:[1,0] op_sel_hi:[0,1] neg_lo:[0,1] neg_hi:[0,1]
	v_pk_add_f32 v[70:71], v[56:57], v[30:31] op_sel_hi:[1,0] neg_lo:[0,1] neg_hi:[0,1]
	v_mov_b32_e32 v56, v57
	v_mov_b32_e32 v57, v29
	v_pk_mov_b32 v[30:31], v[26:27], v[30:31] op_sel:[1,0]
	v_mov_b32_e32 v33, v26
	v_pk_add_f32 v[30:31], v[56:57], v[30:31] neg_lo:[0,1] neg_hi:[0,1]
	v_mov_b32_e32 v70, v58
	v_pk_add_f32 v[26:27], v[32:33], v[30:31] neg_lo:[0,1] neg_hi:[0,1]
	v_mov_b32_e32 v59, v29
	v_pk_add_f32 v[30:31], v[70:71], v[26:27]
	s_nop 0
	v_pk_add_f32 v[32:33], v[30:31], v[30:31] op_sel:[0,1] op_sel_hi:[1,0]
	s_nop 0
	v_pk_add_f32 v[28:29], v[28:29], v[32:33] op_sel:[1,0] op_sel_hi:[0,1]
	v_mov_b32_e32 v31, v28
	v_pk_add_f32 v[56:57], v[30:31], v[58:59] neg_lo:[0,1] neg_hi:[0,1]
	v_mov_b32_e32 v27, v32
	v_sub_f32_e32 v29, v30, v56
	v_pk_add_f32 v[26:27], v[26:27], v[56:57] neg_lo:[0,1] neg_hi:[0,1]
	v_sub_f32_e32 v29, v58, v29
	v_add_f32_e32 v26, v26, v29
	v_add_f32_e32 v26, v26, v27
	v_add_f32_e32 v26, v28, v26
	v_cndmask_b32_e64 v26, v227, v26, s[14:15]
	v_cmp_ngt_f32_e64 s[14:15], -1.0, v69
	s_nop 1
	v_cndmask_b32_e64 v26, v229, v26, s[14:15]
	v_cmp_neq_f32_e64 s[14:15], -1.0, v69
	s_nop 1
	v_cndmask_b32_e64 v26, v232, v26, s[14:15]
	v_cmp_lt_f32_e64 s[14:15], |v69|, s96
	s_nop 1
	v_cndmask_b32_e64 v26, v26, v69, s[14:15]

; __device__ __forceinline__ void p2_prep(PP P, int l, unsigned char* ws, int gw, int ngw, int tid_) {
;     ...
;             if (lane < 8) { const float v = dtr[u] + dtb[lane]; DTF[(size_t)m * 8 + lane] = v > 20.f ? v : log1pf(__expf(v)); } }
.LBB0_422:
	v_mov_b32_e32 v18, v85
	s_mov_b32 s1, 0x41a00000
	s_nop 0
	v_add_f32_e32 v18, v68, v18
	v_cmp_nlt_f32_e64 s[14:15], s1, v18
	s_and_saveexec_b64 s[42:43], s[14:15]
	s_cbranch_execz .LBB0_424
	v_mul_f32_e32 v18, 0x3fb8aa3b, v18
	v_exp_f32_e32 v32, v18
	s_mov_b32 s1, 0x7f800000
	s_waitcnt lgkmcnt(0)
	v_add_f32_e32 v20, 1.0, v32
	v_frexp_mant_f32_e32 v22, v20
	v_cvt_f64_f32_e32 v[18:19], v20
	v_frexp_exp_i32_f64_e32 v18, v[18:19]
	v_cmp_gt_f32_e64 s[14:15], s62, v22
	v_add_f32_e32 v21, -1.0, v20
	v_sub_f32_e32 v23, v21, v20
	v_subbrev_co_u32_e64 v26, s[14:15], 0, v18, s[14:15]
	v_sub_u32_e32 v18, 0, v26
	v_sub_f32_e32 v21, v32, v21
	v_add_f32_e32 v23, 1.0, v23
	v_ldexp_f32 v19, v20, v18
	v_add_f32_e32 v21, v21, v23
	v_add_f32_e32 v20, -1.0, v19
	v_add_f32_e32 v22, 1.0, v19
	v_ldexp_f32 v18, v21, v18
	v_add_f32_e32 v21, 1.0, v20
	v_add_f32_e32 v23, -1.0, v22
	v_sub_f32_e32 v21, v19, v21
	v_sub_f32_e32 v19, v19, v23
	v_add_f32_e32 v21, v18, v21
	v_add_f32_e32 v18, v18, v19
	v_add_f32_e32 v27, v22, v18
	v_rcp_f32_e32 v29, v27
	v_sub_f32_e32 v19, v27, v22
	v_sub_f32_e32 v28, v18, v19
	v_add_f32_e32 v19, v20, v21
	v_mul_f32_e32 v31, v19, v29
	v_sub_f32_e32 v18, v19, v20
	v_mul_f32_e32 v20, v27, v31
	v_fma_f32 v22, v31, v27, -v20
	v_fmac_f32_e32 v22, v31, v28
	v_sub_f32_e32 v30, v21, v18
	v_add_f32_e32 v18, v20, v22
	v_sub_f32_e32 v21, v19, v18
	v_pk_add_f32 v[24:25], v[18:19], v[20:21] neg_lo:[0,1] neg_hi:[0,1]
	v_mov_b32_e32 v23, v18
	v_pk_add_f32 v[18:19], v[24:25], v[22:23] neg_lo:[0,1] neg_hi:[0,1]
	v_cmp_neq_f32_e64 s[14:15], s1, v32
	v_add_f32_e32 v19, v30, v19
	v_add_f32_e32 v18, v18, v19
	v_add_f32_e32 v19, v21, v18
	v_mul_f32_e32 v30, v29, v19
	v_mul_f32_e32 v20, v27, v30
	v_fma_f32 v22, v30, v27, -v20
	v_fmac_f32_e32 v22, v30, v28
	v_sub_f32_e32 v21, v21, v19
	v_add_f32_e32 v27, v18, v21
	v_add_f32_e32 v18, v20, v22
	v_sub_f32_e32 v21, v19, v18
	v_pk_add_f32 v[24:25], v[18:19], v[20:21] neg_lo:[0,1] neg_hi:[0,1]
	v_mov_b32_e32 v23, v18
	v_pk_add_f32 v[18:19], v[24:25], v[22:23] neg_lo:[0,1] neg_hi:[0,1]
	s_nop 0
	v_add_f32_e32 v19, v27, v19
	v_add_f32_e32 v18, v18, v19
	v_add_f32_e32 v19, v31, v30
	v_add_f32_e32 v18, v21, v18
	v_sub_f32_e32 v20, v19, v31
	v_mul_f32_e32 v18, v29, v18
	v_sub_f32_e32 v20, v30, v20
	v_add_f32_e32 v20, v20, v18
	v_add_f32_e32 v22, v19, v20
	v_mul_f32_e32 v23, v22, v22
	v_fmamk_f32 v18, v23, 0x3e9b6dac, v233
	v_fmaak_f32 v197, v23, v18, 0x3f2aaada
	v_cvt_f32_i32_e32 v18, v26
	v_sub_f32_e32 v19, v22, v19
	v_sub_f32_e32 v19, v20, v19
	v_ldexp_f32 v24, v19, 1
	v_mul_f32_e32 v19, v22, v23
	v_ldexp_f32 v21, v22, 1
	v_pk_mul_f32 v[22:23], v[18:19], v[196:197]
	s_nop 0
	v_fma_f32 v20, v18, s94, -v22
	v_fmac_f32_e32 v20, 0xb102e308, v18
	v_pk_add_f32 v[18:19], v[22:23], v[20:21]
	s_nop 0
	v_sub_f32_e32 v21, v19, v21
	v_sub_f32_e32 v21, v23, v21
	v_add_f32_e32 v25, v24, v21
	v_mov_b32_e32 v24, v22
	v_pk_add_f32 v[22:23], v[18:19], v[22:23] neg_lo:[0,1] neg_hi:[0,1]
	v_pk_add_f32 v[26:27], v[18:19], v[24:25]
	v_mov_b32_e32 v21, v18
	v_mov_b32_e32 v23, v27
	v_pk_add_f32 v[28:29], v[20:21], v[22:23] neg_lo:[0,1] neg_hi:[0,1]
	v_pk_add_f32 v[20:21], v[20:21], v[22:23]
	v_mov_b32_e32 v24, v25
	v_pk_add_f32 v[22:23], v[20:21], v[18:19] op_sel:[1,0] op_sel_hi:[0,1] neg_lo:[0,1] neg_hi:[0,1]
	v_pk_add_f32 v[30:31], v[26:27], v[22:23] op_sel_hi:[1,0] neg_lo:[0,1] neg_hi:[0,1]
	v_mov_b32_e32 v26, v27
	v_mov_b32_e32 v27, v21
	v_pk_mov_b32 v[22:23], v[18:19], v[22:23] op_sel:[1,0]
	v_mov_b32_e32 v25, v18
	v_pk_add_f32 v[22:23], v[26:27], v[22:23] neg_lo:[0,1] neg_hi:[0,1]
	v_mov_b32_e32 v30, v28
	v_pk_add_f32 v[18:19], v[24:25], v[22:23] neg_lo:[0,1] neg_hi:[0,1]
	v_mov_b32_e32 v29, v21
	v_pk_add_f32 v[22:23], v[30:31], v[18:19]
	s_nop 0
	v_pk_add_f32 v[24:25], v[22:23], v[22:23] op_sel:[0,1] op_sel_hi:[1,0]
	s_nop 0
	v_pk_add_f32 v[20:21], v[20:21], v[24:25] op_sel:[1,0] op_sel_hi:[0,1]
	v_mov_b32_e32 v23, v20
	v_pk_add_f32 v[26:27], v[22:23], v[28:29] neg_lo:[0,1] neg_hi:[0,1]
	v_mov_b32_e32 v19, v24
	v_sub_f32_e32 v21, v22, v26
	v_pk_add_f32 v[18:19], v[18:19], v[26:27] neg_lo:[0,1] neg_hi:[0,1]
	v_sub_f32_e32 v21, v28, v21
	v_add_f32_e32 v18, v18, v21
	v_add_f32_e32 v18, v18, v19
	v_add_f32_e32 v18, v20, v18
	v_cndmask_b32_e64 v18, v227, v18, s[14:15]
	v_cmp_ngt_f32_e64 s[14:15], -1.0, v32
	s_nop 1
	v_cndmask_b32_e64 v18, v229, v18, s[14:15]
	v_cmp_neq_f32_e64 s[14:15], -1.0, v32
	s_nop 1
	v_cndmask_b32_e64 v18, v232, v18, s[14:15]
	v_cmp_lt_f32_e64 s[14:15], |v32|, s96
	s_nop 1
	v_cndmask_b32_e64 v18, v18, v32, s[14:15]

; __device__ __forceinline__ void p2_prep(PP P, int l, unsigned char* ws, int gw, int ngw, int tid_) {
;     ...
;             if (lane < 8) { const float v = dtr[u] + dtb[lane]; DTF[(size_t)m * 8 + lane] = v > 20.f ? v : log1pf(__expf(v)); } }
.LBB0_430:
	v_mov_b32_e32 v10, v85
	s_mov_b32 s1, 0x41a00000
	s_nop 0
	v_add_f32_e32 v10, v67, v10
	v_cmp_nlt_f32_e64 s[14:15], s1, v10
	s_and_saveexec_b64 s[40:41], s[14:15]
	s_cbranch_execz .LBB0_432
	v_mul_f32_e32 v10, 0x3fb8aa3b, v10
	v_exp_f32_e32 v24, v10
	s_mov_b32 s1, 0x7f800000
	s_waitcnt lgkmcnt(0)
	v_add_f32_e32 v12, 1.0, v24
	v_frexp_mant_f32_e32 v14, v12
	v_cvt_f64_f32_e32 v[10:11], v12
	v_frexp_exp_i32_f64_e32 v10, v[10:11]
	v_cmp_gt_f32_e64 s[14:15], s62, v14
	v_add_f32_e32 v13, -1.0, v12
	v_sub_f32_e32 v15, v13, v12
	v_subbrev_co_u32_e64 v18, s[14:15], 0, v10, s[14:15]
	v_sub_u32_e32 v10, 0, v18
	v_sub_f32_e32 v13, v24, v13
	v_add_f32_e32 v15, 1.0, v15
	v_ldexp_f32 v11, v12, v10
	v_add_f32_e32 v13, v13, v15
	v_add_f32_e32 v12, -1.0, v11
	v_add_f32_e32 v14, 1.0, v11
	v_ldexp_f32 v10, v13, v10
	v_add_f32_e32 v13, 1.0, v12
	v_add_f32_e32 v15, -1.0, v14
	v_sub_f32_e32 v13, v11, v13
	v_sub_f32_e32 v11, v11, v15
	v_add_f32_e32 v13, v10, v13
	v_add_f32_e32 v10, v10, v11
	v_add_f32_e32 v19, v14, v10
	v_rcp_f32_e32 v21, v19
	v_sub_f32_e32 v11, v19, v14
	v_sub_f32_e32 v20, v10, v11
	v_add_f32_e32 v11, v12, v13
	v_mul_f32_e32 v23, v11, v21
	v_sub_f32_e32 v10, v11, v12
	v_mul_f32_e32 v12, v19, v23
	v_fma_f32 v14, v23, v19, -v12
	v_fmac_f32_e32 v14, v23, v20
	v_sub_f32_e32 v22, v13, v10
	v_add_f32_e32 v10, v12, v14
	v_sub_f32_e32 v13, v11, v10
	v_pk_add_f32 v[16:17], v[10:11], v[12:13] neg_lo:[0,1] neg_hi:[0,1]
	v_mov_b32_e32 v15, v10
	v_pk_add_f32 v[10:11], v[16:17], v[14:15] neg_lo:[0,1] neg_hi:[0,1]
	v_cmp_neq_f32_e64 s[14:15], s1, v24
	v_add_f32_e32 v11, v22, v11
	v_add_f32_e32 v10, v10, v11
	v_add_f32_e32 v11, v13, v10
	v_mul_f32_e32 v22, v21, v11
	v_mul_f32_e32 v12, v19, v22
	v_fma_f32 v14, v22, v19, -v12
	v_fmac_f32_e32 v14, v22, v20
	v_sub_f32_e32 v13, v13, v11
	v_add_f32_e32 v19, v10, v13
	v_add_f32_e32 v10, v12, v14
	v_sub_f32_e32 v13, v11, v10
	v_pk_add_f32 v[16:17], v[10:11], v[12:13] neg_lo:[0,1] neg_hi:[0,1]
	v_mov_b32_e32 v15, v10
	v_pk_add_f32 v[10:11], v[16:17], v[14:15] neg_lo:[0,1] neg_hi:[0,1]
	s_nop 0
	v_add_f32_e32 v11, v19, v11
	v_add_f32_e32 v10, v10, v11
	v_add_f32_e32 v11, v23, v22
	v_add_f32_e32 v10, v13, v10
	v_sub_f32_e32 v12, v11, v23
	v_mul_f32_e32 v10, v21, v10
	v_sub_f32_e32 v12, v22, v12
	v_add_f32_e32 v12, v12, v10
	v_add_f32_e32 v14, v11, v12
	v_mul_f32_e32 v15, v14, v14
	v_fmamk_f32 v10, v15, 0x3e9b6dac, v233
	v_fmaak_f32 v197, v15, v10, 0x3f2aaada
	v_cvt_f32_i32_e32 v10, v18
	v_sub_f32_e32 v11, v14, v11
	v_sub_f32_e32 v11, v12, v11
	v_ldexp_f32 v16, v11, 1
	v_mul_f32_e32 v11, v14, v15
	v_ldexp_f32 v13, v14, 1
	v_pk_mul_f32 v[14:15], v[10:11], v[196:197]
	s_nop 0
	v_fma_f32 v12, v10, s94, -v14
	v_fmac_f32_e32 v12, 0xb102e308, v10
	v_pk_add_f32 v[10:11], v[14:15], v[12:13]
	s_nop 0
	v_sub_f32_e32 v13, v11, v13
	v_sub_f32_e32 v13, v15, v13
	v_add_f32_e32 v17, v16, v13
	v_mov_b32_e32 v16, v14
	v_pk_add_f32 v[14:15], v[10:11], v[14:15] neg_lo:[0,1] neg_hi:[0,1]
	v_pk_add_f32 v[18:19], v[10:11], v[16:17]
	v_mov_b32_e32 v13, v10
	v_mov_b32_e32 v15, v19
	v_pk_add_f32 v[20:21], v[12:13], v[14:15] neg_lo:[0,1] neg_hi:[0,1]
	v_pk_add_f32 v[12:13], v[12:13], v[14:15]
	v_mov_b32_e32 v16, v17
	v_pk_add_f32 v[14:15], v[12:13], v[10:11] op_sel:[1,0] op_sel_hi:[0,1] neg_lo:[0,1] neg_hi:[0,1]
	v_pk_add_f32 v[22:23], v[18:19], v[14:15] op_sel_hi:[1,0] neg_lo:[0,1] neg_hi:[0,1]
	v_mov_b32_e32 v18, v19
	v_mov_b32_e32 v19, v13
	v_pk_mov_b32 v[14:15], v[10:11], v[14:15] op_sel:[1,0]
	v_mov_b32_e32 v17, v10
	v_pk_add_f32 v[14:15], v[18:19], v[14:15] neg_lo:[0,1] neg_hi:[0,1]
	v_mov_b32_e32 v22, v20
	v_pk_add_f32 v[10:11], v[16:17], v[14:15] neg_lo:[0,1] neg_hi:[0,1]
	v_mov_b32_e32 v21, v13
	v_pk_add_f32 v[14:15], v[22:23], v[10:11]
	s_nop 0
	v_pk_add_f32 v[16:17], v[14:15], v[14:15] op_sel:[0,1] op_sel_hi:[1,0]
	s_nop 0
	v_pk_add_f32 v[12:13], v[12:13], v[16:17] op_sel:[1,0] op_sel_hi:[0,1]
	v_mov_b32_e32 v15, v12
	v_pk_add_f32 v[18:19], v[14:15], v[20:21] neg_lo:[0,1] neg_hi:[0,1]
	v_mov_b32_e32 v11, v16
	v_sub_f32_e32 v13, v14, v18
	v_pk_add_f32 v[10:11], v[10:11], v[18:19] neg_lo:[0,1] neg_hi:[0,1]
	v_sub_f32_e32 v13, v20, v13
	v_add_f32_e32 v10, v10, v13
	v_add_f32_e32 v10, v10, v11
	v_add_f32_e32 v10, v12, v10
	v_cndmask_b32_e64 v10, v227, v10, s[14:15]
	v_cmp_ngt_f32_e64 s[14:15], -1.0, v24
	s_nop 1
	v_cndmask_b32_e64 v10, v229, v10, s[14:15]
	v_cmp_neq_f32_e64 s[14:15], -1.0, v24
	s_nop 1
	v_cndmask_b32_e64 v10, v232, v10, s[14:15]
	v_cmp_lt_f32_e64 s[14:15], |v24|, s96
	s_nop 1
	v_cndmask_b32_e64 v10, v10, v24, s[14:15]

; __device__ __forceinline__ void p2_prep(PP P, int l, unsigned char* ws, int gw, int ngw, int tid_) {
;     ...
;             if (lane < 8) { const float v = dtr[u] + dtb[lane]; DTF[(size_t)m * 8 + lane] = v > 20.f ? v : log1pf(__expf(v)); } }
.LBB0_438:
	v_mov_b32_e32 v2, v85
	s_mov_b32 s1, 0x41a00000
	s_nop 0
	v_add_f32_e32 v2, v66, v2
	v_cmp_nlt_f32_e64 s[14:15], s1, v2
	s_and_saveexec_b64 s[38:39], s[14:15]
	s_cbranch_execz .LBB0_375
	v_mul_f32_e32 v2, 0x3fb8aa3b, v2
	v_exp_f32_e32 v16, v2
	s_mov_b32 s1, 0x7f800000
	s_waitcnt lgkmcnt(0)
	v_add_f32_e32 v4, 1.0, v16
	v_frexp_mant_f32_e32 v6, v4
	v_cvt_f64_f32_e32 v[2:3], v4
	v_frexp_exp_i32_f64_e32 v2, v[2:3]
	v_cmp_gt_f32_e64 s[14:15], s62, v6
	v_add_f32_e32 v5, -1.0, v4
	v_sub_f32_e32 v7, v5, v4
	v_subbrev_co_u32_e64 v10, s[14:15], 0, v2, s[14:15]
	v_sub_u32_e32 v2, 0, v10
	v_sub_f32_e32 v5, v16, v5
	v_add_f32_e32 v7, 1.0, v7
	v_ldexp_f32 v3, v4, v2
	v_add_f32_e32 v5, v5, v7
	v_add_f32_e32 v4, -1.0, v3
	v_add_f32_e32 v6, 1.0, v3
	v_ldexp_f32 v2, v5, v2
	v_add_f32_e32 v5, 1.0, v4
	v_add_f32_e32 v7, -1.0, v6
	v_sub_f32_e32 v5, v3, v5
	v_sub_f32_e32 v3, v3, v7
	v_add_f32_e32 v5, v2, v5
	v_add_f32_e32 v2, v2, v3
	v_add_f32_e32 v11, v6, v2
	v_rcp_f32_e32 v13, v11
	v_sub_f32_e32 v3, v11, v6
	v_sub_f32_e32 v12, v2, v3
	v_add_f32_e32 v3, v4, v5
	v_mul_f32_e32 v15, v3, v13
	v_sub_f32_e32 v2, v3, v4
	v_mul_f32_e32 v4, v11, v15
	v_fma_f32 v6, v15, v11, -v4
	v_fmac_f32_e32 v6, v15, v12
	v_sub_f32_e32 v14, v5, v2
	v_add_f32_e32 v2, v4, v6
	v_sub_f32_e32 v5, v3, v2
	v_pk_add_f32 v[8:9], v[2:3], v[4:5] neg_lo:[0,1] neg_hi:[0,1]
	v_mov_b32_e32 v7, v2
	v_pk_add_f32 v[2:3], v[8:9], v[6:7] neg_lo:[0,1] neg_hi:[0,1]
	v_cmp_neq_f32_e64 s[14:15], s1, v16
	v_add_f32_e32 v3, v14, v3
	v_add_f32_e32 v2, v2, v3
	v_add_f32_e32 v3, v5, v2
	v_mul_f32_e32 v14, v13, v3
	v_mul_f32_e32 v4, v11, v14
	v_fma_f32 v6, v14, v11, -v4
	v_fmac_f32_e32 v6, v14, v12
	v_sub_f32_e32 v5, v5, v3
	v_add_f32_e32 v11, v2, v5
	v_add_f32_e32 v2, v4, v6
	v_sub_f32_e32 v5, v3, v2
	v_pk_add_f32 v[8:9], v[2:3], v[4:5] neg_lo:[0,1] neg_hi:[0,1]
	v_mov_b32_e32 v7, v2
	v_pk_add_f32 v[2:3], v[8:9], v[6:7] neg_lo:[0,1] neg_hi:[0,1]
	s_nop 0
	v_add_f32_e32 v3, v11, v3
	v_add_f32_e32 v2, v2, v3
	v_add_f32_e32 v3, v15, v14
	v_add_f32_e32 v2, v5, v2
	v_sub_f32_e32 v4, v3, v15
	v_mul_f32_e32 v2, v13, v2
	v_sub_f32_e32 v4, v14, v4
	v_add_f32_e32 v4, v4, v2
	v_add_f32_e32 v6, v3, v4
	v_mul_f32_e32 v7, v6, v6
	v_fmamk_f32 v2, v7, 0x3e9b6dac, v233
	v_fmaak_f32 v197, v7, v2, 0x3f2aaada
	v_cvt_f32_i32_e32 v2, v10
	v_sub_f32_e32 v3, v6, v3
	v_sub_f32_e32 v3, v4, v3
	v_ldexp_f32 v8, v3, 1
	v_mul_f32_e32 v3, v6, v7
	v_ldexp_f32 v5, v6, 1
	v_pk_mul_f32 v[6:7], v[2:3], v[196:197]
	s_nop 0
	v_fma_f32 v4, v2, s94, -v6
	v_fmac_f32_e32 v4, 0xb102e308, v2
	v_pk_add_f32 v[2:3], v[6:7], v[4:5]
	s_nop 0
	v_sub_f32_e32 v5, v3, v5
	v_sub_f32_e32 v5, v7, v5
	v_add_f32_e32 v9, v8, v5
	v_mov_b32_e32 v8, v6
	v_pk_add_f32 v[6:7], v[2:3], v[6:7] neg_lo:[0,1] neg_hi:[0,1]
	v_pk_add_f32 v[10:11], v[2:3], v[8:9]
	v_mov_b32_e32 v5, v2
	v_mov_b32_e32 v7, v11
	v_pk_add_f32 v[12:13], v[4:5], v[6:7] neg_lo:[0,1] neg_hi:[0,1]
	v_pk_add_f32 v[4:5], v[4:5], v[6:7]
	v_mov_b32_e32 v8, v9
	v_pk_add_f32 v[6:7], v[4:5], v[2:3] op_sel:[1,0] op_sel_hi:[0,1] neg_lo:[0,1] neg_hi:[0,1]
	v_pk_add_f32 v[14:15], v[10:11], v[6:7] op_sel_hi:[1,0] neg_lo:[0,1] neg_hi:[0,1]
	v_mov_b32_e32 v10, v11
	v_mov_b32_e32 v11, v5
	v_pk_mov_b32 v[6:7], v[2:3], v[6:7] op_sel:[1,0]
	v_mov_b32_e32 v9, v2
	v_pk_add_f32 v[6:7], v[10:11], v[6:7] neg_lo:[0,1] neg_hi:[0,1]
	v_mov_b32_e32 v14, v12
	v_pk_add_f32 v[2:3], v[8:9], v[6:7] neg_lo:[0,1] neg_hi:[0,1]
	v_mov_b32_e32 v13, v5
	v_pk_add_f32 v[6:7], v[14:15], v[2:3]
	s_nop 0
	v_pk_add_f32 v[8:9], v[6:7], v[6:7] op_sel:[0,1] op_sel_hi:[1,0]
	s_nop 0
	v_pk_add_f32 v[4:5], v[4:5], v[8:9] op_sel:[1,0] op_sel_hi:[0,1]
	v_mov_b32_e32 v7, v4
	v_pk_add_f32 v[10:11], v[6:7], v[12:13] neg_lo:[0,1] neg_hi:[0,1]
	v_mov_b32_e32 v3, v8
	v_sub_f32_e32 v5, v6, v10
	v_pk_add_f32 v[2:3], v[2:3], v[10:11] neg_lo:[0,1] neg_hi:[0,1]
	v_sub_f32_e32 v5, v12, v5
	v_add_f32_e32 v2, v2, v5
	v_add_f32_e32 v2, v2, v3
	v_add_f32_e32 v2, v4, v2
	v_cndmask_b32_e64 v2, v227, v2, s[14:15]
	v_cmp_ngt_f32_e64 s[14:15], -1.0, v16
	s_nop 1
	v_cndmask_b32_e64 v2, v229, v2, s[14:15]
	v_cmp_neq_f32_e64 s[14:15], -1.0, v16
	s_nop 1
	v_cndmask_b32_e64 v2, v232, v2, s[14:15]
	v_cmp_lt_f32_e64 s[14:15], |v16|, s96
	s_nop 1
	v_cndmask_b32_e64 v2, v2, v16, s[14:15]
	s_branch .LBB0_375

; __device__ __forceinline__ float bflo(unsigned w) { return __uint_as_float(w << 16); }
; __device__ __forceinline__ float bfhi(unsigned w) { return __uint_as_float(w & 0xffff0000u); }
; __device__ __forceinline__ float sigmoidf_(float x) { return __builtin_amdgcn_rcpf(1.f + __builtin_amdgcn_exp2f(-1.4426950408889634f * x)); }
;     __device__ __forceinline__ void operator()(AccRef acc, const Unit& u, int wr, int wc, int fr, int fq) const {
;     ...
;             const int ch0 = u.pn * 128 + wc * 32 + 8 * fq + 4 * n;
;             const f32x4 ba = *(const f32x4*)(b_a + ch0), bi = *(const f32x4*)(b_i + ch0), lm = *(const f32x4*)(lam + ch0);
;             f32x4 sp;
; #pragma unroll
;             for (int e = 0; e < 4; ++e) sp[e] = -8.f * log1pf(__expf(-lm[e]));
;             EPI_ROWS_BEGIN
;                 bf16_t* xp = y3 + (size_t)row * 2048 + ch0;
;                 const u32x2 xw = *(const u32x2*)xp;
;                 const f32x4 xc = (f32x4){bflo(xw.x), bfhi(xw.x), bflo(xw.y), bfhi(xw.y)};
;                 f32x4 uo, lo;
; #pragma unroll
;                 for (int e = 0; e < 4; ++e) {
;                     const float rr = acc[ai][0][m][n][e] + ba[e], ii = acc[ai][1][m][n][e] + bi[e];
;                     const float log_a = sp[e] * sigmoidf_(rr);
.LBB0_793:
	v_lshl_or_b32 v154, s31, 7, v168
	v_ashrrev_i32_e32 v155, 31, v154
	v_lshlrev_b64 v[138:139], 2, v[154:155]
	v_lshl_add_u64 v[160:161], s[10:11], 0, v[138:139]
	v_lshl_add_u64 v[156:157], s[26:27], 0, v[138:139]
	v_lshl_add_u64 v[158:159], s[8:9], 0, v[138:139]
	global_load_dwordx4 v[138:141], v[160:161], off
	s_mov_b32 s31, 0x3f2aaaab
	s_mov_b32 s38, 0x3f317218
	global_load_dwordx4 v[102:105], v[156:157], off
	s_mov_b32 s39, 0x7f800000
	v_lshl_add_u32 v162, s62, 8, v166
	s_mov_b32 s43, 0x33800000
	global_load_dwordx4 v[90:93], v[158:159], off
	s_waitcnt vmcnt(0)
	v_lshlrev_b32_e32 v236, 12, v162
	v_lshl_add_u32 v236, v154, 1, v236
	v_mov_b32_e32 v237, v236
	global_load_dwordx2 v[184:185], v237, s[14:15]
	v_add_u32_e32 v237, 0x10000, v236
	global_load_dwordx2 v[186:187], v237, s[14:15]
	v_add_u32_e32 v237, 0x20000, v236
	global_load_dwordx2 v[188:189], v237, s[14:15]
	v_add_u32_e32 v237, 0x30000, v236
	global_load_dwordx2 v[190:191], v237, s[14:15]
	v_add_u32_e32 v237, 0x80000, v236
	global_load_dwordx2 v[192:193], v237, s[14:15]
	v_add_u32_e32 v237, 0x90000, v236
	global_load_dwordx2 v[206:207], v237, s[14:15]
	v_add_u32_e32 v237, 0xa0000, v236
	global_load_dwordx2 v[208:209], v237, s[14:15]
	v_add_u32_e32 v237, 0xb0000, v236
	global_load_dwordx2 v[210:211], v237, s[14:15]
	v_mov_b32_e32 v237, v236
	global_load_dwordx2 v[212:213], v237, s[14:15] offset:8
	v_add_u32_e32 v237, 0x10000, v236
	global_load_dwordx2 v[214:215], v237, s[14:15] offset:8
	v_add_u32_e32 v237, 0x20000, v236
	global_load_dwordx2 v[216:217], v237, s[14:15] offset:8
	v_add_u32_e32 v237, 0x30000, v236
	global_load_dwordx2 v[218:219], v237, s[14:15] offset:8
	v_add_u32_e32 v237, 0x80000, v236
	global_load_dwordx2 v[220:221], v237, s[14:15] offset:8
	v_add_u32_e32 v237, 0x90000, v236
	global_load_dwordx2 v[198:199], v237, s[14:15] offset:8
	v_add_u32_e32 v237, 0xa0000, v236
	global_load_dwordx2 v[200:201], v237, s[14:15] offset:8
	v_add_u32_e32 v237, 0xb0000, v236
	global_load_dwordx2 v[202:203], v237, s[14:15] offset:8
	v_mul_f32_e32 v138, 0xbfb8aa3b, v138
	v_exp_f32_e32 v138, v138
	v_add_f32_e32 v134, v134, v102
	v_mul_f32_e32 v134, 0xbfb8aa3b, v134
	v_add_f32_e32 v163, 1.0, v138
	v_add_f32_e32 v152, -1.0, v163
	v_sub_f32_e32 v153, v152, v163
	v_add_f32_e32 v153, 1.0, v153
	v_sub_f32_e32 v152, v138, v152
	v_add_f32_e32 v164, v152, v153
	v_frexp_mant_f32_e32 v152, v163
	v_cmp_gt_f32_e32 vcc, s31, v152
	v_cvt_f64_f32_e32 v[152:153], v163
	v_frexp_exp_i32_f64_e32 v152, v[152:153]
	v_subbrev_co_u32_e32 v174, vcc, 0, v152, vcc
	v_sub_u32_e32 v152, 0, v174
	v_ldexp_f32 v153, v163, v152
	v_add_f32_e32 v163, -1.0, v153
	v_add_f32_e32 v165, 1.0, v153
	v_ldexp_f32 v152, v164, v152
	v_add_f32_e32 v164, 1.0, v163
	v_add_f32_e32 v170, -1.0, v165
	v_sub_f32_e32 v164, v153, v164
	v_sub_f32_e32 v153, v153, v170
	v_add_f32_e32 v164, v152, v164
	v_add_f32_e32 v152, v152, v153
	v_add_f32_e32 v175, v165, v152
	v_rcp_f32_e32 v177, v175
	v_sub_f32_e32 v153, v175, v165
	v_sub_f32_e32 v176, v152, v153
	v_add_f32_e32 v153, v163, v164
	v_sub_f32_e32 v152, v153, v163
	v_mul_f32_e32 v178, v153, v177
	v_sub_f32_e32 v163, v164, v152
	v_mul_f32_e32 v164, v175, v178
	v_fma_f32 v170, v178, v175, -v164
	v_fmac_f32_e32 v170, v178, v176
	v_add_f32_e32 v152, v164, v170
	v_sub_f32_e32 v165, v153, v152
	v_pk_add_f32 v[172:173], v[152:153], v[164:165] neg_lo:[0,1] neg_hi:[0,1]
	v_mov_b32_e32 v171, v152
	v_pk_add_f32 v[152:153], v[172:173], v[170:171] neg_lo:[0,1] neg_hi:[0,1]
	v_cmp_neq_f32_e32 vcc, s39, v138
	v_add_f32_e32 v153, v163, v153
	v_add_f32_e32 v152, v152, v153
	v_add_f32_e32 v153, v165, v152
	v_mul_f32_e32 v163, v177, v153
	v_mul_f32_e32 v164, v175, v163
	v_fma_f32 v170, v163, v175, -v164
	v_fmac_f32_e32 v170, v163, v176
	v_sub_f32_e32 v165, v165, v153
	v_add_f32_e32 v175, v152, v165
	v_add_f32_e32 v152, v164, v170
	v_sub_f32_e32 v165, v153, v152
	v_pk_add_f32 v[172:173], v[152:153], v[164:165] neg_lo:[0,1] neg_hi:[0,1]
	v_mov_b32_e32 v171, v152
	v_pk_add_f32 v[152:153], v[172:173], v[170:171] neg_lo:[0,1] neg_hi:[0,1]
	v_exp_f32_e32 v134, v134
	v_add_f32_e32 v153, v175, v153
	v_add_f32_e32 v152, v152, v153
	v_add_f32_e32 v153, v178, v163
	v_add_f32_e32 v152, v165, v152
	v_sub_f32_e32 v164, v153, v178
	v_mul_f32_e32 v152, v177, v152
	v_sub_f32_e32 v163, v163, v164
	v_add_f32_e32 v163, v163, v152
	v_add_f32_e32 v164, v153, v163
	v_mul_f32_e32 v170, v164, v164
	v_fmamk_f32 v152, v170, 0x3e9b6dac, v233
	v_fmaak_f32 v197, v170, v152, 0x3f2aaada
	v_cvt_f32_i32_e32 v152, v174
	v_sub_f32_e32 v153, v164, v153
	v_sub_f32_e32 v153, v163, v153
	v_ldexp_f32 v163, v153, 1
	v_mul_f32_e32 v153, v164, v170
	v_pk_mul_f32 v[170:171], v[152:153], v[196:197]
	v_ldexp_f32 v165, v164, 1
	v_fma_f32 v164, v152, s38, -v170
	v_fmac_f32_e32 v164, 0xb102e308, v152
	v_pk_add_f32 v[152:153], v[170:171], v[164:165]
	v_mov_b32_e32 v172, v170
	v_sub_f32_e32 v165, v153, v165
	v_sub_f32_e32 v165, v171, v165
	v_add_f32_e32 v173, v163, v165
	v_pk_add_f32 v[170:171], v[152:153], v[170:171] neg_lo:[0,1] neg_hi:[0,1]
	v_pk_add_f32 v[174:175], v[152:153], v[172:173]
	v_mov_b32_e32 v165, v152
	v_mov_b32_e32 v171, v175
	v_pk_add_f32 v[176:177], v[164:165], v[170:171] neg_lo:[0,1] neg_hi:[0,1]
	v_pk_add_f32 v[164:165], v[164:165], v[170:171]
	v_mov_b32_e32 v172, v173
	v_pk_add_f32 v[170:171], v[164:165], v[152:153] op_sel:[1,0] op_sel_hi:[0,1] neg_lo:[0,1] neg_hi:[0,1]
	v_pk_add_f32 v[178:179], v[174:175], v[170:171] op_sel_hi:[1,0] neg_lo:[0,1] neg_hi:[0,1]
	v_mov_b32_e32 v174, v175
	v_mov_b32_e32 v175, v165
	v_pk_mov_b32 v[170:171], v[152:153], v[170:171] op_sel:[1,0]
	v_mov_b32_e32 v173, v152
; __device__ __forceinline__ float bflo(unsigned w) { return __uint_as_float(w << 16); }
; __device__ __forceinline__ float bfhi(unsigned w) { return __uint_as_float(w & 0xffff0000u); }
; __device__ __forceinline__ float sigmoidf_(float x) { return __builtin_amdgcn_rcpf(1.f + __builtin_amdgcn_exp2f(-1.4426950408889634f * x)); }
;     __device__ __forceinline__ void operator()(AccRef acc, const Unit& u, int wr, int wc, int fr, int fq) const {
;     ...
;             for (int e = 0; e < 4; ++e) sp[e] = -8.f * log1pf(__expf(-lm[e]));
;             EPI_ROWS_BEGIN
;                 bf16_t* xp = y3 + (size_t)row * 2048 + ch0;
;                 const u32x2 xw = *(const u32x2*)xp;
;                 const f32x4 xc = (f32x4){bflo(xw.x), bfhi(xw.x), bflo(xw.y), bfhi(xw.y)};
;                 f32x4 uo, lo;
; #pragma unroll
;                 for (int e = 0; e < 4; ++e) {
;                     const float rr = acc[ai][0][m][n][e] + ba[e], ii = acc[ai][1][m][n][e] + bi[e];
;                     const float log_a = sp[e] * sigmoidf_(rr);
;                     const float mult = sqrtf(one_minus_exp(2.f * log_a));
;                     uo[e] = xc[e] * sigmoidf_(ii) * mult; lo[e] = log_a;
	v_pk_add_f32 v[170:171], v[174:175], v[170:171] neg_lo:[0,1] neg_hi:[0,1]
	v_mov_b32_e32 v178, v176
	v_pk_add_f32 v[152:153], v[172:173], v[170:171] neg_lo:[0,1] neg_hi:[0,1]
	v_mov_b32_e32 v177, v165
	v_pk_add_f32 v[170:171], v[178:179], v[152:153]
	v_add_f32_e32 v134, 1.0, v134
	v_pk_add_f32 v[172:173], v[170:171], v[170:171] op_sel:[0,1] op_sel_hi:[1,0]
	v_rcp_f32_e32 v134, v134
	v_pk_add_f32 v[164:165], v[164:165], v[172:173] op_sel:[1,0] op_sel_hi:[0,1]
	v_mov_b32_e32 v171, v164
	v_pk_add_f32 v[174:175], v[170:171], v[176:177] neg_lo:[0,1] neg_hi:[0,1]
	v_mov_b32_e32 v153, v172
	v_sub_f32_e32 v163, v170, v174
	v_pk_add_f32 v[152:153], v[152:153], v[174:175] neg_lo:[0,1] neg_hi:[0,1]
	v_sub_f32_e32 v163, v176, v163
	v_add_f32_e32 v152, v152, v163
	v_add_f32_e32 v152, v152, v153
	v_add_f32_e32 v152, v164, v152
	v_cndmask_b32_e32 v152, v227, v152, vcc
	v_cmp_ngt_f32_e32 vcc, -1.0, v138
	v_ashrrev_i32_e32 v163, 31, v162
	s_nop 0
	v_cndmask_b32_e32 v152, v229, v152, vcc
	v_cmp_neq_f32_e32 vcc, -1.0, v138
	s_nop 1
	v_cndmask_b32_e32 v152, v232, v152, vcc
	v_cmp_lt_f32_e64 vcc, |v138|, s43
	s_nop 1
	v_cndmask_b32_e32 v138, v152, v138, vcc
	v_lshlrev_b64 v[152:153], 12, v[162:163]
	v_lshl_add_u64 v[152:153], s[14:15], 0, v[152:153]
	v_lshl_add_u64 v[152:153], v[154:155], 1, v[152:153]
	s_nop 0
	v_mul_f32_e32 v170, 0xc1000000, v138
	v_mul_f32_e32 v134, v134, v170
	v_add_f32_e32 v171, v134, v134
	v_cmp_ngt_f32_e32 vcc, s33, v171
	s_and_saveexec_b64 s[0:1], vcc
	s_xor_b64 s[0:1], exec, s[0:1]
	v_fmamk_f32 v138, v171, 0x39500d01, v224
	v_fmaak_f32 v138, v171, v138, 0x3c088889
	v_fmaak_f32 v138, v171, v138, 0x3d2aaaab
	v_fmaak_f32 v138, v171, v138, 0x3e2aaaab
	v_fma_f32 v138, v171, v138, 0.5
	v_fma_f32 v138, v171, v138, 1.0
	v_mul_f32_e64 v138, v138, -v171
	s_andn2_saveexec_b64 s[0:1], s[0:1]
	v_mul_f32_e32 v138, 0x3fb8aa3b, v171
	v_exp_f32_e32 v138, v138
	s_nop 0
	v_sub_f32_e32 v138, 1.0, v138
	s_or_b64 exec, exec, s[0:1]
	v_mul_f32_e32 v139, 0xbfb8aa3b, v139
	v_exp_f32_e32 v139, v139
	v_add_f32_e32 v135, v135, v103
	v_mul_f32_e32 v135, 0xbfb8aa3b, v135
	v_exp_f32_e32 v135, v135
	v_add_f32_e32 v171, 1.0, v139
	v_frexp_mant_f32_e32 v175, v171
	v_cvt_f64_f32_e32 v[172:173], v171
	v_add_f32_e32 v174, -1.0, v171
	v_frexp_exp_i32_f64_e32 v172, v[172:173]
	v_cmp_gt_f32_e32 vcc, s31, v175
	v_sub_f32_e32 v176, v174, v171
	v_sub_f32_e32 v174, v139, v174
	v_subbrev_co_u32_e32 v172, vcc, 0, v172, vcc
	v_add_f32_e32 v176, 1.0, v176
	v_sub_u32_e32 v173, 0, v172
	v_add_f32_e32 v174, v174, v176
	v_ldexp_f32 v171, v171, v173
	v_ldexp_f32 v173, v174, v173
	v_add_f32_e32 v174, -1.0, v171
	v_add_f32_e32 v177, 1.0, v171
	v_add_f32_e32 v175, 1.0, v174
	v_add_f32_e32 v178, -1.0, v177
	v_sub_f32_e32 v175, v171, v175
	v_sub_f32_e32 v171, v171, v178
	v_add_f32_e32 v171, v173, v171
	v_add_f32_e32 v175, v173, v175
	v_add_f32_e32 v173, v177, v171
	v_rcp_f32_e32 v178, v173
	v_add_f32_e32 v176, v174, v175
	v_sub_f32_e32 v174, v176, v174
	v_sub_f32_e32 v174, v175, v174
	v_sub_f32_e32 v175, v173, v177
	v_sub_f32_e32 v171, v171, v175
	v_mul_f32_e32 v175, v176, v178
	v_mul_f32_e32 v177, v173, v175
	v_fma_f32 v179, v175, v173, -v177
	v_fmac_f32_e32 v179, v175, v171
	v_add_f32_e32 v180, v177, v179
	v_sub_f32_e32 v181, v176, v180
	v_sub_f32_e32 v176, v176, v181
	v_sub_f32_e32 v177, v180, v177
	v_sub_f32_e32 v176, v176, v180
	v_add_f32_e32 v174, v174, v176
	v_sub_f32_e32 v176, v177, v179
	v_add_f32_e32 v174, v176, v174
	v_add_f32_e32 v176, v181, v174
	v_mul_f32_e32 v177, v178, v176
	v_mul_f32_e32 v179, v173, v177
	v_fma_f32 v173, v177, v173, -v179
	v_fmac_f32_e32 v173, v177, v171
	v_sub_f32_e32 v171, v181, v176
	v_add_f32_e32 v171, v174, v171
	v_add_f32_e32 v174, v179, v173
	v_sub_f32_e32 v180, v176, v174
	v_sub_f32_e32 v176, v176, v180
	v_sub_f32_e32 v179, v174, v179
	v_sub_f32_e32 v174, v176, v174
	v_add_f32_e32 v171, v171, v174
	v_sub_f32_e32 v173, v179, v173
	v_cvt_f32_i32_e32 v172, v172
	v_add_f32_e32 v171, v173, v171
	v_add_f32_e32 v173, v175, v177
	v_add_f32_e32 v171, v180, v171
	v_sub_f32_e32 v174, v173, v175
	v_mul_f32_e32 v171, v178, v171
	v_sub_f32_e32 v174, v177, v174
	v_add_f32_e32 v171, v174, v171
	v_mul_f32_e32 v177, 0x3f317218, v172
	v_add_f32_e32 v174, v173, v171
	v_fma_f32 v178, v172, s38, -v177
	v_mul_f32_e32 v175, v174, v174
	v_fmac_f32_e32 v178, 0xb102e308, v172
	v_sub_f32_e32 v172, v174, v173
	v_fmamk_f32 v176, v175, 0x3e9b6dac, v233
	v_sub_f32_e32 v171, v171, v172
	v_add_f32_e32 v172, v177, v178
	v_fmaak_f32 v176, v175, v176, 0x3f2aaada
	v_sub_f32_e32 v173, v172, v177
	v_ldexp_f32 v177, v174, 1
	v_mul_f32_e32 v174, v174, v175
	v_mul_f32_e32 v174, v174, v176
	v_add_f32_e32 v175, v177, v174
	v_sub_f32_e32 v176, v175, v177
	v_ldexp_f32 v171, v171, 1
	v_sub_f32_e32 v174, v174, v176
	v_add_f32_e32 v171, v171, v174
	v_add_f32_e32 v174, v175, v171
	v_sub_f32_e32 v175, v174, v175
	v_sub_f32_e32 v171, v171, v175
	v_add_f32_e32 v175, v172, v174
	v_sub_f32_e32 v176, v175, v172
	v_sub_f32_e32 v177, v175, v176
	v_sub_f32_e32 v173, v178, v173
	v_sub_f32_e32 v172, v172, v177
	v_sub_f32_e32 v174, v174, v176
	v_add_f32_e32 v172, v174, v172
	v_add_f32_e32 v174, v173, v171
	v_sub_f32_e32 v176, v174, v173
	v_sub_f32_e32 v177, v174, v176
	v_sub_f32_e32 v173, v173, v177
	v_sub_f32_e32 v171, v171, v176
	v_add_f32_e32 v172, v174, v172
	v_add_f32_e32 v171, v171, v173
	v_add_f32_e32 v173, v175, v172
	v_sub_f32_e32 v174, v173, v175
	v_sub_f32_e32 v172, v172, v174
	v_add_f32_e32 v171, v171, v172
	v_add_f32_e32 v171, v173, v171
	v_cmp_neq_f32_e32 vcc, s39, v139
	v_add_f32_e32 v135, 1.0, v135
	v_rcp_f32_e32 v135, v135
	v_cndmask_b32_e32 v171, v227, v171, vcc
	v_cmp_ngt_f32_e32 vcc, -1.0, v139
; __device__ __forceinline__ float bflo(unsigned w) { return __uint_as_float(w << 16); }
; __device__ __forceinline__ float bfhi(unsigned w) { return __uint_as_float(w & 0xffff0000u); }
; __device__ __forceinline__ float sigmoidf_(float x) { return __builtin_amdgcn_rcpf(1.f + __builtin_amdgcn_exp2f(-1.4426950408889634f * x)); }
;     __device__ __forceinline__ void operator()(AccRef acc, const Unit& u, int wr, int wc, int fr, int fq) const {
;     ...
;             for (int e = 0; e < 4; ++e) sp[e] = -8.f * log1pf(__expf(-lm[e]));
;             EPI_ROWS_BEGIN
;                 bf16_t* xp = y3 + (size_t)row * 2048 + ch0;
;                 const u32x2 xw = *(const u32x2*)xp;
;                 const f32x4 xc = (f32x4){bflo(xw.x), bfhi(xw.x), bflo(xw.y), bfhi(xw.y)};
;                 f32x4 uo, lo;
; #pragma unroll
;                 for (int e = 0; e < 4; ++e) {
;                     const float rr = acc[ai][0][m][n][e] + ba[e], ii = acc[ai][1][m][n][e] + bi[e];
;                     const float log_a = sp[e] * sigmoidf_(rr);
;                     const float mult = sqrtf(one_minus_exp(2.f * log_a));
	s_nop 1
	v_cndmask_b32_e32 v171, v229, v171, vcc
	v_cmp_neq_f32_e32 vcc, -1.0, v139
	s_nop 1
	v_cndmask_b32_e32 v171, v232, v171, vcc
	v_cmp_lt_f32_e64 vcc, |v139|, s43
	s_nop 1
	v_cndmask_b32_e32 v139, v171, v139, vcc
	v_mul_f32_e32 v171, 0xc1000000, v139
	v_mul_f32_e32 v135, v135, v171
	v_add_f32_e32 v172, v135, v135
	v_cmp_ngt_f32_e32 vcc, s33, v172
	s_and_saveexec_b64 s[0:1], vcc
	s_xor_b64 s[0:1], exec, s[0:1]
	v_fmamk_f32 v139, v172, 0x39500d01, v224
	v_fmaak_f32 v139, v172, v139, 0x3c088889
	v_fmaak_f32 v139, v172, v139, 0x3d2aaaab
	v_fmaak_f32 v139, v172, v139, 0x3e2aaaab
	v_fma_f32 v139, v172, v139, 0.5
	v_fma_f32 v139, v172, v139, 1.0
	v_mul_f32_e64 v139, v139, -v172
	s_andn2_saveexec_b64 s[0:1], s[0:1]
	v_mul_f32_e32 v139, 0x3fb8aa3b, v172
	v_exp_f32_e32 v139, v139
	s_nop 0
	v_sub_f32_e32 v139, 1.0, v139
	s_or_b64 exec, exec, s[0:1]
	v_mul_f32_e32 v140, 0xbfb8aa3b, v140
	v_exp_f32_e32 v140, v140
	v_add_f32_e32 v136, v136, v104
	v_mul_f32_e32 v136, 0xbfb8aa3b, v136
	v_exp_f32_e32 v136, v136
	v_add_f32_e32 v174, 1.0, v140
	v_frexp_mant_f32_e32 v176, v174
	v_cvt_f64_f32_e32 v[172:173], v174
	v_add_f32_e32 v175, -1.0, v174
	v_frexp_exp_i32_f64_e32 v172, v[172:173]
	v_cmp_gt_f32_e32 vcc, s31, v176
	v_sub_f32_e32 v177, v175, v174
	v_sub_f32_e32 v175, v140, v175
	v_subbrev_co_u32_e32 v172, vcc, 0, v172, vcc
	v_add_f32_e32 v177, 1.0, v177
	v_sub_u32_e32 v173, 0, v172
	v_add_f32_e32 v175, v175, v177
	v_ldexp_f32 v174, v174, v173
	v_ldexp_f32 v173, v175, v173
	v_add_f32_e32 v175, -1.0, v174
	v_add_f32_e32 v178, 1.0, v174
	v_add_f32_e32 v176, 1.0, v175
	v_add_f32_e32 v179, -1.0, v178
	v_sub_f32_e32 v176, v174, v176
	v_sub_f32_e32 v174, v174, v179
	v_add_f32_e32 v176, v173, v176
	v_add_f32_e32 v173, v173, v174
	v_add_f32_e32 v174, v178, v173
	v_rcp_f32_e32 v179, v174
	v_add_f32_e32 v177, v175, v176
	v_sub_f32_e32 v175, v177, v175
	v_sub_f32_e32 v175, v176, v175
	v_sub_f32_e32 v176, v174, v178
	v_sub_f32_e32 v173, v173, v176
	v_mul_f32_e32 v176, v177, v179
	v_mul_f32_e32 v178, v174, v176
	v_fma_f32 v180, v176, v174, -v178
	v_fmac_f32_e32 v180, v176, v173
	v_add_f32_e32 v181, v178, v180
	v_sub_f32_e32 v182, v177, v181
	v_sub_f32_e32 v177, v177, v182
	v_sub_f32_e32 v178, v181, v178
	v_sub_f32_e32 v177, v177, v181
	v_add_f32_e32 v175, v175, v177
	v_sub_f32_e32 v177, v178, v180
	v_add_f32_e32 v175, v177, v175
	v_add_f32_e32 v177, v182, v175
	v_mul_f32_e32 v178, v179, v177
	v_mul_f32_e32 v180, v174, v178
	v_fma_f32 v174, v178, v174, -v180
	v_fmac_f32_e32 v174, v178, v173
	v_sub_f32_e32 v173, v182, v177
	v_add_f32_e32 v173, v175, v173
	v_add_f32_e32 v175, v180, v174
	v_sub_f32_e32 v181, v177, v175
	v_sub_f32_e32 v177, v177, v181
	v_sub_f32_e32 v180, v175, v180
	v_sub_f32_e32 v175, v177, v175
	v_add_f32_e32 v173, v173, v175
	v_sub_f32_e32 v174, v180, v174
	v_cvt_f32_i32_e32 v172, v172
	v_add_f32_e32 v173, v174, v173
	v_add_f32_e32 v174, v176, v178
	v_add_f32_e32 v173, v181, v173
	v_sub_f32_e32 v175, v174, v176
	v_mul_f32_e32 v173, v179, v173
	v_sub_f32_e32 v175, v178, v175
	v_add_f32_e32 v173, v175, v173
	v_mul_f32_e32 v178, 0x3f317218, v172
	v_add_f32_e32 v175, v174, v173
	v_fma_f32 v179, v172, s38, -v178
	v_mul_f32_e32 v176, v175, v175
	v_fmac_f32_e32 v179, 0xb102e308, v172
	v_sub_f32_e32 v172, v175, v174
	v_fmamk_f32 v177, v176, 0x3e9b6dac, v233
	v_sub_f32_e32 v172, v173, v172
	v_add_f32_e32 v173, v178, v179
	v_fmaak_f32 v177, v176, v177, 0x3f2aaada
	v_sub_f32_e32 v174, v173, v178
	v_ldexp_f32 v178, v175, 1
	v_mul_f32_e32 v175, v175, v176
	v_mul_f32_e32 v175, v175, v177
	v_add_f32_e32 v176, v178, v175
	v_sub_f32_e32 v177, v176, v178
	v_ldexp_f32 v172, v172, 1
	v_sub_f32_e32 v175, v175, v177
	v_add_f32_e32 v172, v172, v175
	v_add_f32_e32 v175, v176, v172
	v_sub_f32_e32 v176, v175, v176
	v_sub_f32_e32 v172, v172, v176
	v_add_f32_e32 v176, v173, v175
	v_sub_f32_e32 v177, v176, v173
	v_sub_f32_e32 v178, v176, v177
	v_sub_f32_e32 v174, v179, v174
	v_sub_f32_e32 v173, v173, v178
	v_sub_f32_e32 v175, v175, v177
	v_add_f32_e32 v173, v175, v173
	v_add_f32_e32 v175, v174, v172
	v_sub_f32_e32 v177, v175, v174
	v_sub_f32_e32 v178, v175, v177
	v_sub_f32_e32 v174, v174, v178
	v_sub_f32_e32 v172, v172, v177
	v_add_f32_e32 v173, v175, v173
	v_add_f32_e32 v172, v172, v174
	v_add_f32_e32 v174, v176, v173
	v_sub_f32_e32 v175, v174, v176
	v_sub_f32_e32 v173, v173, v175
	v_add_f32_e32 v172, v172, v173
	v_add_f32_e32 v172, v174, v172
	v_cmp_neq_f32_e32 vcc, s39, v140
	v_add_f32_e32 v136, 1.0, v136
	v_rcp_f32_e32 v136, v136
	v_cndmask_b32_e32 v172, v227, v172, vcc
	v_cmp_ngt_f32_e32 vcc, -1.0, v140
	s_nop 1
	v_cndmask_b32_e32 v172, v229, v172, vcc
	v_cmp_neq_f32_e32 vcc, -1.0, v140
	s_nop 1
	v_cndmask_b32_e32 v172, v232, v172, vcc
	v_cmp_lt_f32_e64 vcc, |v140|, s43
	s_nop 1
	v_cndmask_b32_e32 v140, v172, v140, vcc
	v_mul_f32_e32 v140, 0xc1000000, v140
	v_mul_f32_e32 v136, v136, v140
	v_add_f32_e32 v173, v136, v136
	v_cmp_ngt_f32_e32 vcc, s33, v173
	s_and_saveexec_b64 s[0:1], vcc
	s_xor_b64 s[0:1], exec, s[0:1]
	v_fmamk_f32 v172, v173, 0x39500d01, v224
	v_fmaak_f32 v172, v173, v172, 0x3c088889
	v_fmaak_f32 v172, v173, v172, 0x3d2aaaab
	v_fmaak_f32 v172, v173, v172, 0x3e2aaaab
	v_fma_f32 v172, v173, v172, 0.5
	v_fma_f32 v172, v173, v172, 1.0
	v_mul_f32_e64 v172, v172, -v173
	s_andn2_saveexec_b64 s[0:1], s[0:1]
	v_mul_f32_e32 v172, 0x3fb8aa3b, v173
	v_exp_f32_e32 v172, v172
	s_nop 0
	v_sub_f32_e32 v172, 1.0, v172
	s_or_b64 exec, exec, s[0:1]
	v_mul_f32_e32 v141, 0xbfb8aa3b, v141
	v_exp_f32_e32 v141, v141
	v_add_f32_e32 v137, v137, v105
	v_mul_f32_e32 v137, 0xbfb8aa3b, v137
	v_exp_f32_e32 v137, v137
	v_add_f32_e32 v173, 1.0, v141
	v_frexp_mant_f32_e32 v177, v173
; __device__ __forceinline__ float bflo(unsigned w) { return __uint_as_float(w << 16); }
; __device__ __forceinline__ float bfhi(unsigned w) { return __uint_as_float(w & 0xffff0000u); }
; __device__ __forceinline__ float sigmoidf_(float x) { return __builtin_amdgcn_rcpf(1.f + __builtin_amdgcn_exp2f(-1.4426950408889634f * x)); }
;     __device__ __forceinline__ void operator()(AccRef acc, const Unit& u, int wr, int wc, int fr, int fq) const {
;     ...
;             for (int e = 0; e < 4; ++e) sp[e] = -8.f * log1pf(__expf(-lm[e]));
;             EPI_ROWS_BEGIN
;                 bf16_t* xp = y3 + (size_t)row * 2048 + ch0;
;                 const u32x2 xw = *(const u32x2*)xp;
;                 const f32x4 xc = (f32x4){bflo(xw.x), bfhi(xw.x), bflo(xw.y), bfhi(xw.y)};
;                 f32x4 uo, lo;
; #pragma unroll
;                 for (int e = 0; e < 4; ++e) {
;                     const float rr = acc[ai][0][m][n][e] + ba[e], ii = acc[ai][1][m][n][e] + bi[e];
;                     const float log_a = sp[e] * sigmoidf_(rr);
;                     const float mult = sqrtf(one_minus_exp(2.f * log_a));
;                     uo[e] = xc[e] * sigmoidf_(ii) * mult; lo[e] = log_a;
	v_cvt_f64_f32_e32 v[174:175], v173
	v_add_f32_e32 v176, -1.0, v173
	v_frexp_exp_i32_f64_e32 v174, v[174:175]
	v_cmp_gt_f32_e32 vcc, s31, v177
	v_sub_f32_e32 v178, v176, v173
	v_sub_f32_e32 v176, v141, v176
	v_subbrev_co_u32_e32 v174, vcc, 0, v174, vcc
	v_add_f32_e32 v178, 1.0, v178
	v_sub_u32_e32 v175, 0, v174
	v_add_f32_e32 v176, v176, v178
	v_ldexp_f32 v173, v173, v175
	v_ldexp_f32 v175, v176, v175
	v_add_f32_e32 v176, -1.0, v173
	v_add_f32_e32 v179, 1.0, v173
	v_add_f32_e32 v177, 1.0, v176
	v_add_f32_e32 v180, -1.0, v179
	v_sub_f32_e32 v177, v173, v177
	v_sub_f32_e32 v173, v173, v180
	v_add_f32_e32 v173, v175, v173
	v_add_f32_e32 v177, v175, v177
	v_add_f32_e32 v175, v179, v173
	v_rcp_f32_e32 v180, v175
	v_add_f32_e32 v178, v176, v177
	v_sub_f32_e32 v176, v178, v176
	v_sub_f32_e32 v176, v177, v176
	v_sub_f32_e32 v177, v175, v179
	v_sub_f32_e32 v173, v173, v177
	v_mul_f32_e32 v177, v178, v180
	v_mul_f32_e32 v179, v175, v177
	v_fma_f32 v181, v177, v175, -v179
	v_fmac_f32_e32 v181, v177, v173
	v_add_f32_e32 v182, v179, v181
	v_sub_f32_e32 v183, v178, v182
	v_sub_f32_e32 v178, v178, v183
	v_sub_f32_e32 v179, v182, v179
	v_sub_f32_e32 v178, v178, v182
	v_add_f32_e32 v176, v176, v178
	v_sub_f32_e32 v178, v179, v181
	v_add_f32_e32 v176, v178, v176
	v_add_f32_e32 v178, v183, v176
	v_mul_f32_e32 v179, v180, v178
	v_mul_f32_e32 v181, v175, v179
	v_fma_f32 v175, v179, v175, -v181
	v_fmac_f32_e32 v175, v179, v173
	v_sub_f32_e32 v173, v183, v178
	v_add_f32_e32 v173, v176, v173
	v_add_f32_e32 v176, v181, v175
	v_sub_f32_e32 v182, v178, v176
	v_sub_f32_e32 v178, v178, v182
	v_sub_f32_e32 v181, v176, v181
	v_sub_f32_e32 v176, v178, v176
	v_add_f32_e32 v173, v173, v176
	v_sub_f32_e32 v175, v181, v175
	v_cvt_f32_i32_e32 v174, v174
	v_add_f32_e32 v173, v175, v173
	v_add_f32_e32 v175, v177, v179
	v_add_f32_e32 v173, v182, v173
	v_sub_f32_e32 v176, v175, v177
	v_mul_f32_e32 v173, v180, v173
	v_sub_f32_e32 v176, v179, v176
	v_add_f32_e32 v173, v176, v173
	v_mul_f32_e32 v179, 0x3f317218, v174
	v_add_f32_e32 v176, v175, v173
	v_fma_f32 v180, v174, s38, -v179
	v_mul_f32_e32 v177, v176, v176
	v_fmac_f32_e32 v180, 0xb102e308, v174
	v_sub_f32_e32 v174, v176, v175
	v_fmamk_f32 v178, v177, 0x3e9b6dac, v233
	v_sub_f32_e32 v173, v173, v174
	v_add_f32_e32 v174, v179, v180
	v_fmaak_f32 v178, v177, v178, 0x3f2aaada
	v_sub_f32_e32 v175, v174, v179
	v_ldexp_f32 v179, v176, 1
	v_mul_f32_e32 v176, v176, v177
	v_mul_f32_e32 v176, v176, v178
	v_add_f32_e32 v177, v179, v176
	v_sub_f32_e32 v178, v177, v179
	v_ldexp_f32 v173, v173, 1
	v_sub_f32_e32 v176, v176, v178
	v_add_f32_e32 v173, v173, v176
	v_add_f32_e32 v176, v177, v173
	v_sub_f32_e32 v177, v176, v177
	v_sub_f32_e32 v173, v173, v177
	v_add_f32_e32 v177, v174, v176
	v_sub_f32_e32 v178, v177, v174
	v_sub_f32_e32 v179, v177, v178
	v_sub_f32_e32 v175, v180, v175
	v_sub_f32_e32 v174, v174, v179
	v_sub_f32_e32 v176, v176, v178
	v_add_f32_e32 v174, v176, v174
	v_add_f32_e32 v176, v175, v173
	v_sub_f32_e32 v178, v176, v175
	v_sub_f32_e32 v179, v176, v178
	v_sub_f32_e32 v175, v175, v179
	v_sub_f32_e32 v173, v173, v178
	v_add_f32_e32 v174, v176, v174
	v_add_f32_e32 v173, v173, v175
	v_add_f32_e32 v175, v177, v174
	v_sub_f32_e32 v176, v175, v177
	v_sub_f32_e32 v174, v174, v176
	v_add_f32_e32 v173, v173, v174
	v_add_f32_e32 v173, v175, v173
	v_cmp_neq_f32_e32 vcc, s39, v141
	v_add_f32_e32 v137, 1.0, v137
	v_rcp_f32_e32 v137, v137
	v_cndmask_b32_e32 v173, v227, v173, vcc
	v_cmp_ngt_f32_e32 vcc, -1.0, v141
	s_nop 1
	v_cndmask_b32_e32 v173, v229, v173, vcc
	v_cmp_neq_f32_e32 vcc, -1.0, v141
	s_nop 1
	v_cndmask_b32_e32 v173, v232, v173, vcc
	v_cmp_lt_f32_e64 vcc, |v141|, s43
	s_nop 1
	v_cndmask_b32_e32 v141, v173, v141, vcc
	v_mul_f32_e32 v141, 0xc1000000, v141
	v_mul_f32_e32 v137, v137, v141
	v_add_f32_e32 v174, v137, v137
	v_cmp_ngt_f32_e32 vcc, s33, v174
	s_and_saveexec_b64 s[0:1], vcc
	s_xor_b64 s[0:1], exec, s[0:1]
	v_fmamk_f32 v173, v174, 0x39500d01, v224
	v_fmaak_f32 v173, v174, v173, 0x3c088889
	v_fmaak_f32 v173, v174, v173, 0x3d2aaaab
	v_fmaak_f32 v173, v174, v173, 0x3e2aaaab
	v_fma_f32 v173, v174, v173, 0.5
	v_fma_f32 v173, v174, v173, 1.0
	v_mul_f32_e64 v173, v173, -v174
	s_andn2_saveexec_b64 s[0:1], s[0:1]
	v_mul_f32_e32 v173, 0x3fb8aa3b, v174
	v_exp_f32_e32 v173, v173
	s_nop 0
	v_sub_f32_e32 v173, 1.0, v173
	s_or_b64 exec, exec, s[0:1]
	v_mul_f32_e32 v174, 0x4f800000, v172
	v_cmp_gt_f32_e32 vcc, s30, v172
	v_add_f32_e32 v132, v132, v92
	v_mul_f32_e32 v132, 0xbfb8aa3b, v132
	v_cndmask_b32_e32 v172, v172, v174, vcc
	v_sqrt_f32_e32 v174, v172
	v_exp_f32_e32 v132, v132
	s_waitcnt vmcnt(15)
; __device__ __forceinline__ unsigned cvt_pk_bf16(float lo, float hi) { unsigned r; asm("v_cvt_pk_bf16_f32 %0, %1, %2" : "=v"(r) : "v"(lo), "v"(hi)); return r; }
; __device__ __forceinline__ float bflo(unsigned w) { return __uint_as_float(w << 16); }
; __device__ __forceinline__ float bfhi(unsigned w) { return __uint_as_float(w & 0xffff0000u); }
; __device__ __forceinline__ float sigmoidf_(float x) { return __builtin_amdgcn_rcpf(1.f + __builtin_amdgcn_exp2f(-1.4426950408889634f * x)); }
;     __device__ __forceinline__ void operator()(AccRef acc, const Unit& u, int wr, int wc, int fr, int fq) const {
;     ...
;             EPI_ROWS_BEGIN
;                 bf16_t* xp = y3 + (size_t)row * 2048 + ch0;
;                 const u32x2 xw = *(const u32x2*)xp;
;                 const f32x4 xc = (f32x4){bflo(xw.x), bfhi(xw.x), bflo(xw.y), bfhi(xw.y)};
;                 f32x4 uo, lo;
; #pragma unroll
;                 for (int e = 0; e < 4; ++e) {
;                     const float rr = acc[ai][0][m][n][e] + ba[e], ii = acc[ai][1][m][n][e] + bi[e];
;                     const float log_a = sp[e] * sigmoidf_(rr);
;                     const float mult = sqrtf(one_minus_exp(2.f * log_a));
;                     uo[e] = xc[e] * sigmoidf_(ii) * mult; lo[e] = log_a;
;                 }
;                 u32x2 w0, w1; w0.x = cvt_pk_bf16(uo[0], uo[1]); w0.y = cvt_pk_bf16(uo[2], uo[3]); w1.x = cvt_pk_bf16(lo[0], lo[1]); w1.y = cvt_pk_bf16(lo[2], lo[3]);
;                 *(u32x2*)xp = w0;
;                 *(u32x2*)(la + (size_t)row * 512 + ch0) = w1;
	v_lshlrev_b32_e32 v175, 16, v185
	v_add_f32_e32 v131, v131, v91
	v_add_u32_e32 v176, -1, v174
	v_fma_f32 v177, -v176, v174, v172
	v_cmp_ge_f32_e64 s[6:7], 0, v177
	v_add_u32_e32 v177, 1, v174
	v_add_f32_e32 v132, 1.0, v132
	v_cndmask_b32_e64 v176, v174, v176, s[6:7]
	v_fma_f32 v174, -v177, v174, v172
	v_cmp_lt_f32_e64 s[6:7], 0, v174
	v_rcp_f32_e32 v132, v132
	v_mul_f32_e32 v131, 0xbfb8aa3b, v131
	v_cndmask_b32_e64 v174, v176, v177, s[6:7]
	v_mul_f32_e32 v176, 0x37800000, v174
	v_cndmask_b32_e32 v174, v174, v176, vcc
	v_cmp_class_f32_e32 vcc, v172, v225
	v_mul_f32_e32 v132, v132, v175
	v_exp_f32_e32 v131, v131
	v_cndmask_b32_e32 v172, v174, v172, vcc
	v_mul_f32_e32 v132, v132, v172
	v_mul_f32_e32 v172, 0x4f800000, v139
	v_cmp_gt_f32_e32 vcc, s30, v139
	v_add_f32_e32 v131, 1.0, v131
	v_rcp_f32_e32 v131, v131
	v_cndmask_b32_e32 v139, v139, v172, vcc
	v_sqrt_f32_e32 v172, v139
	v_and_b32_e32 v174, 0xffff0000, v184
	v_mul_f32_e32 v131, v131, v174
	v_add_f32_e32 v130, v130, v90
	v_add_u32_e32 v175, -1, v172
	v_fma_f32 v176, -v175, v172, v139
	v_cmp_ge_f32_e64 s[6:7], 0, v176
	v_add_u32_e32 v176, 1, v172
	v_mul_f32_e32 v130, 0xbfb8aa3b, v130
	v_cndmask_b32_e64 v175, v172, v175, s[6:7]
	v_fma_f32 v172, -v176, v172, v139
	v_cmp_lt_f32_e64 s[6:7], 0, v172
	v_exp_f32_e32 v130, v130
	v_add_f32_e32 v133, v133, v93
	v_cndmask_b32_e64 v172, v175, v176, s[6:7]
	v_mul_f32_e32 v175, 0x37800000, v172
	v_cndmask_b32_e32 v172, v172, v175, vcc
	v_cmp_class_f32_e32 vcc, v139, v225
	v_add_f32_e32 v130, 1.0, v130
	v_rcp_f32_e32 v130, v130
	v_cndmask_b32_e32 v139, v172, v139, vcc
	v_mul_f32_e32 v172, 0x4f800000, v138
	v_cmp_gt_f32_e32 vcc, s30, v138
	v_mul_f32_e32 v131, v131, v139
	v_lshlrev_b32_e32 v139, 16, v184
	v_cndmask_b32_e32 v138, v138, v172, vcc
	v_sqrt_f32_e32 v172, v138
	v_mul_f32_e32 v133, 0xbfb8aa3b, v133
	v_exp_f32_e32 v133, v133
	v_mul_f32_e32 v130, v130, v139
	v_add_u32_e32 v164, -1, v172
	v_fma_f32 v174, -v164, v172, v138
	v_cmp_ge_f32_e64 s[6:7], 0, v174
	v_add_u32_e32 v174, 1, v172
	v_add_f32_e32 v133, 1.0, v133
	v_cndmask_b32_e64 v164, v172, v164, s[6:7]
	v_fma_f32 v172, -v174, v172, v138
	v_cmp_lt_f32_e64 s[6:7], 0, v172
	v_rcp_f32_e32 v133, v133
	v_add_f32_e32 v126, v126, v102
	v_cndmask_b32_e64 v164, v164, v174, s[6:7]
	v_mul_f32_e32 v172, 0x37800000, v164
	v_cndmask_b32_e32 v164, v164, v172, vcc
	v_cmp_class_f32_e32 vcc, v138, v225
	v_mul_f32_e32 v126, 0xbfb8aa3b, v126
	v_exp_f32_e32 v126, v126
	v_cndmask_b32_e32 v138, v164, v138, vcc
	v_mul_f32_e32 v164, 0x4f800000, v173
	v_cmp_gt_f32_e32 vcc, s30, v173
	v_mul_f32_e32 v130, v130, v138
	v_and_b32_e32 v138, 0xffff0000, v185
	v_cndmask_b32_e32 v164, v173, v164, vcc
	v_sqrt_f32_e32 v172, v164
	v_mul_f32_e32 v133, v133, v138
	v_cvt_pk_bf16_f32 v130, v130, v131
	v_cvt_pk_bf16_f32 v138, v134, v135
	v_add_u32_e32 v139, -1, v172
	v_fma_f32 v165, -v139, v172, v164
	v_cmp_ge_f32_e64 s[6:7], 0, v165
	v_add_u32_e32 v165, 1, v172
	v_lshlrev_b64 v[134:135], 1, v[154:155]
	v_cndmask_b32_e64 v139, v172, v139, s[6:7]
	v_fma_f32 v172, -v165, v172, v164
	v_cmp_lt_f32_e64 s[6:7], 0, v172
	v_add_f32_e32 v126, 1.0, v126
	v_rcp_f32_e32 v126, v126
	v_cndmask_b32_e64 v139, v139, v165, s[6:7]
	v_mul_f32_e32 v165, 0x37800000, v139
	v_cndmask_b32_e32 v139, v139, v165, vcc
	v_cmp_class_f32_e32 vcc, v164, v225
	v_mul_f32_e32 v126, v126, v170
	s_nop 0
	v_cndmask_b32_e32 v139, v139, v164, vcc
	v_mul_f32_e32 v133, v133, v139
	v_cvt_pk_bf16_f32 v131, v132, v133
	v_cvt_pk_bf16_f32 v139, v136, v137
	global_store_dwordx2 v[152:153], v[130:131], off
	v_lshlrev_b64 v[130:131], 10, v[162:163]
	v_or_b32_e32 v136, 16, v162
	v_lshl_add_u64 v[130:131], s[12:13], 0, v[130:131]
	v_ashrrev_i32_e32 v137, 31, v136
	v_lshl_add_u64 v[132:133], v[130:131], 0, v[134:135]
	v_lshlrev_b64 v[130:131], 12, v[136:137]
	global_store_dwordx2 v[132:133], v[138:139], off
	v_lshl_add_u64 v[130:131], s[14:15], 0, v[130:131]
	v_lshl_add_u64 v[130:131], v[130:131], 0, v[134:135]
	s_nop 0
	v_add_f32_e32 v164, v126, v126
	v_cmp_ngt_f32_e32 vcc, s33, v164
	s_and_saveexec_b64 s[0:1], vcc
	s_xor_b64 s[0:1], exec, s[0:1]
	v_fmamk_f32 v163, v164, 0x39500d01, v224
	v_fmaak_f32 v163, v164, v163, 0x3c088889
	v_fmaak_f32 v163, v164, v163, 0x3d2aaaab
	v_fmaak_f32 v163, v164, v163, 0x3e2aaaab
	v_fma_f32 v163, v164, v163, 0.5
	v_fma_f32 v163, v164, v163, 1.0
	v_mul_f32_e64 v163, v163, -v164
	s_andn2_saveexec_b64 s[0:1], s[0:1]
	v_mul_f32_e32 v163, 0x3fb8aa3b, v164
	v_exp_f32_e32 v163, v163
	s_nop 0
	v_sub_f32_e32 v163, 1.0, v163
	s_or_b64 exec, exec, s[0:1]
	v_add_f32_e32 v127, v127, v103
	v_mul_f32_e32 v127, 0xbfb8aa3b, v127
	v_exp_f32_e32 v127, v127
	s_nop 0
	v_add_f32_e32 v127, 1.0, v127
	v_rcp_f32_e32 v127, v127
	s_nop 0
	v_mul_f32_e32 v127, v127, v171
	v_add_f32_e32 v165, v127, v127
	v_cmp_ngt_f32_e32 vcc, s33, v165
	s_and_saveexec_b64 s[0:1], vcc
	s_xor_b64 s[0:1], exec, s[0:1]
	v_fmamk_f32 v164, v165, 0x39500d01, v224
	v_fmaak_f32 v164, v165, v164, 0x3c088889
	v_fmaak_f32 v164, v165, v164, 0x3d2aaaab
	v_fmaak_f32 v164, v165, v164, 0x3e2aaaab
	v_fma_f32 v164, v165, v164, 0.5
	v_fma_f32 v164, v165, v164, 1.0
	v_mul_f32_e64 v164, v164, -v165
	s_andn2_saveexec_b64 s[0:1], s[0:1]
	v_mul_f32_e32 v164, 0x3fb8aa3b, v165
	v_exp_f32_e32 v164, v164
	s_nop 0
	v_sub_f32_e32 v164, 1.0, v164
	s_or_b64 exec, exec, s[0:1]
	v_add_f32_e32 v128, v128, v104
	v_mul_f32_e32 v128, 0xbfb8aa3b, v128
	v_exp_f32_e32 v128, v128
	s_nop 0
	v_add_f32_e32 v128, 1.0, v128
	v_rcp_f32_e32 v128, v128
	s_nop 0
	v_mul_f32_e32 v128, v128, v140
	v_add_f32_e32 v165, v128, v128
	v_cmp_ngt_f32_e32 vcc, s33, v165
	s_and_saveexec_b64 s[0:1], vcc
	s_xor_b64 s[0:1], exec, s[0:1]
	v_fmamk_f32 v172, v165, 0x39500d01, v224
; __device__ __forceinline__ unsigned cvt_pk_bf16(float lo, float hi) { unsigned r; asm("v_cvt_pk_bf16_f32 %0, %1, %2" : "=v"(r) : "v"(lo), "v"(hi)); return r; }
; __device__ __forceinline__ float bflo(unsigned w) { return __uint_as_float(w << 16); }
; __device__ __forceinline__ float bfhi(unsigned w) { return __uint_as_float(w & 0xffff0000u); }
; __device__ __forceinline__ float sigmoidf_(float x) { return __builtin_amdgcn_rcpf(1.f + __builtin_amdgcn_exp2f(-1.4426950408889634f * x)); }
;     __device__ __forceinline__ void operator()(AccRef acc, const Unit& u, int wr, int wc, int fr, int fq) const {
;     ...
;             EPI_ROWS_BEGIN
;                 bf16_t* xp = y3 + (size_t)row * 2048 + ch0;
;                 const u32x2 xw = *(const u32x2*)xp;
;                 const f32x4 xc = (f32x4){bflo(xw.x), bfhi(xw.x), bflo(xw.y), bfhi(xw.y)};
;                 f32x4 uo, lo;
; #pragma unroll
;                 for (int e = 0; e < 4; ++e) {
;                     const float rr = acc[ai][0][m][n][e] + ba[e], ii = acc[ai][1][m][n][e] + bi[e];
;                     const float log_a = sp[e] * sigmoidf_(rr);
;                     const float mult = sqrtf(one_minus_exp(2.f * log_a));
;                     uo[e] = xc[e] * sigmoidf_(ii) * mult; lo[e] = log_a;
;                 }
;                 u32x2 w0, w1; w0.x = cvt_pk_bf16(uo[0], uo[1]); w0.y = cvt_pk_bf16(uo[2], uo[3]); w1.x = cvt_pk_bf16(lo[0], lo[1]); w1.y = cvt_pk_bf16(lo[2], lo[3]);
;                 *(u32x2*)xp = w0;
;                 *(u32x2*)(la + (size_t)row * 512 + ch0) = w1;
	v_fmaak_f32 v172, v165, v172, 0x3c088889
	v_fmaak_f32 v172, v165, v172, 0x3d2aaaab
	v_fmaak_f32 v172, v165, v172, 0x3e2aaaab
	v_fma_f32 v172, v165, v172, 0.5
	v_fma_f32 v172, v165, v172, 1.0
	v_mul_f32_e64 v172, v172, -v165
	s_andn2_saveexec_b64 s[0:1], s[0:1]
	v_mul_f32_e32 v165, 0x3fb8aa3b, v165
	v_exp_f32_e32 v165, v165
	s_nop 0
	v_sub_f32_e32 v172, 1.0, v165
	s_or_b64 exec, exec, s[0:1]
	v_add_f32_e32 v129, v129, v105
	v_mul_f32_e32 v129, 0xbfb8aa3b, v129
	v_exp_f32_e32 v129, v129
	s_nop 0
	v_add_f32_e32 v129, 1.0, v129
	v_rcp_f32_e32 v129, v129
	s_nop 0
	v_mul_f32_e32 v129, v129, v141
	v_add_f32_e32 v173, v129, v129
	v_cmp_ngt_f32_e32 vcc, s33, v173
	s_and_saveexec_b64 s[0:1], vcc
	s_xor_b64 s[0:1], exec, s[0:1]
	v_fmamk_f32 v165, v173, 0x39500d01, v224
	v_fmaak_f32 v165, v173, v165, 0x3c088889
	v_fmaak_f32 v165, v173, v165, 0x3d2aaaab
	v_fmaak_f32 v165, v173, v165, 0x3e2aaaab
	v_fma_f32 v165, v173, v165, 0.5
	v_fma_f32 v165, v173, v165, 1.0
	v_mul_f32_e64 v165, v165, -v173
	s_andn2_saveexec_b64 s[0:1], s[0:1]
	v_mul_f32_e32 v165, 0x3fb8aa3b, v173
	v_exp_f32_e32 v165, v165
	s_nop 0
	v_sub_f32_e32 v165, 1.0, v165
	s_or_b64 exec, exec, s[0:1]
	v_mul_f32_e32 v173, 0x4f800000, v172
	v_cmp_gt_f32_e32 vcc, s30, v172
	v_add_f32_e32 v124, v124, v92
	v_mul_f32_e32 v124, 0xbfb8aa3b, v124
	v_cndmask_b32_e32 v172, v172, v173, vcc
	v_sqrt_f32_e32 v173, v172
	v_exp_f32_e32 v124, v124
	s_waitcnt vmcnt(16)
	v_lshlrev_b32_e32 v174, 16, v187
	v_add_f32_e32 v123, v123, v91
	v_add_u32_e32 v175, -1, v173
	v_fma_f32 v176, -v175, v173, v172
	v_cmp_ge_f32_e64 s[6:7], 0, v176
	v_add_u32_e32 v176, 1, v173
	v_add_f32_e32 v124, 1.0, v124
	v_cndmask_b32_e64 v175, v173, v175, s[6:7]
	v_fma_f32 v173, -v176, v173, v172
	v_cmp_lt_f32_e64 s[6:7], 0, v173
	v_rcp_f32_e32 v124, v124
	v_mul_f32_e32 v123, 0xbfb8aa3b, v123
	v_cndmask_b32_e64 v173, v175, v176, s[6:7]
	v_mul_f32_e32 v175, 0x37800000, v173
	v_cndmask_b32_e32 v173, v173, v175, vcc
	v_cmp_class_f32_e32 vcc, v172, v225
	v_mul_f32_e32 v124, v124, v174
	v_exp_f32_e32 v123, v123
	v_cndmask_b32_e32 v172, v173, v172, vcc
	v_mul_f32_e32 v124, v124, v172
	v_mul_f32_e32 v172, 0x4f800000, v164
	v_cmp_gt_f32_e32 vcc, s30, v164
	v_add_f32_e32 v123, 1.0, v123
	v_rcp_f32_e32 v123, v123
	v_cndmask_b32_e32 v164, v164, v172, vcc
	v_sqrt_f32_e32 v172, v164
	v_and_b32_e32 v173, 0xffff0000, v186
	v_mul_f32_e32 v123, v123, v173
	v_add_f32_e32 v122, v122, v90
	v_add_u32_e32 v174, -1, v172
	v_fma_f32 v175, -v174, v172, v164
	v_cmp_ge_f32_e64 s[6:7], 0, v175
	v_add_u32_e32 v175, 1, v172
	v_mul_f32_e32 v122, 0xbfb8aa3b, v122
	v_cndmask_b32_e64 v174, v172, v174, s[6:7]
	v_fma_f32 v172, -v175, v172, v164
	v_cmp_lt_f32_e64 s[6:7], 0, v172
	v_exp_f32_e32 v122, v122
	v_add_f32_e32 v125, v125, v93
	v_cndmask_b32_e64 v172, v174, v175, s[6:7]
	v_mul_f32_e32 v174, 0x37800000, v172
	v_cndmask_b32_e32 v172, v172, v174, vcc
	v_cmp_class_f32_e32 vcc, v164, v225
	v_add_f32_e32 v122, 1.0, v122
	v_rcp_f32_e32 v122, v122
	v_cndmask_b32_e32 v164, v172, v164, vcc
	v_mul_f32_e32 v172, 0x4f800000, v163
	v_cmp_gt_f32_e32 vcc, s30, v163
	v_mul_f32_e32 v123, v123, v164
	v_mul_f32_e32 v125, 0xbfb8aa3b, v125
	v_cndmask_b32_e32 v163, v163, v172, vcc
	v_sqrt_f32_e32 v172, v163
	v_lshlrev_b32_e32 v138, 16, v186
	v_exp_f32_e32 v125, v125
	v_mul_f32_e32 v122, v122, v138
	v_add_u32_e32 v164, -1, v172
	v_fma_f32 v173, -v164, v172, v163
	v_cmp_ge_f32_e64 s[6:7], 0, v173
	v_add_u32_e32 v173, 1, v172
	v_and_b32_e32 v138, 0xffff0000, v187
	v_cndmask_b32_e64 v164, v172, v164, s[6:7]
	v_fma_f32 v172, -v173, v172, v163
	v_cmp_lt_f32_e64 s[6:7], 0, v172
	v_add_f32_e32 v125, 1.0, v125
	v_rcp_f32_e32 v125, v125
	v_cndmask_b32_e64 v164, v164, v173, s[6:7]
	v_mul_f32_e32 v172, 0x37800000, v164
	v_cndmask_b32_e32 v164, v164, v172, vcc
	v_cmp_class_f32_e32 vcc, v163, v225
	v_mul_f32_e32 v125, v125, v138
	v_cvt_pk_bf16_f32 v126, v126, v127
	v_cvt_pk_bf16_f32 v127, v128, v129
	v_add_f32_e32 v118, v118, v102
	v_cndmask_b32_e32 v163, v164, v163, vcc
	v_mul_f32_e32 v164, 0x4f800000, v165
	v_cmp_gt_f32_e32 vcc, s30, v165
	v_mul_f32_e32 v122, v122, v163
	v_cvt_pk_bf16_f32 v122, v122, v123
	v_mul_f32_e32 v118, 0xbfb8aa3b, v118
	v_cndmask_b32_e32 v164, v165, v164, vcc
	v_sqrt_f32_e32 v165, v164
	v_exp_f32_e32 v118, v118
	v_add_u32_e32 v139, -1, v165
	v_fma_f32 v163, -v139, v165, v164
	v_cmp_ge_f32_e64 s[6:7], 0, v163
	v_add_u32_e32 v163, 1, v165
	v_add_f32_e32 v118, 1.0, v118
	v_cndmask_b32_e64 v139, v165, v139, s[6:7]
	v_fma_f32 v165, -v163, v165, v164
	v_cmp_lt_f32_e64 s[6:7], 0, v165
	v_rcp_f32_e32 v118, v118
	s_nop 0
	v_cndmask_b32_e64 v139, v139, v163, s[6:7]
	v_mul_f32_e32 v163, 0x37800000, v139
	v_cndmask_b32_e32 v139, v139, v163, vcc
	v_cmp_class_f32_e32 vcc, v164, v225
	v_mul_f32_e32 v118, v118, v170
	s_nop 0
	v_cndmask_b32_e32 v139, v139, v164, vcc
	v_mul_f32_e32 v125, v125, v139
	v_cvt_pk_bf16_f32 v123, v124, v125
	global_store_dwordx2 v[130:131], v[122:123], off
	v_lshlrev_b64 v[122:123], 10, v[136:137]
	v_lshl_add_u64 v[122:123], s[12:13], 0, v[122:123]
	v_lshl_add_u64 v[124:125], v[122:123], 0, v[134:135]
	global_store_dwordx2 v[124:125], v[126:127], off
	v_or_b32_e32 v126, 32, v162
	v_ashrrev_i32_e32 v127, 31, v126
	v_lshlrev_b64 v[122:123], 12, v[126:127]
	v_lshl_add_u64 v[122:123], s[14:15], 0, v[122:123]
	v_lshl_add_u64 v[122:123], v[122:123], 0, v[134:135]
	s_nop 0
	v_add_f32_e32 v137, v118, v118
	v_cmp_ngt_f32_e32 vcc, s33, v137
	s_and_saveexec_b64 s[0:1], vcc
	s_xor_b64 s[0:1], exec, s[0:1]
	v_fmamk_f32 v136, v137, 0x39500d01, v224
	v_fmaak_f32 v136, v137, v136, 0x3c088889
	v_fmaak_f32 v136, v137, v136, 0x3d2aaaab
	v_fmaak_f32 v136, v137, v136, 0x3e2aaaab
; __device__ __forceinline__ unsigned cvt_pk_bf16(float lo, float hi) { unsigned r; asm("v_cvt_pk_bf16_f32 %0, %1, %2" : "=v"(r) : "v"(lo), "v"(hi)); return r; }
; __device__ __forceinline__ float bflo(unsigned w) { return __uint_as_float(w << 16); }
; __device__ __forceinline__ float bfhi(unsigned w) { return __uint_as_float(w & 0xffff0000u); }
; __device__ __forceinline__ float sigmoidf_(float x) { return __builtin_amdgcn_rcpf(1.f + __builtin_amdgcn_exp2f(-1.4426950408889634f * x)); }
;     __device__ __forceinline__ void operator()(AccRef acc, const Unit& u, int wr, int wc, int fr, int fq) const {
;     ...
;             EPI_ROWS_BEGIN
;                 bf16_t* xp = y3 + (size_t)row * 2048 + ch0;
;                 const u32x2 xw = *(const u32x2*)xp;
;                 const f32x4 xc = (f32x4){bflo(xw.x), bfhi(xw.x), bflo(xw.y), bfhi(xw.y)};
;                 f32x4 uo, lo;
; #pragma unroll
;                 for (int e = 0; e < 4; ++e) {
;                     const float rr = acc[ai][0][m][n][e] + ba[e], ii = acc[ai][1][m][n][e] + bi[e];
;                     const float log_a = sp[e] * sigmoidf_(rr);
;                     const float mult = sqrtf(one_minus_exp(2.f * log_a));
;                     uo[e] = xc[e] * sigmoidf_(ii) * mult; lo[e] = log_a;
;                 }
;                 u32x2 w0, w1; w0.x = cvt_pk_bf16(uo[0], uo[1]); w0.y = cvt_pk_bf16(uo[2], uo[3]); w1.x = cvt_pk_bf16(lo[0], lo[1]); w1.y = cvt_pk_bf16(lo[2], lo[3]);
;                 *(u32x2*)xp = w0;
;                 *(u32x2*)(la + (size_t)row * 512 + ch0) = w1;
	v_fma_f32 v136, v137, v136, 0.5
	v_fma_f32 v136, v137, v136, 1.0
	v_mul_f32_e64 v136, v136, -v137
	s_andn2_saveexec_b64 s[0:1], s[0:1]
	v_mul_f32_e32 v136, 0x3fb8aa3b, v137
	v_exp_f32_e32 v136, v136
	s_nop 0
	v_sub_f32_e32 v136, 1.0, v136
	s_or_b64 exec, exec, s[0:1]
	v_add_f32_e32 v119, v119, v103
	v_mul_f32_e32 v119, 0xbfb8aa3b, v119
	v_exp_f32_e32 v119, v119
	s_nop 0
	v_add_f32_e32 v119, 1.0, v119
	v_rcp_f32_e32 v119, v119
	s_nop 0
	v_mul_f32_e32 v119, v119, v171
	v_add_f32_e32 v138, v119, v119
	v_cmp_ngt_f32_e32 vcc, s33, v138
	s_and_saveexec_b64 s[0:1], vcc
	s_xor_b64 s[0:1], exec, s[0:1]
	v_fmamk_f32 v137, v138, 0x39500d01, v224
	v_fmaak_f32 v137, v138, v137, 0x3c088889
	v_fmaak_f32 v137, v138, v137, 0x3d2aaaab
	v_fmaak_f32 v137, v138, v137, 0x3e2aaaab
	v_fma_f32 v137, v138, v137, 0.5
	v_fma_f32 v137, v138, v137, 1.0
	v_mul_f32_e64 v137, v137, -v138
	s_andn2_saveexec_b64 s[0:1], s[0:1]
	v_mul_f32_e32 v137, 0x3fb8aa3b, v138
	v_exp_f32_e32 v137, v137
	s_nop 0
	v_sub_f32_e32 v137, 1.0, v137
	s_or_b64 exec, exec, s[0:1]
	v_add_f32_e32 v120, v120, v104
	v_mul_f32_e32 v120, 0xbfb8aa3b, v120
	v_exp_f32_e32 v120, v120
	s_nop 0
	v_add_f32_e32 v120, 1.0, v120
	v_rcp_f32_e32 v120, v120
	s_nop 0
	v_mul_f32_e32 v120, v120, v140
	v_add_f32_e32 v138, v120, v120
	v_cmp_ngt_f32_e32 vcc, s33, v138
	s_and_saveexec_b64 s[0:1], vcc
	s_xor_b64 s[0:1], exec, s[0:1]
	v_fmamk_f32 v139, v138, 0x39500d01, v224
	v_fmaak_f32 v139, v138, v139, 0x3c088889
	v_fmaak_f32 v139, v138, v139, 0x3d2aaaab
	v_fmaak_f32 v139, v138, v139, 0x3e2aaaab
	v_fma_f32 v139, v138, v139, 0.5
	v_fma_f32 v139, v138, v139, 1.0
	v_mul_f32_e64 v139, v139, -v138
	s_andn2_saveexec_b64 s[0:1], s[0:1]
	v_mul_f32_e32 v138, 0x3fb8aa3b, v138
	v_exp_f32_e32 v138, v138
	s_nop 0
	v_sub_f32_e32 v139, 1.0, v138
	s_or_b64 exec, exec, s[0:1]
	v_add_f32_e32 v121, v121, v105
	v_mul_f32_e32 v121, 0xbfb8aa3b, v121
	v_exp_f32_e32 v121, v121
	s_nop 0
	v_add_f32_e32 v121, 1.0, v121
	v_rcp_f32_e32 v121, v121
	s_nop 0
	v_mul_f32_e32 v121, v121, v141
	v_add_f32_e32 v163, v121, v121
	v_cmp_ngt_f32_e32 vcc, s33, v163
	s_and_saveexec_b64 s[0:1], vcc
	s_xor_b64 s[0:1], exec, s[0:1]
	v_fmamk_f32 v138, v163, 0x39500d01, v224
	v_fmaak_f32 v138, v163, v138, 0x3c088889
	v_fmaak_f32 v138, v163, v138, 0x3d2aaaab
	v_fmaak_f32 v138, v163, v138, 0x3e2aaaab
	v_fma_f32 v138, v163, v138, 0.5
	v_fma_f32 v138, v163, v138, 1.0
	v_mul_f32_e64 v138, v138, -v163
	s_andn2_saveexec_b64 s[0:1], s[0:1]
	v_mul_f32_e32 v138, 0x3fb8aa3b, v163
	v_exp_f32_e32 v138, v138
	s_nop 0
	v_sub_f32_e32 v138, 1.0, v138
	s_or_b64 exec, exec, s[0:1]
	v_mul_f32_e32 v163, 0x4f800000, v139
	v_cmp_gt_f32_e32 vcc, s30, v139
	v_add_f32_e32 v116, v116, v92
	v_mul_f32_e32 v116, 0xbfb8aa3b, v116
	v_cndmask_b32_e32 v139, v139, v163, vcc
	v_sqrt_f32_e32 v163, v139
	v_exp_f32_e32 v116, v116
	s_waitcnt vmcnt(17)
	v_lshlrev_b32_e32 v164, 16, v189
	v_add_f32_e32 v115, v115, v91
	v_add_u32_e32 v165, -1, v163
	v_fma_f32 v172, -v165, v163, v139
	v_cmp_ge_f32_e64 s[6:7], 0, v172
	v_add_u32_e32 v172, 1, v163
	v_add_f32_e32 v116, 1.0, v116
	v_cndmask_b32_e64 v165, v163, v165, s[6:7]
	v_fma_f32 v163, -v172, v163, v139
	v_cmp_lt_f32_e64 s[6:7], 0, v163
	v_rcp_f32_e32 v116, v116
	v_mul_f32_e32 v115, 0xbfb8aa3b, v115
	v_cndmask_b32_e64 v163, v165, v172, s[6:7]
	v_mul_f32_e32 v165, 0x37800000, v163
	v_cndmask_b32_e32 v163, v163, v165, vcc
	v_cmp_class_f32_e32 vcc, v139, v225
	v_mul_f32_e32 v116, v116, v164
	v_exp_f32_e32 v115, v115
	v_cndmask_b32_e32 v139, v163, v139, vcc
	v_mul_f32_e32 v116, v116, v139
	v_mul_f32_e32 v139, 0x4f800000, v137
	v_cmp_gt_f32_e32 vcc, s30, v137
	v_add_f32_e32 v115, 1.0, v115
	v_rcp_f32_e32 v115, v115
	v_cndmask_b32_e32 v137, v137, v139, vcc
	v_sqrt_f32_e32 v139, v137
	v_and_b32_e32 v163, 0xffff0000, v188
	v_mul_f32_e32 v115, v115, v163
	v_add_f32_e32 v114, v114, v90
	v_add_u32_e32 v164, -1, v139
	v_fma_f32 v165, -v164, v139, v137
	v_cmp_ge_f32_e64 s[6:7], 0, v165
	v_add_u32_e32 v165, 1, v139
	v_mul_f32_e32 v114, 0xbfb8aa3b, v114
	v_cndmask_b32_e64 v164, v139, v164, s[6:7]
	v_fma_f32 v139, -v165, v139, v137
	v_cmp_lt_f32_e64 s[6:7], 0, v139
	v_exp_f32_e32 v114, v114
	v_add_f32_e32 v117, v117, v93
	v_cndmask_b32_e64 v139, v164, v165, s[6:7]
	v_mul_f32_e32 v164, 0x37800000, v139
	v_cndmask_b32_e32 v139, v139, v164, vcc
	v_cmp_class_f32_e32 vcc, v137, v225
	v_add_f32_e32 v114, 1.0, v114
	v_rcp_f32_e32 v114, v114
	v_cndmask_b32_e32 v137, v139, v137, vcc
	v_mul_f32_e32 v139, 0x4f800000, v136
	v_cmp_gt_f32_e32 vcc, s30, v136
	v_mul_f32_e32 v115, v115, v137
	v_mul_f32_e32 v117, 0xbfb8aa3b, v117
	v_cndmask_b32_e32 v136, v136, v139, vcc
	v_sqrt_f32_e32 v139, v136
	v_lshlrev_b32_e32 v128, 16, v188
	v_exp_f32_e32 v117, v117
	v_mul_f32_e32 v114, v114, v128
	v_add_u32_e32 v137, -1, v139
	v_fma_f32 v163, -v137, v139, v136
	v_cmp_ge_f32_e64 s[6:7], 0, v163
	v_add_u32_e32 v163, 1, v139
	v_and_b32_e32 v128, 0xffff0000, v189
	v_cndmask_b32_e64 v137, v139, v137, s[6:7]
	v_fma_f32 v139, -v163, v139, v136
	v_cmp_lt_f32_e64 s[6:7], 0, v139
	v_add_f32_e32 v117, 1.0, v117
	v_rcp_f32_e32 v117, v117
	v_cndmask_b32_e64 v137, v137, v163, s[6:7]
	v_mul_f32_e32 v139, 0x37800000, v137
	v_cndmask_b32_e32 v137, v137, v139, vcc
	v_cmp_class_f32_e32 vcc, v136, v225
	v_mul_f32_e32 v117, v117, v128
	v_cvt_pk_bf16_f32 v118, v118, v119
	v_cvt_pk_bf16_f32 v119, v120, v121
	v_add_f32_e32 v110, v110, v102
	v_cndmask_b32_e32 v136, v137, v136, vcc
	v_mul_f32_e32 v137, 0x4f800000, v138
	v_cmp_gt_f32_e32 vcc, s30, v138
	v_mul_f32_e32 v114, v114, v136
	v_cvt_pk_bf16_f32 v114, v114, v115
	v_mul_f32_e32 v110, 0xbfb8aa3b, v110
	v_cndmask_b32_e32 v137, v138, v137, vcc
	v_sqrt_f32_e32 v138, v137
; __device__ __forceinline__ unsigned cvt_pk_bf16(float lo, float hi) { unsigned r; asm("v_cvt_pk_bf16_f32 %0, %1, %2" : "=v"(r) : "v"(lo), "v"(hi)); return r; }
; __device__ __forceinline__ float bflo(unsigned w) { return __uint_as_float(w << 16); }
; __device__ __forceinline__ float bfhi(unsigned w) { return __uint_as_float(w & 0xffff0000u); }
; __device__ __forceinline__ float sigmoidf_(float x) { return __builtin_amdgcn_rcpf(1.f + __builtin_amdgcn_exp2f(-1.4426950408889634f * x)); }
;     __device__ __forceinline__ void operator()(AccRef acc, const Unit& u, int wr, int wc, int fr, int fq) const {
;     ...
;             EPI_ROWS_BEGIN
;                 bf16_t* xp = y3 + (size_t)row * 2048 + ch0;
;                 const u32x2 xw = *(const u32x2*)xp;
;                 const f32x4 xc = (f32x4){bflo(xw.x), bfhi(xw.x), bflo(xw.y), bfhi(xw.y)};
;                 f32x4 uo, lo;
; #pragma unroll
;                 for (int e = 0; e < 4; ++e) {
;                     const float rr = acc[ai][0][m][n][e] + ba[e], ii = acc[ai][1][m][n][e] + bi[e];
;                     const float log_a = sp[e] * sigmoidf_(rr);
;                     const float mult = sqrtf(one_minus_exp(2.f * log_a));
;                     uo[e] = xc[e] * sigmoidf_(ii) * mult; lo[e] = log_a;
;                 }
;                 u32x2 w0, w1; w0.x = cvt_pk_bf16(uo[0], uo[1]); w0.y = cvt_pk_bf16(uo[2], uo[3]); w1.x = cvt_pk_bf16(lo[0], lo[1]); w1.y = cvt_pk_bf16(lo[2], lo[3]);
;                 *(u32x2*)xp = w0;
;                 *(u32x2*)(la + (size_t)row * 512 + ch0) = w1;
	v_exp_f32_e32 v110, v110
	v_add_u32_e32 v129, -1, v138
	v_fma_f32 v136, -v129, v138, v137
	v_cmp_ge_f32_e64 s[6:7], 0, v136
	v_add_u32_e32 v136, 1, v138
	v_add_f32_e32 v110, 1.0, v110
	v_cndmask_b32_e64 v129, v138, v129, s[6:7]
	v_fma_f32 v138, -v136, v138, v137
	v_cmp_lt_f32_e64 s[6:7], 0, v138
	v_rcp_f32_e32 v110, v110
	s_nop 0
	v_cndmask_b32_e64 v129, v129, v136, s[6:7]
	v_mul_f32_e32 v136, 0x37800000, v129
	v_cndmask_b32_e32 v129, v129, v136, vcc
	v_cmp_class_f32_e32 vcc, v137, v225
	v_mul_f32_e32 v110, v110, v170
	s_nop 0
	v_cndmask_b32_e32 v129, v129, v137, vcc
	v_mul_f32_e32 v117, v117, v129
	v_cvt_pk_bf16_f32 v115, v116, v117
	global_store_dwordx2 v[122:123], v[114:115], off
	v_lshlrev_b64 v[114:115], 10, v[126:127]
	v_lshl_add_u64 v[114:115], s[12:13], 0, v[114:115]
	v_lshl_add_u64 v[116:117], v[114:115], 0, v[134:135]
	global_store_dwordx2 v[116:117], v[118:119], off
	v_or_b32_e32 v118, 48, v162
	v_ashrrev_i32_e32 v119, 31, v118
	v_lshlrev_b64 v[114:115], 12, v[118:119]
	v_lshl_add_u64 v[114:115], s[14:15], 0, v[114:115]
	v_lshl_add_u64 v[114:115], v[114:115], 0, v[134:135]
	s_nop 0
	v_add_f32_e32 v127, v110, v110
	v_cmp_ngt_f32_e32 vcc, s33, v127
	s_and_saveexec_b64 s[0:1], vcc
	s_xor_b64 s[0:1], exec, s[0:1]
	v_fmamk_f32 v126, v127, 0x39500d01, v224
	v_fmaak_f32 v126, v127, v126, 0x3c088889
	v_fmaak_f32 v126, v127, v126, 0x3d2aaaab
	v_fmaak_f32 v126, v127, v126, 0x3e2aaaab
	v_fma_f32 v126, v127, v126, 0.5
	v_fma_f32 v126, v127, v126, 1.0
	v_mul_f32_e64 v126, v126, -v127
	s_andn2_saveexec_b64 s[0:1], s[0:1]
	v_mul_f32_e32 v126, 0x3fb8aa3b, v127
	v_exp_f32_e32 v126, v126
	s_nop 0
	v_sub_f32_e32 v126, 1.0, v126
	s_or_b64 exec, exec, s[0:1]
	v_add_f32_e32 v111, v111, v103
	v_mul_f32_e32 v111, 0xbfb8aa3b, v111
	v_exp_f32_e32 v111, v111
	s_nop 0
	v_add_f32_e32 v111, 1.0, v111
	v_rcp_f32_e32 v111, v111
	s_nop 0
	v_mul_f32_e32 v111, v111, v171
	v_add_f32_e32 v128, v111, v111
	v_cmp_ngt_f32_e32 vcc, s33, v128
	s_and_saveexec_b64 s[0:1], vcc
	s_xor_b64 s[0:1], exec, s[0:1]
	v_fmamk_f32 v127, v128, 0x39500d01, v224
	v_fmaak_f32 v127, v128, v127, 0x3c088889
	v_fmaak_f32 v127, v128, v127, 0x3d2aaaab
	v_fmaak_f32 v127, v128, v127, 0x3e2aaaab
	v_fma_f32 v127, v128, v127, 0.5
	v_fma_f32 v127, v128, v127, 1.0
	v_mul_f32_e64 v127, v127, -v128
	s_andn2_saveexec_b64 s[0:1], s[0:1]
	v_mul_f32_e32 v127, 0x3fb8aa3b, v128
	v_exp_f32_e32 v127, v127
	s_nop 0
	v_sub_f32_e32 v127, 1.0, v127
	s_or_b64 exec, exec, s[0:1]
	v_add_f32_e32 v112, v112, v104
	v_mul_f32_e32 v112, 0xbfb8aa3b, v112
	v_exp_f32_e32 v112, v112
	s_nop 0
	v_add_f32_e32 v112, 1.0, v112
	v_rcp_f32_e32 v112, v112
	s_nop 0
	v_mul_f32_e32 v112, v112, v140
	v_add_f32_e32 v128, v112, v112
	v_cmp_ngt_f32_e32 vcc, s33, v128
	s_and_saveexec_b64 s[0:1], vcc
	s_xor_b64 s[0:1], exec, s[0:1]
	v_fmamk_f32 v129, v128, 0x39500d01, v224
	v_fmaak_f32 v129, v128, v129, 0x3c088889
	v_fmaak_f32 v129, v128, v129, 0x3d2aaaab
	v_fmaak_f32 v129, v128, v129, 0x3e2aaaab
	v_fma_f32 v129, v128, v129, 0.5
	v_fma_f32 v129, v128, v129, 1.0
	v_mul_f32_e64 v129, v129, -v128
	s_andn2_saveexec_b64 s[0:1], s[0:1]
	v_mul_f32_e32 v128, 0x3fb8aa3b, v128
	v_exp_f32_e32 v128, v128
	s_nop 0
	v_sub_f32_e32 v129, 1.0, v128
	s_or_b64 exec, exec, s[0:1]
	v_add_f32_e32 v113, v113, v105
	v_mul_f32_e32 v113, 0xbfb8aa3b, v113
	v_exp_f32_e32 v113, v113
	s_nop 0
	v_add_f32_e32 v113, 1.0, v113
	v_rcp_f32_e32 v113, v113
	s_nop 0
	v_mul_f32_e32 v113, v113, v141
	v_add_f32_e32 v136, v113, v113
	v_cmp_ngt_f32_e32 vcc, s33, v136
	s_and_saveexec_b64 s[0:1], vcc
	s_xor_b64 s[0:1], exec, s[0:1]
	v_fmamk_f32 v128, v136, 0x39500d01, v224
	v_fmaak_f32 v128, v136, v128, 0x3c088889
	v_fmaak_f32 v128, v136, v128, 0x3d2aaaab
	v_fmaak_f32 v128, v136, v128, 0x3e2aaaab
	v_fma_f32 v128, v136, v128, 0.5
	v_fma_f32 v128, v136, v128, 1.0
	v_mul_f32_e64 v128, v128, -v136
	s_andn2_saveexec_b64 s[0:1], s[0:1]
	v_mul_f32_e32 v128, 0x3fb8aa3b, v136
	v_exp_f32_e32 v128, v128
	s_nop 0
	v_sub_f32_e32 v128, 1.0, v128
	s_or_b64 exec, exec, s[0:1]
	v_mul_f32_e32 v136, 0x4f800000, v129
	v_cmp_gt_f32_e32 vcc, s30, v129
	v_add_f32_e32 v108, v108, v92
	v_mul_f32_e32 v108, 0xbfb8aa3b, v108
	v_cndmask_b32_e32 v129, v129, v136, vcc
	v_sqrt_f32_e32 v136, v129
	v_exp_f32_e32 v108, v108
	s_waitcnt vmcnt(18)
; __device__ __forceinline__ unsigned cvt_pk_bf16(float lo, float hi) { unsigned r; asm("v_cvt_pk_bf16_f32 %0, %1, %2" : "=v"(r) : "v"(lo), "v"(hi)); return r; }
; __device__ __forceinline__ float bflo(unsigned w) { return __uint_as_float(w << 16); }
; __device__ __forceinline__ float bfhi(unsigned w) { return __uint_as_float(w & 0xffff0000u); }
; __device__ __forceinline__ float sigmoidf_(float x) { return __builtin_amdgcn_rcpf(1.f + __builtin_amdgcn_exp2f(-1.4426950408889634f * x)); }
;     __device__ __forceinline__ void operator()(AccRef acc, const Unit& u, int wr, int wc, int fr, int fq) const {
;     ...
;             EPI_ROWS_BEGIN
;                 bf16_t* xp = y3 + (size_t)row * 2048 + ch0;
;                 const u32x2 xw = *(const u32x2*)xp;
;                 const f32x4 xc = (f32x4){bflo(xw.x), bfhi(xw.x), bflo(xw.y), bfhi(xw.y)};
;                 f32x4 uo, lo;
; #pragma unroll
;                 for (int e = 0; e < 4; ++e) {
;                     const float rr = acc[ai][0][m][n][e] + ba[e], ii = acc[ai][1][m][n][e] + bi[e];
;                     const float log_a = sp[e] * sigmoidf_(rr);
;                     const float mult = sqrtf(one_minus_exp(2.f * log_a));
;                     uo[e] = xc[e] * sigmoidf_(ii) * mult; lo[e] = log_a;
;                 }
;                 u32x2 w0, w1; w0.x = cvt_pk_bf16(uo[0], uo[1]); w0.y = cvt_pk_bf16(uo[2], uo[3]); w1.x = cvt_pk_bf16(lo[0], lo[1]); w1.y = cvt_pk_bf16(lo[2], lo[3]);
;                 *(u32x2*)xp = w0;
;                 *(u32x2*)(la + (size_t)row * 512 + ch0) = w1;
	v_lshlrev_b32_e32 v137, 16, v191
	v_add_f32_e32 v107, v107, v91
	v_add_u32_e32 v138, -1, v136
	v_fma_f32 v139, -v138, v136, v129
	v_cmp_ge_f32_e64 s[6:7], 0, v139
	v_add_u32_e32 v139, 1, v136
	v_add_f32_e32 v108, 1.0, v108
	v_cndmask_b32_e64 v138, v136, v138, s[6:7]
	v_fma_f32 v136, -v139, v136, v129
	v_cmp_lt_f32_e64 s[6:7], 0, v136
	v_rcp_f32_e32 v108, v108
	v_mul_f32_e32 v107, 0xbfb8aa3b, v107
	v_cndmask_b32_e64 v136, v138, v139, s[6:7]
	v_mul_f32_e32 v138, 0x37800000, v136
	v_cndmask_b32_e32 v136, v136, v138, vcc
	v_cmp_class_f32_e32 vcc, v129, v225
	v_mul_f32_e32 v108, v108, v137
	v_exp_f32_e32 v107, v107
	v_cndmask_b32_e32 v129, v136, v129, vcc
	v_mul_f32_e32 v108, v108, v129
	v_mul_f32_e32 v129, 0x4f800000, v127
	v_cmp_gt_f32_e32 vcc, s30, v127
	v_add_f32_e32 v107, 1.0, v107
	v_rcp_f32_e32 v107, v107
	v_cndmask_b32_e32 v127, v127, v129, vcc
	v_sqrt_f32_e32 v129, v127
	v_and_b32_e32 v136, 0xffff0000, v190
	v_mul_f32_e32 v107, v107, v136
	v_add_f32_e32 v106, v106, v90
	v_add_u32_e32 v137, -1, v129
	v_fma_f32 v138, -v137, v129, v127
	v_cmp_ge_f32_e64 s[6:7], 0, v138
	v_add_u32_e32 v138, 1, v129
	v_mul_f32_e32 v106, 0xbfb8aa3b, v106
	v_cndmask_b32_e64 v137, v129, v137, s[6:7]
	v_fma_f32 v129, -v138, v129, v127
	v_cmp_lt_f32_e64 s[6:7], 0, v129
	v_exp_f32_e32 v106, v106
	v_add_f32_e32 v109, v109, v93
	v_cndmask_b32_e64 v129, v137, v138, s[6:7]
	v_mul_f32_e32 v137, 0x37800000, v129
	v_cndmask_b32_e32 v129, v129, v137, vcc
	v_cmp_class_f32_e32 vcc, v127, v225
	v_add_f32_e32 v106, 1.0, v106
	v_rcp_f32_e32 v106, v106
	v_cndmask_b32_e32 v127, v129, v127, vcc
	v_mul_f32_e32 v129, 0x4f800000, v126
	v_cmp_gt_f32_e32 vcc, s30, v126
	v_mul_f32_e32 v107, v107, v127
	v_mul_f32_e32 v109, 0xbfb8aa3b, v109
	v_cndmask_b32_e32 v126, v126, v129, vcc
	v_sqrt_f32_e32 v129, v126
	v_lshlrev_b32_e32 v120, 16, v190
	v_exp_f32_e32 v109, v109
	v_mul_f32_e32 v106, v106, v120
	v_add_u32_e32 v127, -1, v129
	v_fma_f32 v136, -v127, v129, v126
	v_cmp_ge_f32_e64 s[6:7], 0, v136
	v_add_u32_e32 v136, 1, v129
	v_and_b32_e32 v120, 0xffff0000, v191
	v_cndmask_b32_e64 v127, v129, v127, s[6:7]
	v_fma_f32 v129, -v136, v129, v126
	v_cmp_lt_f32_e64 s[6:7], 0, v129
	v_add_f32_e32 v109, 1.0, v109
	v_rcp_f32_e32 v109, v109
	v_cndmask_b32_e64 v127, v127, v136, s[6:7]
	v_mul_f32_e32 v129, 0x37800000, v127
	v_cndmask_b32_e32 v127, v127, v129, vcc
	v_cmp_class_f32_e32 vcc, v126, v225
	v_mul_f32_e32 v109, v109, v120
	v_cvt_pk_bf16_f32 v110, v110, v111
	v_cvt_pk_bf16_f32 v111, v112, v113
	v_add_f32_e32 v98, v98, v102
	v_cndmask_b32_e32 v126, v127, v126, vcc
	v_mul_f32_e32 v127, 0x4f800000, v128
	v_cmp_gt_f32_e32 vcc, s30, v128
	v_mul_f32_e32 v106, v106, v126
	v_cvt_pk_bf16_f32 v106, v106, v107
	v_mul_f32_e32 v98, 0xbfb8aa3b, v98
	v_cndmask_b32_e32 v127, v128, v127, vcc
	v_sqrt_f32_e32 v128, v127
	v_exp_f32_e32 v98, v98
	v_add_u32_e32 v121, -1, v128
	v_fma_f32 v126, -v121, v128, v127
	v_cmp_ge_f32_e64 s[6:7], 0, v126
	v_add_u32_e32 v126, 1, v128
	v_add_f32_e32 v98, 1.0, v98
	v_cndmask_b32_e64 v121, v128, v121, s[6:7]
	v_fma_f32 v128, -v126, v128, v127
	v_cmp_lt_f32_e64 s[6:7], 0, v128
	v_rcp_f32_e32 v98, v98
	s_nop 0
	v_cndmask_b32_e64 v121, v121, v126, s[6:7]
	v_mul_f32_e32 v126, 0x37800000, v121
	v_cndmask_b32_e32 v121, v121, v126, vcc
	v_cmp_class_f32_e32 vcc, v127, v225
	v_mul_f32_e32 v98, v98, v170
	s_nop 0
	v_cndmask_b32_e32 v121, v121, v127, vcc
	v_mul_f32_e32 v109, v109, v121
	v_cvt_pk_bf16_f32 v107, v108, v109
	global_store_dwordx2 v[114:115], v[106:107], off
	v_lshlrev_b64 v[106:107], 10, v[118:119]
	v_lshl_add_u64 v[106:107], s[12:13], 0, v[106:107]
	v_lshl_add_u64 v[108:109], v[106:107], 0, v[134:135]
	global_store_dwordx2 v[108:109], v[110:111], off
	v_add_u32_e32 v110, 0x80, v162
	v_ashrrev_i32_e32 v111, 31, v110
	v_lshlrev_b64 v[106:107], 12, v[110:111]
	v_lshl_add_u64 v[106:107], s[14:15], 0, v[106:107]
	v_lshl_add_u64 v[106:107], v[106:107], 0, v[134:135]
	s_nop 0
	v_add_f32_e32 v119, v98, v98
	v_cmp_ngt_f32_e32 vcc, s33, v119
	s_and_saveexec_b64 s[0:1], vcc
	s_xor_b64 s[0:1], exec, s[0:1]
	v_fmamk_f32 v118, v119, 0x39500d01, v224
	v_fmaak_f32 v118, v119, v118, 0x3c088889
	v_fmaak_f32 v118, v119, v118, 0x3d2aaaab
	v_fmaak_f32 v118, v119, v118, 0x3e2aaaab
	v_fma_f32 v118, v119, v118, 0.5
	v_fma_f32 v118, v119, v118, 1.0
	v_mul_f32_e64 v118, v118, -v119
	s_andn2_saveexec_b64 s[0:1], s[0:1]
	v_mul_f32_e32 v118, 0x3fb8aa3b, v119
	v_exp_f32_e32 v118, v118
	s_nop 0
	v_sub_f32_e32 v118, 1.0, v118
	s_or_b64 exec, exec, s[0:1]
	v_add_f32_e32 v99, v99, v103
	v_mul_f32_e32 v99, 0xbfb8aa3b, v99
	v_exp_f32_e32 v99, v99
	s_nop 0
	v_add_f32_e32 v99, 1.0, v99
	v_rcp_f32_e32 v99, v99
	s_nop 0
	v_mul_f32_e32 v99, v99, v171
	v_add_f32_e32 v120, v99, v99
	v_cmp_ngt_f32_e32 vcc, s33, v120
	s_and_saveexec_b64 s[0:1], vcc
	s_xor_b64 s[0:1], exec, s[0:1]
	v_fmamk_f32 v119, v120, 0x39500d01, v224
	v_fmaak_f32 v119, v120, v119, 0x3c088889
	v_fmaak_f32 v119, v120, v119, 0x3d2aaaab
	v_fmaak_f32 v119, v120, v119, 0x3e2aaaab
	v_fma_f32 v119, v120, v119, 0.5
	v_fma_f32 v119, v120, v119, 1.0
	v_mul_f32_e64 v119, v119, -v120
	s_andn2_saveexec_b64 s[0:1], s[0:1]
	v_mul_f32_e32 v119, 0x3fb8aa3b, v120
	v_exp_f32_e32 v119, v119
	s_nop 0
	v_sub_f32_e32 v119, 1.0, v119
	s_or_b64 exec, exec, s[0:1]
	v_add_f32_e32 v100, v100, v104
	v_mul_f32_e32 v100, 0xbfb8aa3b, v100
	v_exp_f32_e32 v100, v100
	s_nop 0
	v_add_f32_e32 v100, 1.0, v100
	v_rcp_f32_e32 v100, v100
	s_nop 0
	v_mul_f32_e32 v100, v100, v140
	v_add_f32_e32 v120, v100, v100
	v_cmp_ngt_f32_e32 vcc, s33, v120
	s_and_saveexec_b64 s[0:1], vcc
	s_xor_b64 s[0:1], exec, s[0:1]
	v_fmamk_f32 v121, v120, 0x39500d01, v224
	v_fmaak_f32 v121, v120, v121, 0x3c088889
	v_fmaak_f32 v121, v120, v121, 0x3d2aaaab
	v_fmaak_f32 v121, v120, v121, 0x3e2aaaab
	v_fma_f32 v121, v120, v121, 0.5
	v_fma_f32 v121, v120, v121, 1.0
	v_mul_f32_e64 v121, v121, -v120
	s_andn2_saveexec_b64 s[0:1], s[0:1]
	v_mul_f32_e32 v120, 0x3fb8aa3b, v120
	v_exp_f32_e32 v120, v120
	s_nop 0
	v_sub_f32_e32 v121, 1.0, v120
	s_or_b64 exec, exec, s[0:1]
	v_add_f32_e32 v101, v101, v105
	v_mul_f32_e32 v101, 0xbfb8aa3b, v101
	v_exp_f32_e32 v101, v101
	s_nop 0
	v_add_f32_e32 v101, 1.0, v101
	v_rcp_f32_e32 v101, v101
	s_nop 0
	v_mul_f32_e32 v101, v101, v141
	v_add_f32_e32 v126, v101, v101
	v_cmp_ngt_f32_e32 vcc, s33, v126
	s_and_saveexec_b64 s[0:1], vcc
	s_xor_b64 s[0:1], exec, s[0:1]
	v_fmamk_f32 v120, v126, 0x39500d01, v224
	v_fmaak_f32 v120, v126, v120, 0x3c088889
	v_fmaak_f32 v120, v126, v120, 0x3d2aaaab
	v_fmaak_f32 v120, v126, v120, 0x3e2aaaab
	v_fma_f32 v120, v126, v120, 0.5
	v_fma_f32 v120, v126, v120, 1.0
	v_mul_f32_e64 v120, v120, -v126
	s_andn2_saveexec_b64 s[0:1], s[0:1]
	v_mul_f32_e32 v120, 0x3fb8aa3b, v126
	v_exp_f32_e32 v120, v120
	s_nop 0
	v_sub_f32_e32 v120, 1.0, v120
	s_or_b64 exec, exec, s[0:1]
	v_mul_f32_e32 v126, 0x4f800000, v121
	v_cmp_gt_f32_e32 vcc, s30, v121
	v_add_f32_e32 v96, v96, v92
	v_mul_f32_e32 v96, 0xbfb8aa3b, v96
	v_cndmask_b32_e32 v121, v121, v126, vcc
	v_sqrt_f32_e32 v126, v121
	v_exp_f32_e32 v96, v96
	s_waitcnt vmcnt(19)
; __device__ __forceinline__ unsigned cvt_pk_bf16(float lo, float hi) { unsigned r; asm("v_cvt_pk_bf16_f32 %0, %1, %2" : "=v"(r) : "v"(lo), "v"(hi)); return r; }
; __device__ __forceinline__ float bflo(unsigned w) { return __uint_as_float(w << 16); }
; __device__ __forceinline__ float bfhi(unsigned w) { return __uint_as_float(w & 0xffff0000u); }
; __device__ __forceinline__ float sigmoidf_(float x) { return __builtin_amdgcn_rcpf(1.f + __builtin_amdgcn_exp2f(-1.4426950408889634f * x)); }
;     __device__ __forceinline__ void operator()(AccRef acc, const Unit& u, int wr, int wc, int fr, int fq) const {
;     ...
;             EPI_ROWS_BEGIN
;                 bf16_t* xp = y3 + (size_t)row * 2048 + ch0;
;                 const u32x2 xw = *(const u32x2*)xp;
;                 const f32x4 xc = (f32x4){bflo(xw.x), bfhi(xw.x), bflo(xw.y), bfhi(xw.y)};
;                 f32x4 uo, lo;
; #pragma unroll
;                 for (int e = 0; e < 4; ++e) {
;                     const float rr = acc[ai][0][m][n][e] + ba[e], ii = acc[ai][1][m][n][e] + bi[e];
;                     const float log_a = sp[e] * sigmoidf_(rr);
;                     const float mult = sqrtf(one_minus_exp(2.f * log_a));
;                     uo[e] = xc[e] * sigmoidf_(ii) * mult; lo[e] = log_a;
;                 }
;                 u32x2 w0, w1; w0.x = cvt_pk_bf16(uo[0], uo[1]); w0.y = cvt_pk_bf16(uo[2], uo[3]); w1.x = cvt_pk_bf16(lo[0], lo[1]); w1.y = cvt_pk_bf16(lo[2], lo[3]);
;                 *(u32x2*)xp = w0;
;                 *(u32x2*)(la + (size_t)row * 512 + ch0) = w1;
	v_lshlrev_b32_e32 v127, 16, v193
	v_add_f32_e32 v95, v95, v91
	v_add_u32_e32 v128, -1, v126
	v_fma_f32 v129, -v128, v126, v121
	v_cmp_ge_f32_e64 s[6:7], 0, v129
	v_add_u32_e32 v129, 1, v126
	v_add_f32_e32 v96, 1.0, v96
	v_cndmask_b32_e64 v128, v126, v128, s[6:7]
	v_fma_f32 v126, -v129, v126, v121
	v_cmp_lt_f32_e64 s[6:7], 0, v126
	v_rcp_f32_e32 v96, v96
	v_mul_f32_e32 v95, 0xbfb8aa3b, v95
	v_cndmask_b32_e64 v126, v128, v129, s[6:7]
	v_mul_f32_e32 v128, 0x37800000, v126
	v_cndmask_b32_e32 v126, v126, v128, vcc
	v_cmp_class_f32_e32 vcc, v121, v225
	v_mul_f32_e32 v96, v96, v127
	v_exp_f32_e32 v95, v95
	v_cndmask_b32_e32 v121, v126, v121, vcc
	v_mul_f32_e32 v96, v96, v121
	v_mul_f32_e32 v121, 0x4f800000, v119
	v_cmp_gt_f32_e32 vcc, s30, v119
	v_add_f32_e32 v95, 1.0, v95
	v_rcp_f32_e32 v95, v95
	v_cndmask_b32_e32 v119, v119, v121, vcc
	v_sqrt_f32_e32 v121, v119
	v_and_b32_e32 v126, 0xffff0000, v192
	v_mul_f32_e32 v95, v95, v126
	v_add_f32_e32 v94, v94, v90
	v_add_u32_e32 v127, -1, v121
	v_fma_f32 v128, -v127, v121, v119
	v_cmp_ge_f32_e64 s[6:7], 0, v128
	v_add_u32_e32 v128, 1, v121
	v_mul_f32_e32 v94, 0xbfb8aa3b, v94
	v_cndmask_b32_e64 v127, v121, v127, s[6:7]
	v_fma_f32 v121, -v128, v121, v119
	v_cmp_lt_f32_e64 s[6:7], 0, v121
	v_exp_f32_e32 v94, v94
	v_add_f32_e32 v97, v97, v93
	v_cndmask_b32_e64 v121, v127, v128, s[6:7]
	v_mul_f32_e32 v127, 0x37800000, v121
	v_cndmask_b32_e32 v121, v121, v127, vcc
	v_cmp_class_f32_e32 vcc, v119, v225
	v_add_f32_e32 v94, 1.0, v94
	v_rcp_f32_e32 v94, v94
	v_cndmask_b32_e32 v119, v121, v119, vcc
	v_mul_f32_e32 v121, 0x4f800000, v118
	v_cmp_gt_f32_e32 vcc, s30, v118
	v_mul_f32_e32 v95, v95, v119
	v_mul_f32_e32 v97, 0xbfb8aa3b, v97
	v_cndmask_b32_e32 v118, v118, v121, vcc
	v_sqrt_f32_e32 v121, v118
	v_lshlrev_b32_e32 v112, 16, v192
	v_exp_f32_e32 v97, v97
	v_mul_f32_e32 v94, v94, v112
	v_add_u32_e32 v119, -1, v121
	v_fma_f32 v126, -v119, v121, v118
	v_cmp_ge_f32_e64 s[6:7], 0, v126
	v_add_u32_e32 v126, 1, v121
	v_and_b32_e32 v112, 0xffff0000, v193
	v_cndmask_b32_e64 v119, v121, v119, s[6:7]
	v_fma_f32 v121, -v126, v121, v118
	v_cmp_lt_f32_e64 s[6:7], 0, v121
	v_add_f32_e32 v97, 1.0, v97
	v_rcp_f32_e32 v97, v97
	v_cndmask_b32_e64 v119, v119, v126, s[6:7]
	v_mul_f32_e32 v121, 0x37800000, v119
	v_cndmask_b32_e32 v119, v119, v121, vcc
	v_cmp_class_f32_e32 vcc, v118, v225
	v_mul_f32_e32 v97, v97, v112
	v_cvt_pk_bf16_f32 v98, v98, v99
	v_cvt_pk_bf16_f32 v99, v100, v101
	v_add_f32_e32 v86, v86, v102
	v_cndmask_b32_e32 v118, v119, v118, vcc
	v_mul_f32_e32 v119, 0x4f800000, v120
	v_cmp_gt_f32_e32 vcc, s30, v120
	v_mul_f32_e32 v94, v94, v118
	v_cvt_pk_bf16_f32 v94, v94, v95
	v_mul_f32_e32 v86, 0xbfb8aa3b, v86
	v_cndmask_b32_e32 v119, v120, v119, vcc
	v_sqrt_f32_e32 v120, v119
	v_exp_f32_e32 v86, v86
	v_add_u32_e32 v113, -1, v120
	v_fma_f32 v118, -v113, v120, v119
	v_cmp_ge_f32_e64 s[6:7], 0, v118
	v_add_u32_e32 v118, 1, v120
	v_add_f32_e32 v86, 1.0, v86
	v_cndmask_b32_e64 v113, v120, v113, s[6:7]
	v_fma_f32 v120, -v118, v120, v119
	v_cmp_lt_f32_e64 s[6:7], 0, v120
	v_rcp_f32_e32 v86, v86
	s_nop 0
	v_cndmask_b32_e64 v113, v113, v118, s[6:7]
	v_mul_f32_e32 v118, 0x37800000, v113
	v_cndmask_b32_e32 v113, v113, v118, vcc
	v_cmp_class_f32_e32 vcc, v119, v225
	v_mul_f32_e32 v86, v86, v170
	s_nop 0
	v_cndmask_b32_e32 v113, v113, v119, vcc
	v_mul_f32_e32 v97, v97, v113
	v_cvt_pk_bf16_f32 v95, v96, v97
	global_store_dwordx2 v[106:107], v[94:95], off
	v_lshlrev_b64 v[94:95], 10, v[110:111]
	v_lshl_add_u64 v[94:95], s[12:13], 0, v[94:95]
	v_lshl_add_u64 v[96:97], v[94:95], 0, v[134:135]
	global_store_dwordx2 v[96:97], v[98:99], off
	v_add_u32_e32 v98, 0x90, v162
	v_ashrrev_i32_e32 v99, 31, v98
	v_lshlrev_b64 v[94:95], 12, v[98:99]
	v_lshl_add_u64 v[94:95], s[14:15], 0, v[94:95]
	v_lshl_add_u64 v[94:95], v[94:95], 0, v[134:135]
	s_nop 0
	v_add_f32_e32 v111, v86, v86
	v_cmp_ngt_f32_e32 vcc, s33, v111
	s_and_saveexec_b64 s[0:1], vcc
	s_xor_b64 s[0:1], exec, s[0:1]
	v_fmamk_f32 v110, v111, 0x39500d01, v224
	v_fmaak_f32 v110, v111, v110, 0x3c088889
	v_fmaak_f32 v110, v111, v110, 0x3d2aaaab
	v_fmaak_f32 v110, v111, v110, 0x3e2aaaab
	v_fma_f32 v110, v111, v110, 0.5
	v_fma_f32 v110, v111, v110, 1.0
	v_mul_f32_e64 v110, v110, -v111
	s_andn2_saveexec_b64 s[0:1], s[0:1]
	v_mul_f32_e32 v110, 0x3fb8aa3b, v111
	v_exp_f32_e32 v110, v110
	s_nop 0
	v_sub_f32_e32 v110, 1.0, v110
	s_or_b64 exec, exec, s[0:1]
	v_add_f32_e32 v87, v87, v103
	v_mul_f32_e32 v87, 0xbfb8aa3b, v87
	v_exp_f32_e32 v87, v87
	s_nop 0
	v_add_f32_e32 v87, 1.0, v87
	v_rcp_f32_e32 v87, v87
	s_nop 0
	v_mul_f32_e32 v87, v87, v171
	v_add_f32_e32 v112, v87, v87
	v_cmp_ngt_f32_e32 vcc, s33, v112
	s_and_saveexec_b64 s[0:1], vcc
	s_xor_b64 s[0:1], exec, s[0:1]
	v_fmamk_f32 v111, v112, 0x39500d01, v224
	v_fmaak_f32 v111, v112, v111, 0x3c088889
	v_fmaak_f32 v111, v112, v111, 0x3d2aaaab
	v_fmaak_f32 v111, v112, v111, 0x3e2aaaab
	v_fma_f32 v111, v112, v111, 0.5
	v_fma_f32 v111, v112, v111, 1.0
	v_mul_f32_e64 v111, v111, -v112
	s_andn2_saveexec_b64 s[0:1], s[0:1]
	v_mul_f32_e32 v111, 0x3fb8aa3b, v112
	v_exp_f32_e32 v111, v111
	s_nop 0
	v_sub_f32_e32 v111, 1.0, v111
	s_or_b64 exec, exec, s[0:1]
	v_add_f32_e32 v88, v88, v104
	v_mul_f32_e32 v88, 0xbfb8aa3b, v88
	v_exp_f32_e32 v88, v88
	s_nop 0
	v_add_f32_e32 v88, 1.0, v88
	v_rcp_f32_e32 v88, v88
	s_nop 0
	v_mul_f32_e32 v88, v88, v140
	v_add_f32_e32 v112, v88, v88
	v_cmp_ngt_f32_e32 vcc, s33, v112
	s_and_saveexec_b64 s[0:1], vcc
	s_xor_b64 s[0:1], exec, s[0:1]
	v_fmamk_f32 v113, v112, 0x39500d01, v224
	v_fmaak_f32 v113, v112, v113, 0x3c088889
	v_fmaak_f32 v113, v112, v113, 0x3d2aaaab
	v_fmaak_f32 v113, v112, v113, 0x3e2aaaab
	v_fma_f32 v113, v112, v113, 0.5
	v_fma_f32 v113, v112, v113, 1.0
	v_mul_f32_e64 v113, v113, -v112
	s_andn2_saveexec_b64 s[0:1], s[0:1]
	v_mul_f32_e32 v112, 0x3fb8aa3b, v112
	v_exp_f32_e32 v112, v112
	s_nop 0
	v_sub_f32_e32 v113, 1.0, v112
	s_or_b64 exec, exec, s[0:1]
	v_add_f32_e32 v89, v89, v105
	v_mul_f32_e32 v89, 0xbfb8aa3b, v89
	v_exp_f32_e32 v89, v89
	s_nop 0
	v_add_f32_e32 v89, 1.0, v89
	v_rcp_f32_e32 v89, v89
	s_nop 0
	v_mul_f32_e32 v89, v89, v141
	v_add_f32_e32 v118, v89, v89
	v_cmp_ngt_f32_e32 vcc, s33, v118
	s_and_saveexec_b64 s[0:1], vcc
	s_xor_b64 s[0:1], exec, s[0:1]
	v_fmamk_f32 v112, v118, 0x39500d01, v224
	v_fmaak_f32 v112, v118, v112, 0x3c088889
	v_fmaak_f32 v112, v118, v112, 0x3d2aaaab
	v_fmaak_f32 v112, v118, v112, 0x3e2aaaab
	v_fma_f32 v112, v118, v112, 0.5
	v_fma_f32 v112, v118, v112, 1.0
	v_mul_f32_e64 v112, v112, -v118
	s_andn2_saveexec_b64 s[0:1], s[0:1]
	v_mul_f32_e32 v112, 0x3fb8aa3b, v118
	v_exp_f32_e32 v112, v112
	s_nop 0
	v_sub_f32_e32 v112, 1.0, v112
	s_or_b64 exec, exec, s[0:1]
	v_mul_f32_e32 v118, 0x4f800000, v113
	v_cmp_gt_f32_e32 vcc, s30, v113
	v_add_f32_e32 v84, v84, v92
	v_mul_f32_e32 v84, 0xbfb8aa3b, v84
	v_cndmask_b32_e32 v113, v113, v118, vcc
	v_sqrt_f32_e32 v118, v113
	v_exp_f32_e32 v84, v84
	s_waitcnt vmcnt(20)
; __device__ __forceinline__ unsigned cvt_pk_bf16(float lo, float hi) { unsigned r; asm("v_cvt_pk_bf16_f32 %0, %1, %2" : "=v"(r) : "v"(lo), "v"(hi)); return r; }
; __device__ __forceinline__ float bflo(unsigned w) { return __uint_as_float(w << 16); }
; __device__ __forceinline__ float bfhi(unsigned w) { return __uint_as_float(w & 0xffff0000u); }
; __device__ __forceinline__ float sigmoidf_(float x) { return __builtin_amdgcn_rcpf(1.f + __builtin_amdgcn_exp2f(-1.4426950408889634f * x)); }
;     __device__ __forceinline__ void operator()(AccRef acc, const Unit& u, int wr, int wc, int fr, int fq) const {
;     ...
;             EPI_ROWS_BEGIN
;                 bf16_t* xp = y3 + (size_t)row * 2048 + ch0;
;                 const u32x2 xw = *(const u32x2*)xp;
;                 const f32x4 xc = (f32x4){bflo(xw.x), bfhi(xw.x), bflo(xw.y), bfhi(xw.y)};
;                 f32x4 uo, lo;
; #pragma unroll
;                 for (int e = 0; e < 4; ++e) {
;                     const float rr = acc[ai][0][m][n][e] + ba[e], ii = acc[ai][1][m][n][e] + bi[e];
;                     const float log_a = sp[e] * sigmoidf_(rr);
;                     const float mult = sqrtf(one_minus_exp(2.f * log_a));
;                     uo[e] = xc[e] * sigmoidf_(ii) * mult; lo[e] = log_a;
;                 }
;                 u32x2 w0, w1; w0.x = cvt_pk_bf16(uo[0], uo[1]); w0.y = cvt_pk_bf16(uo[2], uo[3]); w1.x = cvt_pk_bf16(lo[0], lo[1]); w1.y = cvt_pk_bf16(lo[2], lo[3]);
;                 *(u32x2*)xp = w0;
;                 *(u32x2*)(la + (size_t)row * 512 + ch0) = w1;
	v_lshlrev_b32_e32 v119, 16, v207
	v_add_f32_e32 v83, v83, v91
	v_add_u32_e32 v120, -1, v118
	v_fma_f32 v121, -v120, v118, v113
	v_cmp_ge_f32_e64 s[6:7], 0, v121
	v_add_u32_e32 v121, 1, v118
	v_add_f32_e32 v84, 1.0, v84
	v_cndmask_b32_e64 v120, v118, v120, s[6:7]
	v_fma_f32 v118, -v121, v118, v113
	v_cmp_lt_f32_e64 s[6:7], 0, v118
	v_rcp_f32_e32 v84, v84
	v_mul_f32_e32 v83, 0xbfb8aa3b, v83
	v_cndmask_b32_e64 v118, v120, v121, s[6:7]
	v_mul_f32_e32 v120, 0x37800000, v118
	v_cndmask_b32_e32 v118, v118, v120, vcc
	v_cmp_class_f32_e32 vcc, v113, v225
	v_mul_f32_e32 v84, v84, v119
	v_exp_f32_e32 v83, v83
	v_cndmask_b32_e32 v113, v118, v113, vcc
	v_mul_f32_e32 v84, v84, v113
	v_mul_f32_e32 v113, 0x4f800000, v111
	v_cmp_gt_f32_e32 vcc, s30, v111
	v_add_f32_e32 v83, 1.0, v83
	v_rcp_f32_e32 v83, v83
	v_cndmask_b32_e32 v111, v111, v113, vcc
	v_sqrt_f32_e32 v113, v111
	v_and_b32_e32 v118, 0xffff0000, v206
	v_mul_f32_e32 v83, v83, v118
	v_add_f32_e32 v82, v82, v90
	v_add_u32_e32 v119, -1, v113
	v_fma_f32 v120, -v119, v113, v111
	v_cmp_ge_f32_e64 s[6:7], 0, v120
	v_add_u32_e32 v120, 1, v113
	v_mul_f32_e32 v82, 0xbfb8aa3b, v82
	v_cndmask_b32_e64 v119, v113, v119, s[6:7]
	v_fma_f32 v113, -v120, v113, v111
	v_cmp_lt_f32_e64 s[6:7], 0, v113
	v_exp_f32_e32 v82, v82
	v_add_f32_e32 v85, v85, v93
	v_cndmask_b32_e64 v113, v119, v120, s[6:7]
	v_mul_f32_e32 v119, 0x37800000, v113
	v_cndmask_b32_e32 v113, v113, v119, vcc
	v_cmp_class_f32_e32 vcc, v111, v225
	v_add_f32_e32 v82, 1.0, v82
	v_rcp_f32_e32 v82, v82
	v_cndmask_b32_e32 v111, v113, v111, vcc
	v_mul_f32_e32 v113, 0x4f800000, v110
	v_cmp_gt_f32_e32 vcc, s30, v110
	v_mul_f32_e32 v83, v83, v111
	v_mul_f32_e32 v85, 0xbfb8aa3b, v85
	v_cndmask_b32_e32 v110, v110, v113, vcc
	v_sqrt_f32_e32 v113, v110
	v_lshlrev_b32_e32 v100, 16, v206
	v_exp_f32_e32 v85, v85
	v_mul_f32_e32 v82, v82, v100
	v_add_u32_e32 v111, -1, v113
	v_fma_f32 v118, -v111, v113, v110
	v_cmp_ge_f32_e64 s[6:7], 0, v118
	v_add_u32_e32 v118, 1, v113
	v_and_b32_e32 v100, 0xffff0000, v207
	v_cndmask_b32_e64 v111, v113, v111, s[6:7]
	v_fma_f32 v113, -v118, v113, v110
	v_cmp_lt_f32_e64 s[6:7], 0, v113
	v_add_f32_e32 v85, 1.0, v85
	v_rcp_f32_e32 v85, v85
	v_cndmask_b32_e64 v111, v111, v118, s[6:7]
	v_mul_f32_e32 v113, 0x37800000, v111
	v_cndmask_b32_e32 v111, v111, v113, vcc
	v_cmp_class_f32_e32 vcc, v110, v225
	v_mul_f32_e32 v85, v85, v100
	v_cvt_pk_bf16_f32 v86, v86, v87
	v_cvt_pk_bf16_f32 v87, v88, v89
	v_add_f32_e32 v78, v78, v102
	v_cndmask_b32_e32 v110, v111, v110, vcc
	v_mul_f32_e32 v111, 0x4f800000, v112
	v_cmp_gt_f32_e32 vcc, s30, v112
	v_mul_f32_e32 v82, v82, v110
	v_cvt_pk_bf16_f32 v82, v82, v83
	v_mul_f32_e32 v78, 0xbfb8aa3b, v78
	v_cndmask_b32_e32 v111, v112, v111, vcc
	v_sqrt_f32_e32 v112, v111
	v_exp_f32_e32 v78, v78
	v_add_u32_e32 v101, -1, v112
	v_fma_f32 v110, -v101, v112, v111
	v_cmp_ge_f32_e64 s[6:7], 0, v110
	v_add_u32_e32 v110, 1, v112
	v_add_f32_e32 v78, 1.0, v78
	v_cndmask_b32_e64 v101, v112, v101, s[6:7]
	v_fma_f32 v112, -v110, v112, v111
	v_cmp_lt_f32_e64 s[6:7], 0, v112
	v_rcp_f32_e32 v78, v78
	s_nop 0
	v_cndmask_b32_e64 v101, v101, v110, s[6:7]
	v_mul_f32_e32 v110, 0x37800000, v101
	v_cndmask_b32_e32 v101, v101, v110, vcc
	v_cmp_class_f32_e32 vcc, v111, v225
	v_mul_f32_e32 v78, v78, v170
	s_nop 0
	v_cndmask_b32_e32 v101, v101, v111, vcc
	v_mul_f32_e32 v85, v85, v101
	v_cvt_pk_bf16_f32 v83, v84, v85
	global_store_dwordx2 v[94:95], v[82:83], off
	v_lshlrev_b64 v[82:83], 10, v[98:99]
	v_lshl_add_u64 v[82:83], s[12:13], 0, v[82:83]
	v_lshl_add_u64 v[84:85], v[82:83], 0, v[134:135]
	global_store_dwordx2 v[84:85], v[86:87], off
	v_add_u32_e32 v86, 0xa0, v162
	v_ashrrev_i32_e32 v87, 31, v86
	v_lshlrev_b64 v[82:83], 12, v[86:87]
	v_lshl_add_u64 v[82:83], s[14:15], 0, v[82:83]
	v_lshl_add_u64 v[82:83], v[82:83], 0, v[134:135]
	s_nop 0
	v_add_f32_e32 v99, v78, v78
	v_cmp_ngt_f32_e32 vcc, s33, v99
	s_and_saveexec_b64 s[0:1], vcc
	s_xor_b64 s[0:1], exec, s[0:1]
	v_fmamk_f32 v98, v99, 0x39500d01, v224
	v_fmaak_f32 v98, v99, v98, 0x3c088889
	v_fmaak_f32 v98, v99, v98, 0x3d2aaaab
	v_fmaak_f32 v98, v99, v98, 0x3e2aaaab
	v_fma_f32 v98, v99, v98, 0.5
	v_fma_f32 v98, v99, v98, 1.0
	v_mul_f32_e64 v98, v98, -v99
	s_andn2_saveexec_b64 s[0:1], s[0:1]
	v_mul_f32_e32 v98, 0x3fb8aa3b, v99
	v_exp_f32_e32 v98, v98
	s_nop 0
	v_sub_f32_e32 v98, 1.0, v98
	s_or_b64 exec, exec, s[0:1]
	v_add_f32_e32 v79, v79, v103
	v_mul_f32_e32 v79, 0xbfb8aa3b, v79
	v_exp_f32_e32 v79, v79
	s_nop 0
	v_add_f32_e32 v79, 1.0, v79
	v_rcp_f32_e32 v79, v79
	s_nop 0
	v_mul_f32_e32 v79, v79, v171
	v_add_f32_e32 v100, v79, v79
	v_cmp_ngt_f32_e32 vcc, s33, v100
	s_and_saveexec_b64 s[0:1], vcc
	s_xor_b64 s[0:1], exec, s[0:1]
	v_fmamk_f32 v99, v100, 0x39500d01, v224
	v_fmaak_f32 v99, v100, v99, 0x3c088889
	v_fmaak_f32 v99, v100, v99, 0x3d2aaaab
	v_fmaak_f32 v99, v100, v99, 0x3e2aaaab
	v_fma_f32 v99, v100, v99, 0.5
	v_fma_f32 v99, v100, v99, 1.0
	v_mul_f32_e64 v99, v99, -v100
	s_andn2_saveexec_b64 s[0:1], s[0:1]
	v_mul_f32_e32 v99, 0x3fb8aa3b, v100
	v_exp_f32_e32 v99, v99
	s_nop 0
	v_sub_f32_e32 v99, 1.0, v99
	s_or_b64 exec, exec, s[0:1]
	v_add_f32_e32 v80, v80, v104
	v_mul_f32_e32 v80, 0xbfb8aa3b, v80
	v_exp_f32_e32 v80, v80
	s_nop 0
	v_add_f32_e32 v80, 1.0, v80
	v_rcp_f32_e32 v80, v80
	s_nop 0
	v_mul_f32_e32 v80, v80, v140
	v_add_f32_e32 v100, v80, v80
	v_cmp_ngt_f32_e32 vcc, s33, v100
	s_and_saveexec_b64 s[0:1], vcc
	s_xor_b64 s[0:1], exec, s[0:1]
	v_fmamk_f32 v101, v100, 0x39500d01, v224
	v_fmaak_f32 v101, v100, v101, 0x3c088889
	v_fmaak_f32 v101, v100, v101, 0x3d2aaaab
	v_fmaak_f32 v101, v100, v101, 0x3e2aaaab
	v_fma_f32 v101, v100, v101, 0.5
	v_fma_f32 v101, v100, v101, 1.0
	v_mul_f32_e64 v101, v101, -v100
	s_andn2_saveexec_b64 s[0:1], s[0:1]
	v_mul_f32_e32 v100, 0x3fb8aa3b, v100
	v_exp_f32_e32 v100, v100
	s_nop 0
	v_sub_f32_e32 v101, 1.0, v100
	s_or_b64 exec, exec, s[0:1]
	v_add_f32_e32 v81, v81, v105
	v_mul_f32_e32 v81, 0xbfb8aa3b, v81
	v_exp_f32_e32 v81, v81
	s_nop 0
	v_add_f32_e32 v81, 1.0, v81
	v_rcp_f32_e32 v81, v81
	s_nop 0
	v_mul_f32_e32 v81, v81, v141
	v_add_f32_e32 v110, v81, v81
	v_cmp_ngt_f32_e32 vcc, s33, v110
	s_and_saveexec_b64 s[0:1], vcc
	s_xor_b64 s[0:1], exec, s[0:1]
	v_fmamk_f32 v100, v110, 0x39500d01, v224
	v_fmaak_f32 v100, v110, v100, 0x3c088889
	v_fmaak_f32 v100, v110, v100, 0x3d2aaaab
	v_fmaak_f32 v100, v110, v100, 0x3e2aaaab
	v_fma_f32 v100, v110, v100, 0.5
	v_fma_f32 v100, v110, v100, 1.0
	v_mul_f32_e64 v100, v100, -v110
	s_andn2_saveexec_b64 s[0:1], s[0:1]
	v_mul_f32_e32 v100, 0x3fb8aa3b, v110
	v_exp_f32_e32 v100, v100
	s_nop 0
	v_sub_f32_e32 v100, 1.0, v100
	s_or_b64 exec, exec, s[0:1]
	v_mul_f32_e32 v110, 0x4f800000, v101
	v_cmp_gt_f32_e32 vcc, s30, v101
	v_add_f32_e32 v76, v76, v92
	v_mul_f32_e32 v76, 0xbfb8aa3b, v76
	v_cndmask_b32_e32 v101, v101, v110, vcc
	v_sqrt_f32_e32 v110, v101
	v_exp_f32_e32 v76, v76
	s_waitcnt vmcnt(21)
; __device__ __forceinline__ unsigned cvt_pk_bf16(float lo, float hi) { unsigned r; asm("v_cvt_pk_bf16_f32 %0, %1, %2" : "=v"(r) : "v"(lo), "v"(hi)); return r; }
; __device__ __forceinline__ float bflo(unsigned w) { return __uint_as_float(w << 16); }
; __device__ __forceinline__ float bfhi(unsigned w) { return __uint_as_float(w & 0xffff0000u); }
; __device__ __forceinline__ float sigmoidf_(float x) { return __builtin_amdgcn_rcpf(1.f + __builtin_amdgcn_exp2f(-1.4426950408889634f * x)); }
;     __device__ __forceinline__ void operator()(AccRef acc, const Unit& u, int wr, int wc, int fr, int fq) const {
;     ...
;             EPI_ROWS_BEGIN
;                 bf16_t* xp = y3 + (size_t)row * 2048 + ch0;
;                 const u32x2 xw = *(const u32x2*)xp;
;                 const f32x4 xc = (f32x4){bflo(xw.x), bfhi(xw.x), bflo(xw.y), bfhi(xw.y)};
;                 f32x4 uo, lo;
; #pragma unroll
;                 for (int e = 0; e < 4; ++e) {
;                     const float rr = acc[ai][0][m][n][e] + ba[e], ii = acc[ai][1][m][n][e] + bi[e];
;                     const float log_a = sp[e] * sigmoidf_(rr);
;                     const float mult = sqrtf(one_minus_exp(2.f * log_a));
;                     uo[e] = xc[e] * sigmoidf_(ii) * mult; lo[e] = log_a;
;                 }
;                 u32x2 w0, w1; w0.x = cvt_pk_bf16(uo[0], uo[1]); w0.y = cvt_pk_bf16(uo[2], uo[3]); w1.x = cvt_pk_bf16(lo[0], lo[1]); w1.y = cvt_pk_bf16(lo[2], lo[3]);
;                 *(u32x2*)xp = w0;
;                 *(u32x2*)(la + (size_t)row * 512 + ch0) = w1;
	v_lshlrev_b32_e32 v111, 16, v209
	v_add_f32_e32 v75, v75, v91
	v_add_u32_e32 v112, -1, v110
	v_fma_f32 v113, -v112, v110, v101
	v_cmp_ge_f32_e64 s[6:7], 0, v113
	v_add_u32_e32 v113, 1, v110
	v_add_f32_e32 v76, 1.0, v76
	v_cndmask_b32_e64 v112, v110, v112, s[6:7]
	v_fma_f32 v110, -v113, v110, v101
	v_cmp_lt_f32_e64 s[6:7], 0, v110
	v_rcp_f32_e32 v76, v76
	v_mul_f32_e32 v75, 0xbfb8aa3b, v75
	v_cndmask_b32_e64 v110, v112, v113, s[6:7]
	v_mul_f32_e32 v112, 0x37800000, v110
	v_cndmask_b32_e32 v110, v110, v112, vcc
	v_cmp_class_f32_e32 vcc, v101, v225
	v_mul_f32_e32 v76, v76, v111
	v_exp_f32_e32 v75, v75
	v_cndmask_b32_e32 v101, v110, v101, vcc
	v_mul_f32_e32 v76, v76, v101
	v_mul_f32_e32 v101, 0x4f800000, v99
	v_cmp_gt_f32_e32 vcc, s30, v99
	v_add_f32_e32 v75, 1.0, v75
	v_rcp_f32_e32 v75, v75
	v_cndmask_b32_e32 v99, v99, v101, vcc
	v_sqrt_f32_e32 v101, v99
	v_and_b32_e32 v110, 0xffff0000, v208
	v_mul_f32_e32 v75, v75, v110
	v_add_f32_e32 v74, v74, v90
	v_add_u32_e32 v111, -1, v101
	v_fma_f32 v112, -v111, v101, v99
	v_cmp_ge_f32_e64 s[6:7], 0, v112
	v_add_u32_e32 v112, 1, v101
	v_mul_f32_e32 v74, 0xbfb8aa3b, v74
	v_cndmask_b32_e64 v111, v101, v111, s[6:7]
	v_fma_f32 v101, -v112, v101, v99
	v_cmp_lt_f32_e64 s[6:7], 0, v101
	v_exp_f32_e32 v74, v74
	v_add_f32_e32 v77, v77, v93
	v_cndmask_b32_e64 v101, v111, v112, s[6:7]
	v_mul_f32_e32 v111, 0x37800000, v101
	v_cndmask_b32_e32 v101, v101, v111, vcc
	v_cmp_class_f32_e32 vcc, v99, v225
	v_add_f32_e32 v74, 1.0, v74
	v_rcp_f32_e32 v74, v74
	v_cndmask_b32_e32 v99, v101, v99, vcc
	v_mul_f32_e32 v101, 0x4f800000, v98
	v_cmp_gt_f32_e32 vcc, s30, v98
	v_mul_f32_e32 v75, v75, v99
	v_mul_f32_e32 v77, 0xbfb8aa3b, v77
	v_cndmask_b32_e32 v98, v98, v101, vcc
	v_sqrt_f32_e32 v101, v98
	v_lshlrev_b32_e32 v88, 16, v208
	v_exp_f32_e32 v77, v77
	v_mul_f32_e32 v74, v74, v88
	v_add_u32_e32 v99, -1, v101
	v_fma_f32 v110, -v99, v101, v98
	v_cmp_ge_f32_e64 s[6:7], 0, v110
	v_add_u32_e32 v110, 1, v101
	v_and_b32_e32 v88, 0xffff0000, v209
	v_cndmask_b32_e64 v99, v101, v99, s[6:7]
	v_fma_f32 v101, -v110, v101, v98
	v_cmp_lt_f32_e64 s[6:7], 0, v101
	v_add_f32_e32 v77, 1.0, v77
	v_rcp_f32_e32 v77, v77
	v_cndmask_b32_e64 v99, v99, v110, s[6:7]
	v_mul_f32_e32 v101, 0x37800000, v99
	v_cndmask_b32_e32 v99, v99, v101, vcc
	v_cmp_class_f32_e32 vcc, v98, v225
	v_mul_f32_e32 v77, v77, v88
	v_add_f32_e32 v70, v70, v102
	v_cndmask_b32_e32 v98, v99, v98, vcc
	v_mul_f32_e32 v99, 0x4f800000, v100
	v_cmp_gt_f32_e32 vcc, s30, v100
	v_mul_f32_e32 v74, v74, v98
	v_cvt_pk_bf16_f32 v74, v74, v75
	v_mul_f32_e32 v70, 0xbfb8aa3b, v70
	v_cndmask_b32_e32 v99, v100, v99, vcc
	v_sqrt_f32_e32 v100, v99
	v_exp_f32_e32 v70, v70
	v_add_u32_e32 v89, -1, v100
	v_fma_f32 v98, -v89, v100, v99
	v_cmp_ge_f32_e64 s[6:7], 0, v98
	v_add_u32_e32 v98, 1, v100
	v_add_f32_e32 v70, 1.0, v70
	v_cndmask_b32_e64 v89, v100, v89, s[6:7]
	v_fma_f32 v100, -v98, v100, v99
	v_cmp_lt_f32_e64 s[6:7], 0, v100
	v_rcp_f32_e32 v70, v70
	s_nop 0
	v_cndmask_b32_e64 v89, v89, v98, s[6:7]
	v_mul_f32_e32 v98, 0x37800000, v89
	v_cndmask_b32_e32 v89, v89, v98, vcc
	v_cmp_class_f32_e32 vcc, v99, v225
	v_mul_f32_e32 v70, v70, v170
	s_nop 0
	v_cndmask_b32_e32 v89, v89, v99, vcc
	v_mul_f32_e32 v77, v77, v89
	v_cvt_pk_bf16_f32 v75, v76, v77
	global_store_dwordx2 v[82:83], v[74:75], off
	v_lshlrev_b64 v[74:75], 10, v[86:87]
	v_lshl_add_u64 v[74:75], s[12:13], 0, v[74:75]
	v_cvt_pk_bf16_f32 v77, v80, v81
	v_lshl_add_u64 v[80:81], v[74:75], 0, v[134:135]
	v_add_u32_e32 v74, 0xb0, v162
	v_cvt_pk_bf16_f32 v76, v78, v79
	v_ashrrev_i32_e32 v75, 31, v74
	global_store_dwordx2 v[80:81], v[76:77], off
	v_lshlrev_b64 v[76:77], 12, v[74:75]
	v_lshl_add_u64 v[76:77], s[14:15], 0, v[76:77]
	v_lshl_add_u64 v[78:79], v[76:77], 0, v[134:135]
	s_nop 0
	v_add_f32_e32 v87, v70, v70
	v_cmp_ngt_f32_e32 vcc, s33, v87
	s_and_saveexec_b64 s[0:1], vcc
	s_xor_b64 s[0:1], exec, s[0:1]
	v_fmamk_f32 v86, v87, 0x39500d01, v224
	v_fmaak_f32 v86, v87, v86, 0x3c088889
	v_fmaak_f32 v86, v87, v86, 0x3d2aaaab
	v_fmaak_f32 v86, v87, v86, 0x3e2aaaab
	v_fma_f32 v86, v87, v86, 0.5
	v_fma_f32 v86, v87, v86, 1.0
	v_mul_f32_e64 v86, v86, -v87
	s_andn2_saveexec_b64 s[0:1], s[0:1]
	v_mul_f32_e32 v86, 0x3fb8aa3b, v87
	v_exp_f32_e32 v86, v86
	s_nop 0
	v_sub_f32_e32 v86, 1.0, v86
	s_or_b64 exec, exec, s[0:1]
	v_add_f32_e32 v71, v71, v103
	v_mul_f32_e32 v71, 0xbfb8aa3b, v71
	v_exp_f32_e32 v71, v71
	s_nop 0
	v_add_f32_e32 v71, 1.0, v71
	v_rcp_f32_e32 v71, v71
	s_nop 0
	v_mul_f32_e32 v71, v71, v171
	v_add_f32_e32 v87, v71, v71
	v_cmp_ngt_f32_e32 vcc, s33, v87
	s_and_saveexec_b64 s[0:1], vcc
	s_xor_b64 s[0:1], exec, s[0:1]
	v_fmamk_f32 v88, v87, 0x39500d01, v224
	v_fmaak_f32 v88, v87, v88, 0x3c088889
	v_fmaak_f32 v88, v87, v88, 0x3d2aaaab
	v_fmaak_f32 v88, v87, v88, 0x3e2aaaab
	v_fma_f32 v88, v87, v88, 0.5
	v_fma_f32 v88, v87, v88, 1.0
	v_mul_f32_e64 v88, v88, -v87
	s_andn2_saveexec_b64 s[0:1], s[0:1]
	v_mul_f32_e32 v87, 0x3fb8aa3b, v87
	v_exp_f32_e32 v87, v87
	s_nop 0
	v_sub_f32_e32 v88, 1.0, v87
	s_or_b64 exec, exec, s[0:1]
	v_add_f32_e32 v72, v72, v104
	v_mul_f32_e32 v72, 0xbfb8aa3b, v72
	v_exp_f32_e32 v72, v72
	s_nop 0
	v_add_f32_e32 v72, 1.0, v72
	v_rcp_f32_e32 v72, v72
	s_nop 0
	v_mul_f32_e32 v72, v72, v140
	v_add_f32_e32 v87, v72, v72
	v_cmp_ngt_f32_e32 vcc, s33, v87
	s_and_saveexec_b64 s[0:1], vcc
	s_xor_b64 s[0:1], exec, s[0:1]
	v_fmamk_f32 v89, v87, 0x39500d01, v224
	v_fmaak_f32 v89, v87, v89, 0x3c088889
	v_fmaak_f32 v89, v87, v89, 0x3d2aaaab
	v_fmaak_f32 v89, v87, v89, 0x3e2aaaab
	v_fma_f32 v89, v87, v89, 0.5
	v_fma_f32 v89, v87, v89, 1.0
	v_mul_f32_e64 v89, v89, -v87
	s_andn2_saveexec_b64 s[0:1], s[0:1]
	v_mul_f32_e32 v87, 0x3fb8aa3b, v87
; __device__ __forceinline__ unsigned cvt_pk_bf16(float lo, float hi) { unsigned r; asm("v_cvt_pk_bf16_f32 %0, %1, %2" : "=v"(r) : "v"(lo), "v"(hi)); return r; }
; __device__ __forceinline__ float bflo(unsigned w) { return __uint_as_float(w << 16); }
; __device__ __forceinline__ float bfhi(unsigned w) { return __uint_as_float(w & 0xffff0000u); }
; __device__ __forceinline__ float sigmoidf_(float x) { return __builtin_amdgcn_rcpf(1.f + __builtin_amdgcn_exp2f(-1.4426950408889634f * x)); }
; #define EPI_ROWS_END if (m & 1) asm volatile("" ::: "memory"); }
;     __device__ __forceinline__ void operator()(AccRef acc, const Unit& u, int wr, int wc, int fr, int fq) const {
;     ...
;             const f32x4 ba = *(const f32x4*)(b_a + ch0), bi = *(const f32x4*)(b_i + ch0), lm = *(const f32x4*)(lam + ch0);
;     ...
;             EPI_ROWS_BEGIN
;                 bf16_t* xp = y3 + (size_t)row * 2048 + ch0;
;                 const u32x2 xw = *(const u32x2*)xp;
;                 const f32x4 xc = (f32x4){bflo(xw.x), bfhi(xw.x), bflo(xw.y), bfhi(xw.y)};
;                 f32x4 uo, lo;
; #pragma unroll
;                 for (int e = 0; e < 4; ++e) {
;                     const float rr = acc[ai][0][m][n][e] + ba[e], ii = acc[ai][1][m][n][e] + bi[e];
;                     const float log_a = sp[e] * sigmoidf_(rr);
;                     const float mult = sqrtf(one_minus_exp(2.f * log_a));
;                     uo[e] = xc[e] * sigmoidf_(ii) * mult; lo[e] = log_a;
;                 }
;                 u32x2 w0, w1; w0.x = cvt_pk_bf16(uo[0], uo[1]); w0.y = cvt_pk_bf16(uo[2], uo[3]); w1.x = cvt_pk_bf16(lo[0], lo[1]); w1.y = cvt_pk_bf16(lo[2], lo[3]);
;                 *(u32x2*)xp = w0;
;                 *(u32x2*)(la + (size_t)row * 512 + ch0) = w1;
;                 asm volatile("" ::: "memory");
;             EPI_ROWS_END
	v_exp_f32_e32 v87, v87
	s_nop 0
	v_sub_f32_e32 v89, 1.0, v87
	s_or_b64 exec, exec, s[0:1]
	v_add_f32_e32 v73, v73, v105
	v_mul_f32_e32 v73, 0xbfb8aa3b, v73
	v_exp_f32_e32 v73, v73
	s_nop 0
	v_add_f32_e32 v73, 1.0, v73
	v_rcp_f32_e32 v73, v73
	s_nop 0
	v_mul_f32_e32 v73, v73, v141
	v_add_f32_e32 v98, v73, v73
	v_cmp_ngt_f32_e32 vcc, s33, v98
	s_and_saveexec_b64 s[0:1], vcc
	s_xor_b64 s[0:1], exec, s[0:1]
	v_fmamk_f32 v87, v98, 0x39500d01, v224
	v_fmaak_f32 v87, v98, v87, 0x3c088889
	v_fmaak_f32 v87, v98, v87, 0x3d2aaaab
	v_fmaak_f32 v87, v98, v87, 0x3e2aaaab
	v_fma_f32 v87, v98, v87, 0.5
	v_fma_f32 v87, v98, v87, 1.0
	v_mul_f32_e64 v87, v87, -v98
	s_andn2_saveexec_b64 s[0:1], s[0:1]
	v_mul_f32_e32 v87, 0x3fb8aa3b, v98
	v_exp_f32_e32 v87, v87
	s_nop 0
	v_sub_f32_e32 v87, 1.0, v87
	s_or_b64 exec, exec, s[0:1]
	v_cmp_gt_f32_e32 vcc, s30, v89
	v_mul_f32_e32 v98, 0x4f800000, v89
	v_add_f32_e32 v68, v68, v92
	v_cndmask_b32_e32 v89, v89, v98, vcc
	v_sqrt_f32_e32 v98, v89
	v_mul_f32_e32 v68, 0xbfb8aa3b, v68
	v_exp_f32_e32 v68, v68
	v_add_f32_e32 v67, v67, v91
	v_add_u32_e32 v99, -1, v98
	v_fma_f32 v100, -v99, v98, v89
	v_cmp_ge_f32_e64 s[6:7], 0, v100
	v_add_u32_e32 v100, 1, v98
	v_mul_f32_e32 v91, 0x4f800000, v88
	v_cndmask_b32_e64 v99, v98, v99, s[6:7]
	v_fma_f32 v98, -v100, v98, v89
	v_cmp_lt_f32_e64 s[6:7], 0, v98
	v_add_f32_e32 v68, 1.0, v68
	v_rcp_f32_e32 v68, v68
	v_cndmask_b32_e64 v98, v99, v100, s[6:7]
	v_mul_f32_e32 v99, 0x37800000, v98
	v_cndmask_b32_e32 v98, v98, v99, vcc
	v_cmp_class_f32_e32 vcc, v89, v225
	v_mul_f32_e32 v67, 0xbfb8aa3b, v67
	s_waitcnt vmcnt(22)
	v_lshlrev_b32_e32 v92, 16, v211
	v_cndmask_b32_e32 v89, v98, v89, vcc
	v_cmp_gt_f32_e32 vcc, s30, v88
	v_exp_f32_e32 v67, v67
	v_mul_f32_e32 v68, v68, v92
	v_cndmask_b32_e32 v88, v88, v91, vcc
	v_sqrt_f32_e32 v91, v88
	v_add_f32_e32 v69, v69, v93
	v_add_f32_e32 v67, 1.0, v67
	v_rcp_f32_e32 v67, v67
	v_add_u32_e32 v92, -1, v91
	v_fma_f32 v93, -v92, v91, v88
	v_cmp_ge_f32_e64 s[6:7], 0, v93
	v_add_u32_e32 v93, 1, v91
	v_mul_f32_e32 v68, v68, v89
	v_cndmask_b32_e64 v92, v91, v92, s[6:7]
	v_fma_f32 v91, -v93, v91, v88
	v_cmp_lt_f32_e64 s[6:7], 0, v91
	v_and_b32_e32 v89, 0xffff0000, v210
	v_mul_f32_e32 v67, v67, v89
	v_cndmask_b32_e64 v91, v92, v93, s[6:7]
	v_mul_f32_e32 v92, 0x37800000, v91
	v_cndmask_b32_e32 v91, v91, v92, vcc
	v_cmp_class_f32_e32 vcc, v88, v225
	v_add_f32_e32 v66, v66, v90
	v_mul_f32_e32 v66, 0xbfb8aa3b, v66
	v_cndmask_b32_e32 v88, v91, v88, vcc
	v_mul_f32_e32 v67, v67, v88
	v_cmp_gt_f32_e32 vcc, s30, v86
	v_mul_f32_e32 v88, 0x4f800000, v86
	v_exp_f32_e32 v66, v66
	v_cndmask_b32_e32 v86, v86, v88, vcc
	v_sqrt_f32_e32 v88, v86
	v_lshlrev_b32_e32 v76, 16, v210
	v_add_f32_e32 v66, 1.0, v66
	v_rcp_f32_e32 v66, v66
	v_add_u32_e32 v89, -1, v88
	v_fma_f32 v90, -v89, v88, v86
	v_cmp_ge_f32_e64 s[6:7], 0, v90
	v_add_u32_e32 v90, 1, v88
	v_mul_f32_e32 v66, v66, v76
	v_cndmask_b32_e64 v89, v88, v89, s[6:7]
	v_fma_f32 v88, -v90, v88, v86
	v_cmp_lt_f32_e64 s[6:7], 0, v88
	v_and_b32_e32 v76, 0xffff0000, v211
	v_mul_f32_e32 v77, 0x4f800000, v87
	v_cndmask_b32_e64 v88, v89, v90, s[6:7]
	v_mul_f32_e32 v89, 0x37800000, v88
	v_cndmask_b32_e32 v88, v88, v89, vcc
	v_cmp_class_f32_e32 vcc, v86, v225
	v_mul_f32_e32 v69, 0xbfb8aa3b, v69
	v_exp_f32_e32 v69, v69
	v_cndmask_b32_e32 v86, v88, v86, vcc
	v_cmp_gt_f32_e32 vcc, s30, v87
	v_mul_f32_e32 v66, v66, v86
	v_add_f32_e32 v69, 1.0, v69
	v_cndmask_b32_e32 v77, v87, v77, vcc
	v_sqrt_f32_e32 v86, v77
	v_rcp_f32_e32 v69, v69
	v_cvt_pk_bf16_f32 v66, v66, v67
	v_add_u32_e32 v87, -1, v86
	v_fma_f32 v88, -v87, v86, v77
	v_cmp_ge_f32_e64 s[6:7], 0, v88
	v_add_u32_e32 v88, 1, v86
	v_mul_f32_e32 v69, v69, v76
	v_cndmask_b32_e64 v87, v86, v87, s[6:7]
	v_fma_f32 v86, -v88, v86, v77
	v_cmp_lt_f32_e64 s[6:7], 0, v86
	s_nop 1
	v_cndmask_b32_e64 v86, v87, v88, s[6:7]
	v_mul_f32_e32 v87, 0x37800000, v86
	v_cndmask_b32_e32 v86, v86, v87, vcc
	v_cmp_class_f32_e32 vcc, v77, v225
	s_nop 1
	v_cndmask_b32_e32 v77, v86, v77, vcc
	v_mul_f32_e32 v69, v69, v77
	v_cvt_pk_bf16_f32 v67, v68, v69
	global_store_dwordx2 v[78:79], v[66:67], off
	v_lshlrev_b64 v[66:67], 10, v[74:75]
	v_lshl_add_u64 v[66:67], s[12:13], 0, v[66:67]
	v_lshl_add_u64 v[86:87], v[154:155], 1, v[66:67]
	v_cvt_pk_bf16_f32 v68, v70, v71
	v_cvt_pk_bf16_f32 v69, v72, v73
	global_store_dwordx2 v[86:87], v[68:69], off
	global_load_dwordx4 v[70:73], v[156:157], off offset:16
	global_load_dwordx4 v[66:69], v[158:159], off offset:16
	global_load_dwordx4 v[74:77], v[160:161], off offset:16
	s_waitcnt vmcnt(0)
; __device__ __forceinline__ float bflo(unsigned w) { return __uint_as_float(w << 16); }
; __device__ __forceinline__ float bfhi(unsigned w) { return __uint_as_float(w & 0xffff0000u); }
; __device__ __forceinline__ float sigmoidf_(float x) { return __builtin_amdgcn_rcpf(1.f + __builtin_amdgcn_exp2f(-1.4426950408889634f * x)); }
;     __device__ __forceinline__ void operator()(AccRef acc, const Unit& u, int wr, int wc, int fr, int fq) const {
;     ...
;         for (int n = 0; n < 2; ++n) {
;             const int ch0 = u.pn * 128 + wc * 32 + 8 * fq + 4 * n;
;             const f32x4 ba = *(const f32x4*)(b_a + ch0), bi = *(const f32x4*)(b_i + ch0), lm = *(const f32x4*)(lam + ch0);
;             f32x4 sp;
; #pragma unroll
;             for (int e = 0; e < 4; ++e) sp[e] = -8.f * log1pf(__expf(-lm[e]));
;             EPI_ROWS_BEGIN
;                 bf16_t* xp = y3 + (size_t)row * 2048 + ch0;
;                 const u32x2 xw = *(const u32x2*)xp;
;                 const f32x4 xc = (f32x4){bflo(xw.x), bfhi(xw.x), bflo(xw.y), bfhi(xw.y)};
;                 f32x4 uo, lo;
; #pragma unroll
;                 for (int e = 0; e < 4; ++e) {
;                     const float rr = acc[ai][0][m][n][e] + ba[e], ii = acc[ai][1][m][n][e] + bi[e];
;                     const float log_a = sp[e] * sigmoidf_(rr);
;                     const float mult = sqrtf(one_minus_exp(2.f * log_a));
	v_add_f32_e32 v62, v62, v70
	v_mul_f32_e32 v62, 0xbfb8aa3b, v62
	v_mul_f32_e32 v74, 0xbfb8aa3b, v74
	v_exp_f32_e32 v74, v74
	v_exp_f32_e32 v62, v62
	v_add_f32_e32 v90, 1.0, v74
	v_add_f32_e32 v88, -1.0, v90
	v_sub_f32_e32 v89, v88, v90
	v_add_f32_e32 v89, 1.0, v89
	v_sub_f32_e32 v88, v74, v88
	v_add_f32_e32 v91, v88, v89
	v_frexp_mant_f32_e32 v88, v90
	v_cmp_gt_f32_e32 vcc, s31, v88
	v_cvt_f64_f32_e32 v[88:89], v90
	v_frexp_exp_i32_f64_e32 v88, v[88:89]
	v_subbrev_co_u32_e32 v100, vcc, 0, v88, vcc
	v_sub_u32_e32 v88, 0, v100
	v_ldexp_f32 v89, v90, v88
	v_add_f32_e32 v90, -1.0, v89
	v_add_f32_e32 v92, 1.0, v89
	v_ldexp_f32 v88, v91, v88
	v_add_f32_e32 v91, 1.0, v90
	v_add_f32_e32 v93, -1.0, v92
	v_sub_f32_e32 v91, v89, v91
	v_sub_f32_e32 v89, v89, v93
	v_add_f32_e32 v91, v88, v91
	v_add_f32_e32 v88, v88, v89
	v_add_f32_e32 v101, v92, v88
	v_rcp_f32_e32 v103, v101
	v_sub_f32_e32 v89, v101, v92
	v_sub_f32_e32 v102, v88, v89
	v_add_f32_e32 v89, v90, v91
	v_mul_f32_e32 v105, v89, v103
	v_sub_f32_e32 v88, v89, v90
	v_mul_f32_e32 v90, v101, v105
	v_fma_f32 v92, v105, v101, -v90
	v_fmac_f32_e32 v92, v105, v102
	v_sub_f32_e32 v104, v91, v88
	v_add_f32_e32 v88, v90, v92
	v_sub_f32_e32 v91, v89, v88
	v_pk_add_f32 v[98:99], v[88:89], v[90:91] neg_lo:[0,1] neg_hi:[0,1]
	v_mov_b32_e32 v93, v88
	v_pk_add_f32 v[88:89], v[98:99], v[92:93] neg_lo:[0,1] neg_hi:[0,1]
	v_cmp_neq_f32_e32 vcc, s39, v74
	v_add_f32_e32 v89, v104, v89
	v_add_f32_e32 v88, v88, v89
	v_add_f32_e32 v89, v91, v88
	v_mul_f32_e32 v104, v103, v89
	v_mul_f32_e32 v90, v101, v104
	v_fma_f32 v92, v104, v101, -v90
	v_fmac_f32_e32 v92, v104, v102
	v_sub_f32_e32 v91, v91, v89
	v_add_f32_e32 v101, v88, v91
	v_add_f32_e32 v88, v90, v92
	v_sub_f32_e32 v91, v89, v88
	v_pk_add_f32 v[98:99], v[88:89], v[90:91] neg_lo:[0,1] neg_hi:[0,1]
	v_mov_b32_e32 v93, v88
	v_pk_add_f32 v[88:89], v[98:99], v[92:93] neg_lo:[0,1] neg_hi:[0,1]
	v_add_f32_e32 v62, 1.0, v62
	v_add_f32_e32 v89, v101, v89
	v_add_f32_e32 v88, v88, v89
	v_add_f32_e32 v89, v105, v104
	v_add_f32_e32 v88, v91, v88
	v_sub_f32_e32 v90, v89, v105
	v_mul_f32_e32 v88, v103, v88
	v_sub_f32_e32 v90, v104, v90
	v_add_f32_e32 v90, v90, v88
	v_add_f32_e32 v92, v89, v90
	v_mul_f32_e32 v93, v92, v92
	v_fmamk_f32 v88, v93, 0x3e9b6dac, v233
	v_fmaak_f32 v197, v93, v88, 0x3f2aaada
	v_cvt_f32_i32_e32 v88, v100
	v_sub_f32_e32 v89, v92, v89
	v_sub_f32_e32 v89, v90, v89
	v_ldexp_f32 v98, v89, 1
	v_mul_f32_e32 v89, v92, v93
	v_ldexp_f32 v91, v92, 1
	v_pk_mul_f32 v[92:93], v[88:89], v[196:197]
	v_rcp_f32_e32 v62, v62
	v_fma_f32 v90, v88, s38, -v92
	v_fmac_f32_e32 v90, 0xb102e308, v88
	v_pk_add_f32 v[88:89], v[92:93], v[90:91]
	s_nop 0
	v_sub_f32_e32 v91, v89, v91
	v_sub_f32_e32 v91, v93, v91
	v_add_f32_e32 v99, v98, v91
	v_mov_b32_e32 v98, v92
	v_pk_add_f32 v[92:93], v[88:89], v[92:93] neg_lo:[0,1] neg_hi:[0,1]
	v_pk_add_f32 v[100:101], v[88:89], v[98:99]
	v_mov_b32_e32 v91, v88
	v_mov_b32_e32 v93, v101
	v_pk_add_f32 v[102:103], v[90:91], v[92:93] neg_lo:[0,1] neg_hi:[0,1]
	v_pk_add_f32 v[90:91], v[90:91], v[92:93]
	v_mov_b32_e32 v98, v99
	v_pk_add_f32 v[92:93], v[90:91], v[88:89] op_sel:[1,0] op_sel_hi:[0,1] neg_lo:[0,1] neg_hi:[0,1]
	v_pk_add_f32 v[104:105], v[100:101], v[92:93] op_sel_hi:[1,0] neg_lo:[0,1] neg_hi:[0,1]
	v_mov_b32_e32 v100, v101
	v_mov_b32_e32 v101, v91
	v_pk_mov_b32 v[92:93], v[88:89], v[92:93] op_sel:[1,0]
	v_mov_b32_e32 v99, v88
	v_pk_add_f32 v[92:93], v[100:101], v[92:93] neg_lo:[0,1] neg_hi:[0,1]
	v_mov_b32_e32 v104, v102
	v_pk_add_f32 v[88:89], v[98:99], v[92:93] neg_lo:[0,1] neg_hi:[0,1]
	v_mov_b32_e32 v103, v91
	v_pk_add_f32 v[92:93], v[104:105], v[88:89]
	s_nop 0
	v_pk_add_f32 v[98:99], v[92:93], v[92:93] op_sel:[0,1] op_sel_hi:[1,0]
	s_nop 0
	v_pk_add_f32 v[90:91], v[90:91], v[98:99] op_sel:[1,0] op_sel_hi:[0,1]
	v_mov_b32_e32 v93, v90
	v_pk_add_f32 v[100:101], v[92:93], v[102:103] neg_lo:[0,1] neg_hi:[0,1]
	v_mov_b32_e32 v89, v98
	v_sub_f32_e32 v91, v92, v100
	v_pk_add_f32 v[88:89], v[88:89], v[100:101] neg_lo:[0,1] neg_hi:[0,1]
	v_sub_f32_e32 v91, v102, v91
	v_add_f32_e32 v88, v88, v91
	v_add_f32_e32 v88, v88, v89
	v_add_f32_e32 v88, v90, v88
	v_cndmask_b32_e32 v88, v227, v88, vcc
	v_cmp_ngt_f32_e32 vcc, -1.0, v74
	s_nop 1
	v_cndmask_b32_e32 v88, v229, v88, vcc
	v_cmp_neq_f32_e32 vcc, -1.0, v74
	s_nop 1
	v_cndmask_b32_e32 v88, v232, v88, vcc
	v_cmp_lt_f32_e64 vcc, |v74|, s43
	s_nop 1
	v_cndmask_b32_e32 v74, v88, v74, vcc
	s_nop 0
	v_mul_f32_e32 v74, 0xc1000000, v74
	v_mul_f32_e32 v90, v62, v74
	v_add_f32_e32 v62, v90, v90
	v_cmp_ngt_f32_e32 vcc, s33, v62
	s_and_saveexec_b64 s[0:1], vcc
	s_xor_b64 s[0:1], exec, s[0:1]
	v_fmamk_f32 v91, v62, 0x39500d01, v224
	v_fmaak_f32 v91, v62, v91, 0x3c088889
	v_fmaak_f32 v91, v62, v91, 0x3d2aaaab
	v_fmaak_f32 v91, v62, v91, 0x3e2aaaab
	v_fma_f32 v91, v62, v91, 0.5
	v_fma_f32 v91, v62, v91, 1.0
	v_mul_f32_e64 v91, v91, -v62
	s_andn2_saveexec_b64 s[0:1], s[0:1]
	v_mul_f32_e32 v62, 0x3fb8aa3b, v62
	v_exp_f32_e32 v62, v62
	s_nop 0
	v_sub_f32_e32 v91, 1.0, v62
	s_or_b64 exec, exec, s[0:1]
	v_mul_f32_e32 v62, 0xbfb8aa3b, v75
	v_exp_f32_e32 v62, v62
	v_add_f32_e32 v63, v63, v71
	v_mul_f32_e32 v63, 0xbfb8aa3b, v63
	v_exp_f32_e32 v63, v63
	v_add_f32_e32 v75, 1.0, v62
	v_frexp_mant_f32_e32 v99, v75
	v_cvt_f64_f32_e32 v[92:93], v75
	v_add_f32_e32 v98, -1.0, v75
	v_frexp_exp_i32_f64_e32 v92, v[92:93]
	v_cmp_gt_f32_e32 vcc, s31, v99
	v_sub_f32_e32 v100, v98, v75
	v_sub_f32_e32 v98, v62, v98
	v_subbrev_co_u32_e32 v92, vcc, 0, v92, vcc
	v_add_f32_e32 v100, 1.0, v100
	v_sub_u32_e32 v93, 0, v92
	v_add_f32_e32 v98, v98, v100
	v_ldexp_f32 v75, v75, v93
	v_ldexp_f32 v93, v98, v93
	v_add_f32_e32 v98, -1.0, v75
; __device__ __forceinline__ float bflo(unsigned w) { return __uint_as_float(w << 16); }
; __device__ __forceinline__ float bfhi(unsigned w) { return __uint_as_float(w & 0xffff0000u); }
; __device__ __forceinline__ float sigmoidf_(float x) { return __builtin_amdgcn_rcpf(1.f + __builtin_amdgcn_exp2f(-1.4426950408889634f * x)); }
;     __device__ __forceinline__ void operator()(AccRef acc, const Unit& u, int wr, int wc, int fr, int fq) const {
;     ...
;             for (int e = 0; e < 4; ++e) sp[e] = -8.f * log1pf(__expf(-lm[e]));
;             EPI_ROWS_BEGIN
;                 bf16_t* xp = y3 + (size_t)row * 2048 + ch0;
;                 const u32x2 xw = *(const u32x2*)xp;
;                 const f32x4 xc = (f32x4){bflo(xw.x), bfhi(xw.x), bflo(xw.y), bfhi(xw.y)};
;                 f32x4 uo, lo;
; #pragma unroll
;                 for (int e = 0; e < 4; ++e) {
;                     const float rr = acc[ai][0][m][n][e] + ba[e], ii = acc[ai][1][m][n][e] + bi[e];
;                     const float log_a = sp[e] * sigmoidf_(rr);
;                     const float mult = sqrtf(one_minus_exp(2.f * log_a));
	v_add_f32_e32 v101, 1.0, v75
	v_add_f32_e32 v99, 1.0, v98
	v_add_f32_e32 v102, -1.0, v101
	v_sub_f32_e32 v99, v75, v99
	v_sub_f32_e32 v75, v75, v102
	v_add_f32_e32 v75, v93, v75
	v_add_f32_e32 v99, v93, v99
	v_add_f32_e32 v93, v101, v75
	v_rcp_f32_e32 v102, v93
	v_add_f32_e32 v100, v98, v99
	v_sub_f32_e32 v98, v100, v98
	v_sub_f32_e32 v98, v99, v98
	v_sub_f32_e32 v99, v93, v101
	v_sub_f32_e32 v75, v75, v99
	v_mul_f32_e32 v99, v100, v102
	v_mul_f32_e32 v101, v93, v99
	v_fma_f32 v103, v99, v93, -v101
	v_fmac_f32_e32 v103, v99, v75
	v_add_f32_e32 v104, v101, v103
	v_sub_f32_e32 v105, v100, v104
	v_sub_f32_e32 v100, v100, v105
	v_sub_f32_e32 v101, v104, v101
	v_sub_f32_e32 v100, v100, v104
	v_add_f32_e32 v98, v98, v100
	v_sub_f32_e32 v100, v101, v103
	v_add_f32_e32 v98, v100, v98
	v_add_f32_e32 v100, v105, v98
	v_mul_f32_e32 v101, v102, v100
	v_mul_f32_e32 v103, v93, v101
	v_fma_f32 v93, v101, v93, -v103
	v_fmac_f32_e32 v93, v101, v75
	v_sub_f32_e32 v75, v105, v100
	v_add_f32_e32 v75, v98, v75
	v_add_f32_e32 v98, v103, v93
	v_sub_f32_e32 v104, v100, v98
	v_sub_f32_e32 v100, v100, v104
	v_sub_f32_e32 v103, v98, v103
	v_sub_f32_e32 v98, v100, v98
	v_add_f32_e32 v75, v75, v98
	v_sub_f32_e32 v93, v103, v93
	v_cvt_f32_i32_e32 v92, v92
	v_add_f32_e32 v75, v93, v75
	v_add_f32_e32 v93, v99, v101
	v_add_f32_e32 v75, v104, v75
	v_sub_f32_e32 v98, v93, v99
	v_mul_f32_e32 v75, v102, v75
	v_sub_f32_e32 v98, v101, v98
	v_add_f32_e32 v75, v98, v75
	v_mul_f32_e32 v101, 0x3f317218, v92
	v_add_f32_e32 v98, v93, v75
	v_fma_f32 v102, v92, s38, -v101
	v_mul_f32_e32 v99, v98, v98
	v_fmac_f32_e32 v102, 0xb102e308, v92
	v_sub_f32_e32 v92, v98, v93
	v_fmamk_f32 v100, v99, 0x3e9b6dac, v233
	v_sub_f32_e32 v75, v75, v92
	v_add_f32_e32 v92, v101, v102
	v_fmaak_f32 v100, v99, v100, 0x3f2aaada
	v_sub_f32_e32 v93, v92, v101
	v_ldexp_f32 v101, v98, 1
	v_mul_f32_e32 v98, v98, v99
	v_mul_f32_e32 v98, v98, v100
	v_add_f32_e32 v99, v101, v98
	v_sub_f32_e32 v100, v99, v101
	v_ldexp_f32 v75, v75, 1
	v_sub_f32_e32 v98, v98, v100
	v_add_f32_e32 v75, v75, v98
	v_add_f32_e32 v98, v99, v75
	v_sub_f32_e32 v99, v98, v99
	v_sub_f32_e32 v75, v75, v99
	v_add_f32_e32 v99, v92, v98
	v_sub_f32_e32 v100, v99, v92
	v_sub_f32_e32 v101, v99, v100
	v_sub_f32_e32 v93, v102, v93
	v_sub_f32_e32 v92, v92, v101
	v_sub_f32_e32 v98, v98, v100
	v_add_f32_e32 v92, v98, v92
	v_add_f32_e32 v98, v93, v75
	v_sub_f32_e32 v100, v98, v93
	v_sub_f32_e32 v101, v98, v100
	v_sub_f32_e32 v93, v93, v101
	v_sub_f32_e32 v75, v75, v100
	v_add_f32_e32 v92, v98, v92
	v_add_f32_e32 v75, v75, v93
	v_add_f32_e32 v93, v99, v92
	v_sub_f32_e32 v98, v93, v99
	v_sub_f32_e32 v92, v92, v98
	v_add_f32_e32 v75, v75, v92
	v_add_f32_e32 v75, v93, v75
	v_cmp_neq_f32_e32 vcc, s39, v62
	v_add_f32_e32 v63, 1.0, v63
	v_rcp_f32_e32 v63, v63
	v_cndmask_b32_e32 v75, v227, v75, vcc
	v_cmp_ngt_f32_e32 vcc, -1.0, v62
	s_nop 1
	v_cndmask_b32_e32 v75, v229, v75, vcc
	v_cmp_neq_f32_e32 vcc, -1.0, v62
	s_nop 1
	v_cndmask_b32_e32 v75, v232, v75, vcc
	v_cmp_lt_f32_e64 vcc, |v62|, s43
	s_nop 1
	v_cndmask_b32_e32 v62, v75, v62, vcc
	v_mul_f32_e32 v62, 0xc1000000, v62
	v_mul_f32_e32 v75, v63, v62
	v_add_f32_e32 v63, v75, v75
	v_cmp_ngt_f32_e32 vcc, s33, v63
	s_and_saveexec_b64 s[0:1], vcc
	s_xor_b64 s[0:1], exec, s[0:1]
	v_fmamk_f32 v92, v63, 0x39500d01, v224
	v_fmaak_f32 v92, v63, v92, 0x3c088889
	v_fmaak_f32 v92, v63, v92, 0x3d2aaaab
	v_fmaak_f32 v92, v63, v92, 0x3e2aaaab
	v_fma_f32 v92, v63, v92, 0.5
	v_fma_f32 v92, v63, v92, 1.0
	v_mul_f32_e64 v92, v92, -v63
	s_andn2_saveexec_b64 s[0:1], s[0:1]
	v_mul_f32_e32 v63, 0x3fb8aa3b, v63
	v_exp_f32_e32 v63, v63
	s_nop 0
	v_sub_f32_e32 v92, 1.0, v63
	s_or_b64 exec, exec, s[0:1]
	v_mul_f32_e32 v63, 0xbfb8aa3b, v76
	v_exp_f32_e32 v63, v63
	v_add_f32_e32 v64, v64, v72
	v_mul_f32_e32 v64, 0xbfb8aa3b, v64
	v_exp_f32_e32 v64, v64
	v_add_f32_e32 v76, 1.0, v63
	v_frexp_mant_f32_e32 v100, v76
	v_cvt_f64_f32_e32 v[98:99], v76
	v_add_f32_e32 v93, -1.0, v76
	v_frexp_exp_i32_f64_e32 v98, v[98:99]
	v_cmp_gt_f32_e32 vcc, s31, v100
	v_sub_f32_e32 v101, v93, v76
	v_sub_f32_e32 v93, v63, v93
	v_subbrev_co_u32_e32 v98, vcc, 0, v98, vcc
	v_add_f32_e32 v101, 1.0, v101
	v_sub_u32_e32 v99, 0, v98
	v_add_f32_e32 v93, v93, v101
	v_ldexp_f32 v76, v76, v99
	v_ldexp_f32 v93, v93, v99
	v_add_f32_e32 v99, -1.0, v76
	v_add_f32_e32 v102, 1.0, v76
	v_add_f32_e32 v100, 1.0, v99
	v_add_f32_e32 v103, -1.0, v102
	v_sub_f32_e32 v100, v76, v100
	v_sub_f32_e32 v76, v76, v103
	v_add_f32_e32 v76, v93, v76
	v_add_f32_e32 v100, v93, v100
	v_add_f32_e32 v93, v102, v76
	v_rcp_f32_e32 v103, v93
	v_add_f32_e32 v101, v99, v100
	v_sub_f32_e32 v99, v101, v99
	v_sub_f32_e32 v99, v100, v99
	v_sub_f32_e32 v100, v93, v102
	v_sub_f32_e32 v76, v76, v100
	v_mul_f32_e32 v100, v101, v103
	v_mul_f32_e32 v102, v93, v100
	v_fma_f32 v104, v100, v93, -v102
	v_fmac_f32_e32 v104, v100, v76
	v_add_f32_e32 v105, v102, v104
	v_sub_f32_e32 v110, v101, v105
	v_sub_f32_e32 v101, v101, v110
	v_sub_f32_e32 v102, v105, v102
	v_sub_f32_e32 v101, v101, v105
	v_add_f32_e32 v99, v99, v101
	v_sub_f32_e32 v101, v102, v104
	v_add_f32_e32 v99, v101, v99
	v_add_f32_e32 v101, v110, v99
	v_mul_f32_e32 v102, v103, v101
	v_mul_f32_e32 v104, v93, v102
	v_fma_f32 v93, v102, v93, -v104
	v_fmac_f32_e32 v93, v102, v76
	v_sub_f32_e32 v76, v110, v101
	v_add_f32_e32 v76, v99, v76
	v_add_f32_e32 v99, v104, v93
	v_sub_f32_e32 v105, v101, v99
	v_sub_f32_e32 v101, v101, v105
	v_sub_f32_e32 v104, v99, v104
	v_sub_f32_e32 v99, v101, v99
	v_add_f32_e32 v76, v76, v99
	v_sub_f32_e32 v93, v104, v93
	v_cvt_f32_i32_e32 v98, v98
	v_add_f32_e32 v76, v93, v76
	v_add_f32_e32 v93, v100, v102
	v_add_f32_e32 v76, v105, v76
; __device__ __forceinline__ float bflo(unsigned w) { return __uint_as_float(w << 16); }
; __device__ __forceinline__ float bfhi(unsigned w) { return __uint_as_float(w & 0xffff0000u); }
; __device__ __forceinline__ float sigmoidf_(float x) { return __builtin_amdgcn_rcpf(1.f + __builtin_amdgcn_exp2f(-1.4426950408889634f * x)); }
;     __device__ __forceinline__ void operator()(AccRef acc, const Unit& u, int wr, int wc, int fr, int fq) const {
;     ...
;             for (int e = 0; e < 4; ++e) sp[e] = -8.f * log1pf(__expf(-lm[e]));
;             EPI_ROWS_BEGIN
;                 bf16_t* xp = y3 + (size_t)row * 2048 + ch0;
;                 const u32x2 xw = *(const u32x2*)xp;
;                 const f32x4 xc = (f32x4){bflo(xw.x), bfhi(xw.x), bflo(xw.y), bfhi(xw.y)};
;                 f32x4 uo, lo;
; #pragma unroll
;                 for (int e = 0; e < 4; ++e) {
;                     const float rr = acc[ai][0][m][n][e] + ba[e], ii = acc[ai][1][m][n][e] + bi[e];
;                     const float log_a = sp[e] * sigmoidf_(rr);
;                     const float mult = sqrtf(one_minus_exp(2.f * log_a));
	v_sub_f32_e32 v99, v93, v100
	v_mul_f32_e32 v76, v103, v76
	v_sub_f32_e32 v99, v102, v99
	v_add_f32_e32 v76, v99, v76
	v_mul_f32_e32 v102, 0x3f317218, v98
	v_add_f32_e32 v99, v93, v76
	v_fma_f32 v103, v98, s38, -v102
	v_mul_f32_e32 v100, v99, v99
	v_fmac_f32_e32 v103, 0xb102e308, v98
	v_sub_f32_e32 v93, v99, v93
	v_fmamk_f32 v101, v100, 0x3e9b6dac, v233
	v_sub_f32_e32 v76, v76, v93
	v_add_f32_e32 v93, v102, v103
	v_fmaak_f32 v101, v100, v101, 0x3f2aaada
	v_sub_f32_e32 v98, v93, v102
	v_ldexp_f32 v102, v99, 1
	v_mul_f32_e32 v99, v99, v100
	v_mul_f32_e32 v99, v99, v101
	v_add_f32_e32 v100, v102, v99
	v_sub_f32_e32 v101, v100, v102
	v_ldexp_f32 v76, v76, 1
	v_sub_f32_e32 v99, v99, v101
	v_add_f32_e32 v76, v76, v99
	v_add_f32_e32 v99, v100, v76
	v_sub_f32_e32 v100, v99, v100
	v_sub_f32_e32 v76, v76, v100
	v_add_f32_e32 v100, v93, v99
	v_sub_f32_e32 v101, v100, v93
	v_sub_f32_e32 v102, v100, v101
	v_sub_f32_e32 v98, v103, v98
	v_sub_f32_e32 v93, v93, v102
	v_sub_f32_e32 v99, v99, v101
	v_add_f32_e32 v93, v99, v93
	v_add_f32_e32 v99, v98, v76
	v_sub_f32_e32 v101, v99, v98
	v_sub_f32_e32 v102, v99, v101
	v_sub_f32_e32 v98, v98, v102
	v_sub_f32_e32 v76, v76, v101
	v_add_f32_e32 v93, v99, v93
	v_add_f32_e32 v76, v76, v98
	v_add_f32_e32 v98, v100, v93
	v_sub_f32_e32 v99, v98, v100
	v_sub_f32_e32 v93, v93, v99
	v_add_f32_e32 v76, v76, v93
	v_add_f32_e32 v76, v98, v76
	v_cmp_neq_f32_e32 vcc, s39, v63
	v_add_f32_e32 v64, 1.0, v64
	v_rcp_f32_e32 v64, v64
	v_cndmask_b32_e32 v76, v227, v76, vcc
	v_cmp_ngt_f32_e32 vcc, -1.0, v63
	s_nop 1
	v_cndmask_b32_e32 v76, v229, v76, vcc
	v_cmp_neq_f32_e32 vcc, -1.0, v63
	s_nop 1
	v_cndmask_b32_e32 v76, v232, v76, vcc
	v_cmp_lt_f32_e64 vcc, |v63|, s43
	s_nop 1
	v_cndmask_b32_e32 v63, v76, v63, vcc
	v_mul_f32_e32 v63, 0xc1000000, v63
	v_mul_f32_e32 v76, v64, v63
	v_add_f32_e32 v64, v76, v76
	v_cmp_ngt_f32_e32 vcc, s33, v64
	s_and_saveexec_b64 s[0:1], vcc
	s_xor_b64 s[0:1], exec, s[0:1]
	v_fmamk_f32 v93, v64, 0x39500d01, v224
	v_fmaak_f32 v93, v64, v93, 0x3c088889
	v_fmaak_f32 v93, v64, v93, 0x3d2aaaab
	v_fmaak_f32 v93, v64, v93, 0x3e2aaaab
	v_fma_f32 v93, v64, v93, 0.5
	v_fma_f32 v93, v64, v93, 1.0
	v_mul_f32_e64 v93, v93, -v64
	s_andn2_saveexec_b64 s[0:1], s[0:1]
	v_mul_f32_e32 v64, 0x3fb8aa3b, v64
	v_exp_f32_e32 v64, v64
	s_nop 0
	v_sub_f32_e32 v93, 1.0, v64
	s_or_b64 exec, exec, s[0:1]
	v_mul_f32_e32 v64, 0xbfb8aa3b, v77
	v_exp_f32_e32 v64, v64
	v_add_f32_e32 v65, v65, v73
	v_mul_f32_e32 v65, 0xbfb8aa3b, v65
	v_exp_f32_e32 v65, v65
	v_add_f32_e32 v77, 1.0, v64
	v_frexp_mant_f32_e32 v101, v77
	v_cvt_f64_f32_e32 v[98:99], v77
	v_add_f32_e32 v100, -1.0, v77
	v_frexp_exp_i32_f64_e32 v98, v[98:99]
	v_cmp_gt_f32_e32 vcc, s31, v101
	v_sub_f32_e32 v102, v100, v77
	v_sub_f32_e32 v100, v64, v100
	v_subbrev_co_u32_e32 v98, vcc, 0, v98, vcc
	v_add_f32_e32 v102, 1.0, v102
	v_sub_u32_e32 v99, 0, v98
	v_add_f32_e32 v100, v100, v102
	v_ldexp_f32 v77, v77, v99
	v_ldexp_f32 v99, v100, v99
	v_add_f32_e32 v100, -1.0, v77
	v_add_f32_e32 v103, 1.0, v77
	v_add_f32_e32 v101, 1.0, v100
	v_add_f32_e32 v104, -1.0, v103
	v_sub_f32_e32 v101, v77, v101
	v_sub_f32_e32 v77, v77, v104
	v_add_f32_e32 v77, v99, v77
	v_add_f32_e32 v101, v99, v101
	v_add_f32_e32 v99, v103, v77
	v_rcp_f32_e32 v104, v99
	v_add_f32_e32 v102, v100, v101
	v_sub_f32_e32 v100, v102, v100
	v_sub_f32_e32 v100, v101, v100
	v_sub_f32_e32 v101, v99, v103
	v_sub_f32_e32 v77, v77, v101
	v_mul_f32_e32 v101, v102, v104
	v_mul_f32_e32 v103, v99, v101
	v_fma_f32 v105, v101, v99, -v103
	v_fmac_f32_e32 v105, v101, v77
	v_add_f32_e32 v110, v103, v105
	v_sub_f32_e32 v111, v102, v110
	v_sub_f32_e32 v102, v102, v111
	v_sub_f32_e32 v103, v110, v103
	v_sub_f32_e32 v102, v102, v110
	v_add_f32_e32 v100, v100, v102
	v_sub_f32_e32 v102, v103, v105
	v_add_f32_e32 v100, v102, v100
	v_add_f32_e32 v102, v111, v100
	v_mul_f32_e32 v103, v104, v102
	v_mul_f32_e32 v105, v99, v103
	v_fma_f32 v99, v103, v99, -v105
	v_fmac_f32_e32 v99, v103, v77
	v_sub_f32_e32 v77, v111, v102
	v_add_f32_e32 v77, v100, v77
	v_add_f32_e32 v100, v105, v99
	v_sub_f32_e32 v110, v102, v100
	v_sub_f32_e32 v102, v102, v110
	v_sub_f32_e32 v105, v100, v105
	v_sub_f32_e32 v100, v102, v100
	v_add_f32_e32 v77, v77, v100
	v_sub_f32_e32 v99, v105, v99
	v_cvt_f32_i32_e32 v98, v98
	v_add_f32_e32 v77, v99, v77
	v_add_f32_e32 v99, v101, v103
	v_add_f32_e32 v77, v110, v77
	v_sub_f32_e32 v100, v99, v101
	v_mul_f32_e32 v77, v104, v77
	v_sub_f32_e32 v100, v103, v100
	v_add_f32_e32 v77, v100, v77
	v_mul_f32_e32 v103, 0x3f317218, v98
	v_add_f32_e32 v100, v99, v77
	v_fma_f32 v104, v98, s38, -v103
	v_mul_f32_e32 v101, v100, v100
	v_fmac_f32_e32 v104, 0xb102e308, v98
	v_sub_f32_e32 v98, v100, v99
	v_fmamk_f32 v102, v101, 0x3e9b6dac, v233
	v_sub_f32_e32 v77, v77, v98
	v_add_f32_e32 v98, v103, v104
	v_fmaak_f32 v102, v101, v102, 0x3f2aaada
	v_sub_f32_e32 v99, v98, v103
	v_ldexp_f32 v103, v100, 1
	v_mul_f32_e32 v100, v100, v101
	v_mul_f32_e32 v100, v100, v102
	v_add_f32_e32 v101, v103, v100
	v_sub_f32_e32 v102, v101, v103
	v_ldexp_f32 v77, v77, 1
	v_sub_f32_e32 v100, v100, v102
	v_add_f32_e32 v77, v77, v100
	v_add_f32_e32 v100, v101, v77
	v_sub_f32_e32 v101, v100, v101
	v_sub_f32_e32 v77, v77, v101
	v_add_f32_e32 v101, v98, v100
	v_sub_f32_e32 v102, v101, v98
	v_sub_f32_e32 v103, v101, v102
	v_sub_f32_e32 v99, v104, v99
	v_sub_f32_e32 v98, v98, v103
	v_sub_f32_e32 v100, v100, v102
	v_add_f32_e32 v98, v100, v98
	v_add_f32_e32 v100, v99, v77
	v_sub_f32_e32 v102, v100, v99
	v_sub_f32_e32 v103, v100, v102
	v_sub_f32_e32 v99, v99, v103
	v_sub_f32_e32 v77, v77, v102
	v_add_f32_e32 v98, v100, v98
	v_add_f32_e32 v77, v77, v99
	v_add_f32_e32 v99, v101, v98
; __device__ __forceinline__ unsigned cvt_pk_bf16(float lo, float hi) { unsigned r; asm("v_cvt_pk_bf16_f32 %0, %1, %2" : "=v"(r) : "v"(lo), "v"(hi)); return r; }
; __device__ __forceinline__ float bflo(unsigned w) { return __uint_as_float(w << 16); }
; __device__ __forceinline__ float bfhi(unsigned w) { return __uint_as_float(w & 0xffff0000u); }
; __device__ __forceinline__ float sigmoidf_(float x) { return __builtin_amdgcn_rcpf(1.f + __builtin_amdgcn_exp2f(-1.4426950408889634f * x)); }
;     __device__ __forceinline__ void operator()(AccRef acc, const Unit& u, int wr, int wc, int fr, int fq) const {
;     ...
;             for (int e = 0; e < 4; ++e) sp[e] = -8.f * log1pf(__expf(-lm[e]));
;             EPI_ROWS_BEGIN
;                 bf16_t* xp = y3 + (size_t)row * 2048 + ch0;
;                 const u32x2 xw = *(const u32x2*)xp;
;                 const f32x4 xc = (f32x4){bflo(xw.x), bfhi(xw.x), bflo(xw.y), bfhi(xw.y)};
;                 f32x4 uo, lo;
; #pragma unroll
;                 for (int e = 0; e < 4; ++e) {
;                     const float rr = acc[ai][0][m][n][e] + ba[e], ii = acc[ai][1][m][n][e] + bi[e];
;                     const float log_a = sp[e] * sigmoidf_(rr);
;                     const float mult = sqrtf(one_minus_exp(2.f * log_a));
;                     uo[e] = xc[e] * sigmoidf_(ii) * mult; lo[e] = log_a;
;                 }
;                 u32x2 w0, w1; w0.x = cvt_pk_bf16(uo[0], uo[1]); w0.y = cvt_pk_bf16(uo[2], uo[3]); w1.x = cvt_pk_bf16(lo[0], lo[1]); w1.y = cvt_pk_bf16(lo[2], lo[3]);
;                 *(u32x2*)xp = w0;
;                 *(u32x2*)(la + (size_t)row * 512 + ch0) = w1;
;                 asm volatile("" ::: "memory");
	v_sub_f32_e32 v100, v99, v101
	v_sub_f32_e32 v98, v98, v100
	v_add_f32_e32 v77, v77, v98
	v_add_f32_e32 v77, v99, v77
	v_cmp_neq_f32_e32 vcc, s39, v64
	v_add_f32_e32 v65, 1.0, v65
	v_rcp_f32_e32 v65, v65
	v_cndmask_b32_e32 v77, v227, v77, vcc
	v_cmp_ngt_f32_e32 vcc, -1.0, v64
	s_nop 1
	v_cndmask_b32_e32 v77, v229, v77, vcc
	v_cmp_neq_f32_e32 vcc, -1.0, v64
	s_nop 1
	v_cndmask_b32_e32 v77, v232, v77, vcc
	v_cmp_lt_f32_e64 vcc, |v64|, s43
	s_nop 1
	v_cndmask_b32_e32 v64, v77, v64, vcc
	v_mul_f32_e32 v64, 0xc1000000, v64
	v_mul_f32_e32 v65, v65, v64
	v_add_f32_e32 v98, v65, v65
	v_cmp_ngt_f32_e32 vcc, s33, v98
	s_and_saveexec_b64 s[0:1], vcc
	s_xor_b64 s[0:1], exec, s[0:1]
	v_fmamk_f32 v77, v98, 0x39500d01, v224
	v_fmaak_f32 v77, v98, v77, 0x3c088889
	v_fmaak_f32 v77, v98, v77, 0x3d2aaaab
	v_fmaak_f32 v77, v98, v77, 0x3e2aaaab
	v_fma_f32 v77, v98, v77, 0.5
	v_fma_f32 v77, v98, v77, 1.0
	v_mul_f32_e64 v77, v77, -v98
	s_andn2_saveexec_b64 s[0:1], s[0:1]
	v_mul_f32_e32 v77, 0x3fb8aa3b, v98
	v_exp_f32_e32 v77, v77
	s_nop 0
	v_sub_f32_e32 v77, 1.0, v77
	s_or_b64 exec, exec, s[0:1]
	v_mul_f32_e32 v98, 0x4f800000, v93
	v_cmp_gt_f32_e32 vcc, s30, v93
	v_add_f32_e32 v60, v60, v68
	v_mul_f32_e32 v60, 0xbfb8aa3b, v60
	v_cndmask_b32_e32 v93, v93, v98, vcc
	v_sqrt_f32_e32 v98, v93
	v_exp_f32_e32 v60, v60
	s_nop 0
	v_lshlrev_b32_e32 v99, 16, v213
	v_add_f32_e32 v59, v59, v67
	v_add_u32_e32 v100, -1, v98
	v_fma_f32 v101, -v100, v98, v93
	v_cmp_ge_f32_e64 s[6:7], 0, v101
	v_add_u32_e32 v101, 1, v98
	v_add_f32_e32 v60, 1.0, v60
	v_cndmask_b32_e64 v100, v98, v100, s[6:7]
	v_fma_f32 v98, -v101, v98, v93
	v_cmp_lt_f32_e64 s[6:7], 0, v98
	v_rcp_f32_e32 v60, v60
	v_mul_f32_e32 v59, 0xbfb8aa3b, v59
	v_cndmask_b32_e64 v98, v100, v101, s[6:7]
	v_mul_f32_e32 v100, 0x37800000, v98
	v_cndmask_b32_e32 v98, v98, v100, vcc
	v_cmp_class_f32_e32 vcc, v93, v225
	v_mul_f32_e32 v60, v60, v99
	v_exp_f32_e32 v59, v59
	v_cndmask_b32_e32 v93, v98, v93, vcc
	v_mul_f32_e32 v60, v60, v93
	v_mul_f32_e32 v93, 0x4f800000, v92
	v_cmp_gt_f32_e32 vcc, s30, v92
	v_add_f32_e32 v59, 1.0, v59
	v_rcp_f32_e32 v59, v59
	v_cndmask_b32_e32 v92, v92, v93, vcc
	v_sqrt_f32_e32 v93, v92
	v_and_b32_e32 v98, 0xffff0000, v212
	v_mul_f32_e32 v59, v59, v98
	v_add_f32_e32 v58, v58, v66
	v_add_u32_e32 v99, -1, v93
	v_fma_f32 v100, -v99, v93, v92
	v_cmp_ge_f32_e64 s[6:7], 0, v100
	v_add_u32_e32 v100, 1, v93
	v_mul_f32_e32 v58, 0xbfb8aa3b, v58
	v_cndmask_b32_e64 v99, v93, v99, s[6:7]
	v_fma_f32 v93, -v100, v93, v92
	v_cmp_lt_f32_e64 s[6:7], 0, v93
	v_exp_f32_e32 v58, v58
	v_add_f32_e32 v61, v61, v69
	v_cndmask_b32_e64 v93, v99, v100, s[6:7]
	v_mul_f32_e32 v99, 0x37800000, v93
	v_cndmask_b32_e32 v93, v93, v99, vcc
	v_cmp_class_f32_e32 vcc, v92, v225
	v_add_f32_e32 v58, 1.0, v58
	v_rcp_f32_e32 v58, v58
	v_cndmask_b32_e32 v92, v93, v92, vcc
	v_mul_f32_e32 v93, 0x4f800000, v91
	v_cmp_gt_f32_e32 vcc, s30, v91
	v_mul_f32_e32 v59, v59, v92
	v_mul_f32_e32 v61, 0xbfb8aa3b, v61
	v_cndmask_b32_e32 v91, v91, v93, vcc
	v_sqrt_f32_e32 v93, v91
	v_lshlrev_b32_e32 v88, 16, v212
	v_exp_f32_e32 v61, v61
	v_mul_f32_e32 v58, v58, v88
	v_add_u32_e32 v92, -1, v93
	v_fma_f32 v98, -v92, v93, v91
	v_cmp_ge_f32_e64 s[6:7], 0, v98
	v_add_u32_e32 v98, 1, v93
	v_and_b32_e32 v88, 0xffff0000, v213
	v_cndmask_b32_e64 v92, v93, v92, s[6:7]
	v_fma_f32 v93, -v98, v93, v91
	v_cmp_lt_f32_e64 s[6:7], 0, v93
	v_add_f32_e32 v61, 1.0, v61
	v_rcp_f32_e32 v61, v61
	v_cndmask_b32_e64 v92, v92, v98, s[6:7]
	v_mul_f32_e32 v93, 0x37800000, v92
	v_cndmask_b32_e32 v92, v92, v93, vcc
	v_cmp_class_f32_e32 vcc, v91, v225
	v_mul_f32_e32 v61, v61, v88
	v_add_f32_e32 v54, v54, v70
	v_cndmask_b32_e32 v91, v92, v91, vcc
	v_mul_f32_e32 v92, 0x4f800000, v77
	v_cmp_gt_f32_e32 vcc, s30, v77
	v_mul_f32_e32 v58, v58, v91
	v_cvt_pk_bf16_f32 v58, v58, v59
	v_mul_f32_e32 v54, 0xbfb8aa3b, v54
	v_cndmask_b32_e32 v77, v77, v92, vcc
	v_sqrt_f32_e32 v92, v77
	v_exp_f32_e32 v54, v54
	v_add_u32_e32 v89, -1, v92
	v_fma_f32 v91, -v89, v92, v77
	v_cmp_ge_f32_e64 s[6:7], 0, v91
	v_add_u32_e32 v91, 1, v92
	v_add_f32_e32 v54, 1.0, v54
	v_cndmask_b32_e64 v89, v92, v89, s[6:7]
	v_fma_f32 v92, -v91, v92, v77
	v_cmp_lt_f32_e64 s[6:7], 0, v92
	v_rcp_f32_e32 v54, v54
	s_nop 0
	v_cndmask_b32_e64 v89, v89, v91, s[6:7]
	v_mul_f32_e32 v91, 0x37800000, v89
	v_cndmask_b32_e32 v89, v89, v91, vcc
	v_cmp_class_f32_e32 vcc, v77, v225
	v_mul_f32_e32 v54, v54, v74
	s_nop 0
	v_cndmask_b32_e32 v77, v89, v77, vcc
	v_mul_f32_e32 v61, v61, v77
	v_cvt_pk_bf16_f32 v59, v60, v61
	v_cvt_pk_bf16_f32 v60, v90, v75
	v_cvt_pk_bf16_f32 v61, v76, v65
	global_store_dwordx2 v[152:153], v[58:59], off offset:8
	global_store_dwordx2 v[132:133], v[60:61], off offset:8
	s_nop 0
	v_add_f32_e32 v61, v54, v54
	v_cmp_ngt_f32_e32 vcc, s33, v61
	s_and_saveexec_b64 s[0:1], vcc
	s_xor_b64 s[0:1], exec, s[0:1]
	v_fmamk_f32 v60, v61, 0x39500d01, v224
	v_fmaak_f32 v60, v61, v60, 0x3c088889
	v_fmaak_f32 v60, v61, v60, 0x3d2aaaab
	v_fmaak_f32 v60, v61, v60, 0x3e2aaaab
	v_fma_f32 v60, v61, v60, 0.5
	v_fma_f32 v60, v61, v60, 1.0
	v_mul_f32_e64 v60, v60, -v61
	s_andn2_saveexec_b64 s[0:1], s[0:1]
	v_mul_f32_e32 v60, 0x3fb8aa3b, v61
	v_exp_f32_e32 v60, v60
	s_nop 0
	v_sub_f32_e32 v60, 1.0, v60
	s_or_b64 exec, exec, s[0:1]
	v_add_f32_e32 v55, v55, v71
	v_mul_f32_e32 v55, 0xbfb8aa3b, v55
	v_exp_f32_e32 v55, v55
	s_nop 0
	v_add_f32_e32 v55, 1.0, v55
	v_rcp_f32_e32 v55, v55
	s_nop 0
	v_mul_f32_e32 v55, v55, v62
	v_add_f32_e32 v65, v55, v55
	v_cmp_ngt_f32_e32 vcc, s33, v65
	s_and_saveexec_b64 s[0:1], vcc
	s_xor_b64 s[0:1], exec, s[0:1]
	v_fmamk_f32 v61, v65, 0x39500d01, v224
	v_fmaak_f32 v61, v65, v61, 0x3c088889
	v_fmaak_f32 v61, v65, v61, 0x3d2aaaab
; __device__ __forceinline__ unsigned cvt_pk_bf16(float lo, float hi) { unsigned r; asm("v_cvt_pk_bf16_f32 %0, %1, %2" : "=v"(r) : "v"(lo), "v"(hi)); return r; }
; __device__ __forceinline__ float sigmoidf_(float x) { return __builtin_amdgcn_rcpf(1.f + __builtin_amdgcn_exp2f(-1.4426950408889634f * x)); }
;     __device__ __forceinline__ void operator()(AccRef acc, const Unit& u, int wr, int wc, int fr, int fq) const {
;     ...
;                 for (int e = 0; e < 4; ++e) {
;                     const float rr = acc[ai][0][m][n][e] + ba[e], ii = acc[ai][1][m][n][e] + bi[e];
;                     const float log_a = sp[e] * sigmoidf_(rr);
;                     const float mult = sqrtf(one_minus_exp(2.f * log_a));
;                     uo[e] = xc[e] * sigmoidf_(ii) * mult; lo[e] = log_a;
;                 }
;                 u32x2 w0, w1; w0.x = cvt_pk_bf16(uo[0], uo[1]); w0.y = cvt_pk_bf16(uo[2], uo[3]); w1.x = cvt_pk_bf16(lo[0], lo[1]); w1.y = cvt_pk_bf16(lo[2], lo[3]);
;                 *(u32x2*)xp = w0;
;                 *(u32x2*)(la + (size_t)row * 512 + ch0) = w1;
;                 asm volatile("" ::: "memory");
	v_fmaak_f32 v61, v65, v61, 0x3e2aaaab
	v_fma_f32 v61, v65, v61, 0.5
	v_fma_f32 v61, v65, v61, 1.0
	v_mul_f32_e64 v61, v61, -v65
	s_andn2_saveexec_b64 s[0:1], s[0:1]
	v_mul_f32_e32 v61, 0x3fb8aa3b, v65
	v_exp_f32_e32 v61, v61
	s_nop 0
	v_sub_f32_e32 v61, 1.0, v61
	s_or_b64 exec, exec, s[0:1]
	v_add_f32_e32 v56, v56, v72
	v_mul_f32_e32 v56, 0xbfb8aa3b, v56
	v_exp_f32_e32 v56, v56
	s_nop 0
	v_add_f32_e32 v56, 1.0, v56
	v_rcp_f32_e32 v56, v56
	s_nop 0
	v_mul_f32_e32 v56, v56, v63
	v_add_f32_e32 v65, v56, v56
	v_cmp_ngt_f32_e32 vcc, s33, v65
	s_and_saveexec_b64 s[0:1], vcc
	s_xor_b64 s[0:1], exec, s[0:1]
	v_fmamk_f32 v75, v65, 0x39500d01, v224
	v_fmaak_f32 v75, v65, v75, 0x3c088889
	v_fmaak_f32 v75, v65, v75, 0x3d2aaaab
	v_fmaak_f32 v75, v65, v75, 0x3e2aaaab
	v_fma_f32 v75, v65, v75, 0.5
	v_fma_f32 v75, v65, v75, 1.0
	v_mul_f32_e64 v75, v75, -v65
	s_andn2_saveexec_b64 s[0:1], s[0:1]
	v_mul_f32_e32 v65, 0x3fb8aa3b, v65
	v_exp_f32_e32 v65, v65
	s_nop 0
	v_sub_f32_e32 v75, 1.0, v65
	s_or_b64 exec, exec, s[0:1]
	v_add_f32_e32 v57, v57, v73
	v_mul_f32_e32 v57, 0xbfb8aa3b, v57
	v_exp_f32_e32 v57, v57
	s_nop 0
	v_add_f32_e32 v57, 1.0, v57
	v_rcp_f32_e32 v57, v57
	s_nop 0
	v_mul_f32_e32 v57, v57, v64
	v_add_f32_e32 v76, v57, v57
	v_cmp_ngt_f32_e32 vcc, s33, v76
	s_and_saveexec_b64 s[0:1], vcc
	s_xor_b64 s[0:1], exec, s[0:1]
	v_fmamk_f32 v65, v76, 0x39500d01, v224
	v_fmaak_f32 v65, v76, v65, 0x3c088889
	v_fmaak_f32 v65, v76, v65, 0x3d2aaaab
	v_fmaak_f32 v65, v76, v65, 0x3e2aaaab
	v_fma_f32 v65, v76, v65, 0.5
	v_fma_f32 v65, v76, v65, 1.0
	v_mul_f32_e64 v65, v65, -v76
	s_andn2_saveexec_b64 s[0:1], s[0:1]
	v_mul_f32_e32 v65, 0x3fb8aa3b, v76
	v_exp_f32_e32 v65, v65
	s_nop 0
	v_sub_f32_e32 v65, 1.0, v65
	s_or_b64 exec, exec, s[0:1]
	v_mul_f32_e32 v76, 0x4f800000, v75
	v_cmp_gt_f32_e32 vcc, s30, v75
	v_add_f32_e32 v52, v52, v68
	v_mul_f32_e32 v52, 0xbfb8aa3b, v52
	v_cndmask_b32_e32 v75, v75, v76, vcc
	v_sqrt_f32_e32 v76, v75
	v_exp_f32_e32 v52, v52
	s_nop 0
	v_lshlrev_b32_e32 v77, 16, v215
	v_add_f32_e32 v51, v51, v67
	v_add_u32_e32 v88, -1, v76
	v_fma_f32 v89, -v88, v76, v75
	v_cmp_ge_f32_e64 s[6:7], 0, v89
	v_add_u32_e32 v89, 1, v76
	v_add_f32_e32 v52, 1.0, v52
	v_cndmask_b32_e64 v88, v76, v88, s[6:7]
	v_fma_f32 v76, -v89, v76, v75
	v_cmp_lt_f32_e64 s[6:7], 0, v76
	v_rcp_f32_e32 v52, v52
	v_mul_f32_e32 v51, 0xbfb8aa3b, v51
	v_cndmask_b32_e64 v76, v88, v89, s[6:7]
	v_mul_f32_e32 v88, 0x37800000, v76
	v_cndmask_b32_e32 v76, v76, v88, vcc
	v_cmp_class_f32_e32 vcc, v75, v225
	v_mul_f32_e32 v52, v52, v77
	v_exp_f32_e32 v51, v51
	v_cndmask_b32_e32 v75, v76, v75, vcc
	v_mul_f32_e32 v52, v52, v75
	v_mul_f32_e32 v75, 0x4f800000, v61
	v_cmp_gt_f32_e32 vcc, s30, v61
	v_add_f32_e32 v51, 1.0, v51
	v_rcp_f32_e32 v51, v51
	v_cndmask_b32_e32 v61, v61, v75, vcc
	v_sqrt_f32_e32 v75, v61
	v_and_b32_e32 v76, 0xffff0000, v214
	v_mul_f32_e32 v51, v51, v76
	v_add_f32_e32 v50, v50, v66
	v_add_u32_e32 v77, -1, v75
	v_fma_f32 v88, -v77, v75, v61
	v_cmp_ge_f32_e64 s[6:7], 0, v88
	v_add_u32_e32 v88, 1, v75
	v_mul_f32_e32 v50, 0xbfb8aa3b, v50
	v_cndmask_b32_e64 v77, v75, v77, s[6:7]
	v_fma_f32 v75, -v88, v75, v61
	v_cmp_lt_f32_e64 s[6:7], 0, v75
	v_exp_f32_e32 v50, v50
	v_add_f32_e32 v53, v53, v69
	v_cndmask_b32_e64 v75, v77, v88, s[6:7]
	v_mul_f32_e32 v77, 0x37800000, v75
	v_cndmask_b32_e32 v75, v75, v77, vcc
	v_cmp_class_f32_e32 vcc, v61, v225
	v_add_f32_e32 v50, 1.0, v50
	v_rcp_f32_e32 v50, v50
	v_cndmask_b32_e32 v61, v75, v61, vcc
	v_mul_f32_e32 v75, 0x4f800000, v60
	v_cmp_gt_f32_e32 vcc, s30, v60
	v_mul_f32_e32 v51, v51, v61
	v_mul_f32_e32 v53, 0xbfb8aa3b, v53
	v_cndmask_b32_e32 v60, v60, v75, vcc
	v_sqrt_f32_e32 v75, v60
	v_lshlrev_b32_e32 v58, 16, v214
	v_exp_f32_e32 v53, v53
	v_mul_f32_e32 v50, v50, v58
	v_add_u32_e32 v61, -1, v75
	v_fma_f32 v76, -v61, v75, v60
	v_cmp_ge_f32_e64 s[6:7], 0, v76
	v_add_u32_e32 v76, 1, v75
	v_and_b32_e32 v58, 0xffff0000, v215
	v_cndmask_b32_e64 v61, v75, v61, s[6:7]
	v_fma_f32 v75, -v76, v75, v60
	v_cmp_lt_f32_e64 s[6:7], 0, v75
	v_add_f32_e32 v53, 1.0, v53
	v_rcp_f32_e32 v53, v53
	v_cndmask_b32_e64 v61, v61, v76, s[6:7]
	v_mul_f32_e32 v75, 0x37800000, v61
	v_cndmask_b32_e32 v61, v61, v75, vcc
	v_cmp_class_f32_e32 vcc, v60, v225
	v_mul_f32_e32 v53, v53, v58
	v_add_f32_e32 v46, v46, v70
	v_cndmask_b32_e32 v60, v61, v60, vcc
	v_mul_f32_e32 v61, 0x4f800000, v65
	v_cmp_gt_f32_e32 vcc, s30, v65
	v_mul_f32_e32 v50, v50, v60
	v_cvt_pk_bf16_f32 v50, v50, v51
	v_mul_f32_e32 v46, 0xbfb8aa3b, v46
	v_cndmask_b32_e32 v61, v65, v61, vcc
	v_sqrt_f32_e32 v65, v61
	v_exp_f32_e32 v46, v46
	v_add_u32_e32 v59, -1, v65
	v_fma_f32 v60, -v59, v65, v61
	v_cmp_ge_f32_e64 s[6:7], 0, v60
	v_add_u32_e32 v60, 1, v65
	v_add_f32_e32 v46, 1.0, v46
	v_cndmask_b32_e64 v59, v65, v59, s[6:7]
	v_fma_f32 v65, -v60, v65, v61
	v_cmp_lt_f32_e64 s[6:7], 0, v65
	v_rcp_f32_e32 v46, v46
	s_nop 0
	v_cndmask_b32_e64 v59, v59, v60, s[6:7]
	v_mul_f32_e32 v60, 0x37800000, v59
	v_cndmask_b32_e32 v59, v59, v60, vcc
	v_cmp_class_f32_e32 vcc, v61, v225
	v_mul_f32_e32 v46, v46, v74
	s_nop 0
	v_cndmask_b32_e32 v59, v59, v61, vcc
	v_mul_f32_e32 v53, v53, v59
	v_cvt_pk_bf16_f32 v51, v52, v53
	v_cvt_pk_bf16_f32 v52, v54, v55
	v_cvt_pk_bf16_f32 v53, v56, v57
	global_store_dwordx2 v[130:131], v[50:51], off offset:8
	global_store_dwordx2 v[124:125], v[52:53], off offset:8
	s_nop 0
	v_add_f32_e32 v53, v46, v46
	v_cmp_ngt_f32_e32 vcc, s33, v53
	s_and_saveexec_b64 s[0:1], vcc
	s_xor_b64 s[0:1], exec, s[0:1]
	v_fmamk_f32 v52, v53, 0x39500d01, v224
	v_fmaak_f32 v52, v53, v52, 0x3c088889
	v_fmaak_f32 v52, v53, v52, 0x3d2aaaab
	v_fmaak_f32 v52, v53, v52, 0x3e2aaaab
	v_fma_f32 v52, v53, v52, 0.5
; __device__ __forceinline__ unsigned cvt_pk_bf16(float lo, float hi) { unsigned r; asm("v_cvt_pk_bf16_f32 %0, %1, %2" : "=v"(r) : "v"(lo), "v"(hi)); return r; }
; __device__ __forceinline__ float sigmoidf_(float x) { return __builtin_amdgcn_rcpf(1.f + __builtin_amdgcn_exp2f(-1.4426950408889634f * x)); }
;     __device__ __forceinline__ void operator()(AccRef acc, const Unit& u, int wr, int wc, int fr, int fq) const {
;     ...
;                 for (int e = 0; e < 4; ++e) {
;                     const float rr = acc[ai][0][m][n][e] + ba[e], ii = acc[ai][1][m][n][e] + bi[e];
;                     const float log_a = sp[e] * sigmoidf_(rr);
;                     const float mult = sqrtf(one_minus_exp(2.f * log_a));
;                     uo[e] = xc[e] * sigmoidf_(ii) * mult; lo[e] = log_a;
;                 }
;                 u32x2 w0, w1; w0.x = cvt_pk_bf16(uo[0], uo[1]); w0.y = cvt_pk_bf16(uo[2], uo[3]); w1.x = cvt_pk_bf16(lo[0], lo[1]); w1.y = cvt_pk_bf16(lo[2], lo[3]);
;                 *(u32x2*)xp = w0;
;                 *(u32x2*)(la + (size_t)row * 512 + ch0) = w1;
;                 asm volatile("" ::: "memory");
	v_fma_f32 v52, v53, v52, 1.0
	v_mul_f32_e64 v52, v52, -v53
	s_andn2_saveexec_b64 s[0:1], s[0:1]
	v_mul_f32_e32 v52, 0x3fb8aa3b, v53
	v_exp_f32_e32 v52, v52
	s_nop 0
	v_sub_f32_e32 v52, 1.0, v52
	s_or_b64 exec, exec, s[0:1]
	v_add_f32_e32 v47, v47, v71
	v_mul_f32_e32 v47, 0xbfb8aa3b, v47
	v_exp_f32_e32 v47, v47
	s_nop 0
	v_add_f32_e32 v47, 1.0, v47
	v_rcp_f32_e32 v47, v47
	s_nop 0
	v_mul_f32_e32 v47, v47, v62
	v_add_f32_e32 v54, v47, v47
	v_cmp_ngt_f32_e32 vcc, s33, v54
	s_and_saveexec_b64 s[0:1], vcc
	s_xor_b64 s[0:1], exec, s[0:1]
	v_fmamk_f32 v53, v54, 0x39500d01, v224
	v_fmaak_f32 v53, v54, v53, 0x3c088889
	v_fmaak_f32 v53, v54, v53, 0x3d2aaaab
	v_fmaak_f32 v53, v54, v53, 0x3e2aaaab
	v_fma_f32 v53, v54, v53, 0.5
	v_fma_f32 v53, v54, v53, 1.0
	v_mul_f32_e64 v53, v53, -v54
	s_andn2_saveexec_b64 s[0:1], s[0:1]
	v_mul_f32_e32 v53, 0x3fb8aa3b, v54
	v_exp_f32_e32 v53, v53
	s_nop 0
	v_sub_f32_e32 v53, 1.0, v53
	s_or_b64 exec, exec, s[0:1]
	v_add_f32_e32 v48, v48, v72
	v_mul_f32_e32 v48, 0xbfb8aa3b, v48
	v_exp_f32_e32 v48, v48
	s_nop 0
	v_add_f32_e32 v48, 1.0, v48
	v_rcp_f32_e32 v48, v48
	s_nop 0
	v_mul_f32_e32 v48, v48, v63
	v_add_f32_e32 v54, v48, v48
	v_cmp_ngt_f32_e32 vcc, s33, v54
	s_and_saveexec_b64 s[0:1], vcc
	s_xor_b64 s[0:1], exec, s[0:1]
	v_fmamk_f32 v55, v54, 0x39500d01, v224
	v_fmaak_f32 v55, v54, v55, 0x3c088889
	v_fmaak_f32 v55, v54, v55, 0x3d2aaaab
	v_fmaak_f32 v55, v54, v55, 0x3e2aaaab
	v_fma_f32 v55, v54, v55, 0.5
	v_fma_f32 v55, v54, v55, 1.0
	v_mul_f32_e64 v55, v55, -v54
	s_andn2_saveexec_b64 s[0:1], s[0:1]
	v_mul_f32_e32 v54, 0x3fb8aa3b, v54
	v_exp_f32_e32 v54, v54
	s_nop 0
	v_sub_f32_e32 v55, 1.0, v54
	s_or_b64 exec, exec, s[0:1]
	v_add_f32_e32 v49, v49, v73
	v_mul_f32_e32 v49, 0xbfb8aa3b, v49
	v_exp_f32_e32 v49, v49
	s_nop 0
	v_add_f32_e32 v49, 1.0, v49
	v_rcp_f32_e32 v49, v49
	s_nop 0
	v_mul_f32_e32 v49, v49, v64
	v_add_f32_e32 v56, v49, v49
	v_cmp_ngt_f32_e32 vcc, s33, v56
	s_and_saveexec_b64 s[0:1], vcc
	s_xor_b64 s[0:1], exec, s[0:1]
	v_fmamk_f32 v54, v56, 0x39500d01, v224
	v_fmaak_f32 v54, v56, v54, 0x3c088889
	v_fmaak_f32 v54, v56, v54, 0x3d2aaaab
	v_fmaak_f32 v54, v56, v54, 0x3e2aaaab
	v_fma_f32 v54, v56, v54, 0.5
	v_fma_f32 v54, v56, v54, 1.0
	v_mul_f32_e64 v54, v54, -v56
	s_andn2_saveexec_b64 s[0:1], s[0:1]
	v_mul_f32_e32 v54, 0x3fb8aa3b, v56
	v_exp_f32_e32 v54, v54
	s_nop 0
	v_sub_f32_e32 v54, 1.0, v54
	s_or_b64 exec, exec, s[0:1]
	v_mul_f32_e32 v56, 0x4f800000, v55
	v_cmp_gt_f32_e32 vcc, s30, v55
	v_add_f32_e32 v44, v44, v68
	v_mul_f32_e32 v44, 0xbfb8aa3b, v44
	v_cndmask_b32_e32 v55, v55, v56, vcc
	v_sqrt_f32_e32 v56, v55
	v_exp_f32_e32 v44, v44
	s_nop 0
	v_lshlrev_b32_e32 v57, 16, v217
	v_add_f32_e32 v43, v43, v67
	v_add_u32_e32 v58, -1, v56
	v_fma_f32 v59, -v58, v56, v55
	v_cmp_ge_f32_e64 s[6:7], 0, v59
	v_add_u32_e32 v59, 1, v56
	v_add_f32_e32 v44, 1.0, v44
	v_cndmask_b32_e64 v58, v56, v58, s[6:7]
	v_fma_f32 v56, -v59, v56, v55
	v_cmp_lt_f32_e64 s[6:7], 0, v56
	v_rcp_f32_e32 v44, v44
	v_mul_f32_e32 v43, 0xbfb8aa3b, v43
	v_cndmask_b32_e64 v56, v58, v59, s[6:7]
	v_mul_f32_e32 v58, 0x37800000, v56
	v_cndmask_b32_e32 v56, v56, v58, vcc
	v_cmp_class_f32_e32 vcc, v55, v225
	v_mul_f32_e32 v44, v44, v57
	v_exp_f32_e32 v43, v43
	v_cndmask_b32_e32 v55, v56, v55, vcc
	v_mul_f32_e32 v44, v44, v55
	v_mul_f32_e32 v55, 0x4f800000, v53
	v_cmp_gt_f32_e32 vcc, s30, v53
	v_add_f32_e32 v43, 1.0, v43
	v_rcp_f32_e32 v43, v43
	v_cndmask_b32_e32 v53, v53, v55, vcc
	v_sqrt_f32_e32 v55, v53
	v_and_b32_e32 v56, 0xffff0000, v216
	v_mul_f32_e32 v43, v43, v56
	v_add_f32_e32 v42, v42, v66
	v_add_u32_e32 v57, -1, v55
	v_fma_f32 v58, -v57, v55, v53
	v_cmp_ge_f32_e64 s[6:7], 0, v58
	v_add_u32_e32 v58, 1, v55
	v_mul_f32_e32 v42, 0xbfb8aa3b, v42
	v_cndmask_b32_e64 v57, v55, v57, s[6:7]
	v_fma_f32 v55, -v58, v55, v53
	v_cmp_lt_f32_e64 s[6:7], 0, v55
	v_exp_f32_e32 v42, v42
	v_add_f32_e32 v45, v45, v69
	v_cndmask_b32_e64 v55, v57, v58, s[6:7]
	v_mul_f32_e32 v57, 0x37800000, v55
	v_cndmask_b32_e32 v55, v55, v57, vcc
	v_cmp_class_f32_e32 vcc, v53, v225
	v_add_f32_e32 v42, 1.0, v42
	v_rcp_f32_e32 v42, v42
	v_cndmask_b32_e32 v53, v55, v53, vcc
	v_mul_f32_e32 v55, 0x4f800000, v52
	v_cmp_gt_f32_e32 vcc, s30, v52
	v_mul_f32_e32 v43, v43, v53
	v_mul_f32_e32 v45, 0xbfb8aa3b, v45
	v_cndmask_b32_e32 v52, v52, v55, vcc
	v_sqrt_f32_e32 v55, v52
	v_lshlrev_b32_e32 v50, 16, v216
	v_exp_f32_e32 v45, v45
	v_mul_f32_e32 v42, v42, v50
	v_add_u32_e32 v53, -1, v55
	v_fma_f32 v56, -v53, v55, v52
	v_cmp_ge_f32_e64 s[6:7], 0, v56
	v_add_u32_e32 v56, 1, v55
	v_and_b32_e32 v50, 0xffff0000, v217
	v_cndmask_b32_e64 v53, v55, v53, s[6:7]
	v_fma_f32 v55, -v56, v55, v52
	v_cmp_lt_f32_e64 s[6:7], 0, v55
	v_add_f32_e32 v45, 1.0, v45
	v_rcp_f32_e32 v45, v45
	v_cndmask_b32_e64 v53, v53, v56, s[6:7]
	v_mul_f32_e32 v55, 0x37800000, v53
	v_cndmask_b32_e32 v53, v53, v55, vcc
	v_cmp_class_f32_e32 vcc, v52, v225
	v_mul_f32_e32 v45, v45, v50
	v_add_f32_e32 v38, v38, v70
	v_cndmask_b32_e32 v52, v53, v52, vcc
	v_mul_f32_e32 v53, 0x4f800000, v54
	v_cmp_gt_f32_e32 vcc, s30, v54
	v_mul_f32_e32 v42, v42, v52
	v_cvt_pk_bf16_f32 v42, v42, v43
	v_mul_f32_e32 v38, 0xbfb8aa3b, v38
	v_cndmask_b32_e32 v53, v54, v53, vcc
	v_sqrt_f32_e32 v54, v53
	v_exp_f32_e32 v38, v38
	v_add_u32_e32 v51, -1, v54
	v_fma_f32 v52, -v51, v54, v53
	v_cmp_ge_f32_e64 s[6:7], 0, v52
	v_add_u32_e32 v52, 1, v54
	v_add_f32_e32 v38, 1.0, v38
	v_cndmask_b32_e64 v51, v54, v51, s[6:7]
	v_fma_f32 v54, -v52, v54, v53
	v_cmp_lt_f32_e64 s[6:7], 0, v54
	v_rcp_f32_e32 v38, v38
	s_nop 0
	v_cndmask_b32_e64 v51, v51, v52, s[6:7]
	v_mul_f32_e32 v52, 0x37800000, v51
	v_cndmask_b32_e32 v51, v51, v52, vcc
	v_cmp_class_f32_e32 vcc, v53, v225
; __device__ __forceinline__ unsigned cvt_pk_bf16(float lo, float hi) { unsigned r; asm("v_cvt_pk_bf16_f32 %0, %1, %2" : "=v"(r) : "v"(lo), "v"(hi)); return r; }
; __device__ __forceinline__ float sigmoidf_(float x) { return __builtin_amdgcn_rcpf(1.f + __builtin_amdgcn_exp2f(-1.4426950408889634f * x)); }
;     __device__ __forceinline__ void operator()(AccRef acc, const Unit& u, int wr, int wc, int fr, int fq) const {
;     ...
;                 for (int e = 0; e < 4; ++e) {
;                     const float rr = acc[ai][0][m][n][e] + ba[e], ii = acc[ai][1][m][n][e] + bi[e];
;                     const float log_a = sp[e] * sigmoidf_(rr);
;                     const float mult = sqrtf(one_minus_exp(2.f * log_a));
;                     uo[e] = xc[e] * sigmoidf_(ii) * mult; lo[e] = log_a;
;                 }
;                 u32x2 w0, w1; w0.x = cvt_pk_bf16(uo[0], uo[1]); w0.y = cvt_pk_bf16(uo[2], uo[3]); w1.x = cvt_pk_bf16(lo[0], lo[1]); w1.y = cvt_pk_bf16(lo[2], lo[3]);
;                 *(u32x2*)xp = w0;
;                 *(u32x2*)(la + (size_t)row * 512 + ch0) = w1;
;                 asm volatile("" ::: "memory");
	v_mul_f32_e32 v38, v38, v74
	s_nop 0
	v_cndmask_b32_e32 v51, v51, v53, vcc
	v_mul_f32_e32 v45, v45, v51
	v_cvt_pk_bf16_f32 v43, v44, v45
	v_cvt_pk_bf16_f32 v44, v46, v47
	v_cvt_pk_bf16_f32 v45, v48, v49
	global_store_dwordx2 v[122:123], v[42:43], off offset:8
	global_store_dwordx2 v[116:117], v[44:45], off offset:8
	s_nop 0
	v_add_f32_e32 v45, v38, v38
	v_cmp_ngt_f32_e32 vcc, s33, v45
	s_and_saveexec_b64 s[0:1], vcc
	s_xor_b64 s[0:1], exec, s[0:1]
	v_fmamk_f32 v44, v45, 0x39500d01, v224
	v_fmaak_f32 v44, v45, v44, 0x3c088889
	v_fmaak_f32 v44, v45, v44, 0x3d2aaaab
	v_fmaak_f32 v44, v45, v44, 0x3e2aaaab
	v_fma_f32 v44, v45, v44, 0.5
	v_fma_f32 v44, v45, v44, 1.0
	v_mul_f32_e64 v44, v44, -v45
	s_andn2_saveexec_b64 s[0:1], s[0:1]
	v_mul_f32_e32 v44, 0x3fb8aa3b, v45
	v_exp_f32_e32 v44, v44
	s_nop 0
	v_sub_f32_e32 v44, 1.0, v44
	s_or_b64 exec, exec, s[0:1]
	v_add_f32_e32 v39, v39, v71
	v_mul_f32_e32 v39, 0xbfb8aa3b, v39
	v_exp_f32_e32 v39, v39
	s_nop 0
	v_add_f32_e32 v39, 1.0, v39
	v_rcp_f32_e32 v39, v39
	s_nop 0
	v_mul_f32_e32 v39, v39, v62
	v_add_f32_e32 v46, v39, v39
	v_cmp_ngt_f32_e32 vcc, s33, v46
	s_and_saveexec_b64 s[0:1], vcc
	s_xor_b64 s[0:1], exec, s[0:1]
	v_fmamk_f32 v45, v46, 0x39500d01, v224
	v_fmaak_f32 v45, v46, v45, 0x3c088889
	v_fmaak_f32 v45, v46, v45, 0x3d2aaaab
	v_fmaak_f32 v45, v46, v45, 0x3e2aaaab
	v_fma_f32 v45, v46, v45, 0.5
	v_fma_f32 v45, v46, v45, 1.0
	v_mul_f32_e64 v45, v45, -v46
	s_andn2_saveexec_b64 s[0:1], s[0:1]
	v_mul_f32_e32 v45, 0x3fb8aa3b, v46
	v_exp_f32_e32 v45, v45
	s_nop 0
	v_sub_f32_e32 v45, 1.0, v45
	s_or_b64 exec, exec, s[0:1]
	v_add_f32_e32 v40, v40, v72
	v_mul_f32_e32 v40, 0xbfb8aa3b, v40
	v_exp_f32_e32 v40, v40
	s_nop 0
	v_add_f32_e32 v40, 1.0, v40
	v_rcp_f32_e32 v40, v40
	s_nop 0
	v_mul_f32_e32 v40, v40, v63
	v_add_f32_e32 v46, v40, v40
	v_cmp_ngt_f32_e32 vcc, s33, v46
	s_and_saveexec_b64 s[0:1], vcc
	s_xor_b64 s[0:1], exec, s[0:1]
	v_fmamk_f32 v47, v46, 0x39500d01, v224
	v_fmaak_f32 v47, v46, v47, 0x3c088889
	v_fmaak_f32 v47, v46, v47, 0x3d2aaaab
	v_fmaak_f32 v47, v46, v47, 0x3e2aaaab
	v_fma_f32 v47, v46, v47, 0.5
	v_fma_f32 v47, v46, v47, 1.0
	v_mul_f32_e64 v47, v47, -v46
	s_andn2_saveexec_b64 s[0:1], s[0:1]
	v_mul_f32_e32 v46, 0x3fb8aa3b, v46
	v_exp_f32_e32 v46, v46
	s_nop 0
	v_sub_f32_e32 v47, 1.0, v46
	s_or_b64 exec, exec, s[0:1]
	v_add_f32_e32 v41, v41, v73
	v_mul_f32_e32 v41, 0xbfb8aa3b, v41
	v_exp_f32_e32 v41, v41
	s_nop 0
	v_add_f32_e32 v41, 1.0, v41
	v_rcp_f32_e32 v41, v41
	s_nop 0
	v_mul_f32_e32 v41, v41, v64
	v_add_f32_e32 v48, v41, v41
	v_cmp_ngt_f32_e32 vcc, s33, v48
	s_and_saveexec_b64 s[0:1], vcc
	s_xor_b64 s[0:1], exec, s[0:1]
	v_fmamk_f32 v46, v48, 0x39500d01, v224
	v_fmaak_f32 v46, v48, v46, 0x3c088889
	v_fmaak_f32 v46, v48, v46, 0x3d2aaaab
	v_fmaak_f32 v46, v48, v46, 0x3e2aaaab
	v_fma_f32 v46, v48, v46, 0.5
	v_fma_f32 v46, v48, v46, 1.0
	v_mul_f32_e64 v46, v46, -v48
	s_andn2_saveexec_b64 s[0:1], s[0:1]
	v_mul_f32_e32 v46, 0x3fb8aa3b, v48
	v_exp_f32_e32 v46, v46
	s_nop 0
	v_sub_f32_e32 v46, 1.0, v46
	s_or_b64 exec, exec, s[0:1]
	v_mul_f32_e32 v48, 0x4f800000, v47
	v_cmp_gt_f32_e32 vcc, s30, v47
	v_add_f32_e32 v36, v36, v68
	v_mul_f32_e32 v36, 0xbfb8aa3b, v36
	v_cndmask_b32_e32 v47, v47, v48, vcc
	v_sqrt_f32_e32 v48, v47
	v_exp_f32_e32 v36, v36
	s_nop 0
	v_lshlrev_b32_e32 v49, 16, v219
	v_add_f32_e32 v35, v35, v67
	v_add_u32_e32 v50, -1, v48
	v_fma_f32 v51, -v50, v48, v47
	v_cmp_ge_f32_e64 s[6:7], 0, v51
	v_add_u32_e32 v51, 1, v48
	v_add_f32_e32 v36, 1.0, v36
	v_cndmask_b32_e64 v50, v48, v50, s[6:7]
	v_fma_f32 v48, -v51, v48, v47
	v_cmp_lt_f32_e64 s[6:7], 0, v48
	v_rcp_f32_e32 v36, v36
	v_mul_f32_e32 v35, 0xbfb8aa3b, v35
	v_cndmask_b32_e64 v48, v50, v51, s[6:7]
	v_mul_f32_e32 v50, 0x37800000, v48
	v_cndmask_b32_e32 v48, v48, v50, vcc
	v_cmp_class_f32_e32 vcc, v47, v225
	v_mul_f32_e32 v36, v36, v49
	v_exp_f32_e32 v35, v35
	v_cndmask_b32_e32 v47, v48, v47, vcc
	v_mul_f32_e32 v36, v36, v47
	v_mul_f32_e32 v47, 0x4f800000, v45
	v_cmp_gt_f32_e32 vcc, s30, v45
	v_add_f32_e32 v35, 1.0, v35
	v_rcp_f32_e32 v35, v35
	v_cndmask_b32_e32 v45, v45, v47, vcc
	v_sqrt_f32_e32 v47, v45
	v_and_b32_e32 v48, 0xffff0000, v218
	v_mul_f32_e32 v35, v35, v48
	v_add_f32_e32 v34, v34, v66
	v_add_u32_e32 v49, -1, v47
	v_fma_f32 v50, -v49, v47, v45
	v_cmp_ge_f32_e64 s[6:7], 0, v50
	v_add_u32_e32 v50, 1, v47
	v_mul_f32_e32 v34, 0xbfb8aa3b, v34
	v_cndmask_b32_e64 v49, v47, v49, s[6:7]
	v_fma_f32 v47, -v50, v47, v45
	v_cmp_lt_f32_e64 s[6:7], 0, v47
	v_exp_f32_e32 v34, v34
	v_add_f32_e32 v37, v37, v69
	v_cndmask_b32_e64 v47, v49, v50, s[6:7]
	v_mul_f32_e32 v49, 0x37800000, v47
	v_cndmask_b32_e32 v47, v47, v49, vcc
	v_cmp_class_f32_e32 vcc, v45, v225
	v_add_f32_e32 v34, 1.0, v34
	v_rcp_f32_e32 v34, v34
	v_cndmask_b32_e32 v45, v47, v45, vcc
	v_mul_f32_e32 v47, 0x4f800000, v44
	v_cmp_gt_f32_e32 vcc, s30, v44
	v_mul_f32_e32 v35, v35, v45
	v_mul_f32_e32 v37, 0xbfb8aa3b, v37
	v_cndmask_b32_e32 v44, v44, v47, vcc
	v_sqrt_f32_e32 v47, v44
	v_lshlrev_b32_e32 v42, 16, v218
	v_exp_f32_e32 v37, v37
	v_mul_f32_e32 v34, v34, v42
	v_add_u32_e32 v45, -1, v47
	v_fma_f32 v48, -v45, v47, v44
	v_cmp_ge_f32_e64 s[6:7], 0, v48
	v_add_u32_e32 v48, 1, v47
	v_and_b32_e32 v42, 0xffff0000, v219
	v_cndmask_b32_e64 v45, v47, v45, s[6:7]
	v_fma_f32 v47, -v48, v47, v44
	v_cmp_lt_f32_e64 s[6:7], 0, v47
	v_add_f32_e32 v37, 1.0, v37
	v_rcp_f32_e32 v37, v37
	v_cndmask_b32_e64 v45, v45, v48, s[6:7]
	v_mul_f32_e32 v47, 0x37800000, v45
	v_cndmask_b32_e32 v45, v45, v47, vcc
	v_cmp_class_f32_e32 vcc, v44, v225
	v_mul_f32_e32 v37, v37, v42
	v_add_f32_e32 v30, v30, v70
	v_cndmask_b32_e32 v44, v45, v44, vcc
	v_mul_f32_e32 v45, 0x4f800000, v46
; __device__ __forceinline__ unsigned cvt_pk_bf16(float lo, float hi) { unsigned r; asm("v_cvt_pk_bf16_f32 %0, %1, %2" : "=v"(r) : "v"(lo), "v"(hi)); return r; }
; __device__ __forceinline__ float sigmoidf_(float x) { return __builtin_amdgcn_rcpf(1.f + __builtin_amdgcn_exp2f(-1.4426950408889634f * x)); }
;     __device__ __forceinline__ void operator()(AccRef acc, const Unit& u, int wr, int wc, int fr, int fq) const {
;     ...
;                 for (int e = 0; e < 4; ++e) {
;                     const float rr = acc[ai][0][m][n][e] + ba[e], ii = acc[ai][1][m][n][e] + bi[e];
;                     const float log_a = sp[e] * sigmoidf_(rr);
;                     const float mult = sqrtf(one_minus_exp(2.f * log_a));
;                     uo[e] = xc[e] * sigmoidf_(ii) * mult; lo[e] = log_a;
;                 }
;                 u32x2 w0, w1; w0.x = cvt_pk_bf16(uo[0], uo[1]); w0.y = cvt_pk_bf16(uo[2], uo[3]); w1.x = cvt_pk_bf16(lo[0], lo[1]); w1.y = cvt_pk_bf16(lo[2], lo[3]);
;                 *(u32x2*)xp = w0;
;                 *(u32x2*)(la + (size_t)row * 512 + ch0) = w1;
;                 asm volatile("" ::: "memory");
	v_cmp_gt_f32_e32 vcc, s30, v46
	v_mul_f32_e32 v34, v34, v44
	v_cvt_pk_bf16_f32 v34, v34, v35
	v_mul_f32_e32 v30, 0xbfb8aa3b, v30
	v_cndmask_b32_e32 v45, v46, v45, vcc
	v_sqrt_f32_e32 v46, v45
	v_exp_f32_e32 v30, v30
	v_add_u32_e32 v43, -1, v46
	v_fma_f32 v44, -v43, v46, v45
	v_cmp_ge_f32_e64 s[6:7], 0, v44
	v_add_u32_e32 v44, 1, v46
	v_add_f32_e32 v30, 1.0, v30
	v_cndmask_b32_e64 v43, v46, v43, s[6:7]
	v_fma_f32 v46, -v44, v46, v45
	v_cmp_lt_f32_e64 s[6:7], 0, v46
	v_rcp_f32_e32 v30, v30
	s_nop 0
	v_cndmask_b32_e64 v43, v43, v44, s[6:7]
	v_mul_f32_e32 v44, 0x37800000, v43
	v_cndmask_b32_e32 v43, v43, v44, vcc
	v_cmp_class_f32_e32 vcc, v45, v225
	v_mul_f32_e32 v30, v30, v74
	s_nop 0
	v_cndmask_b32_e32 v43, v43, v45, vcc
	v_mul_f32_e32 v37, v37, v43
	v_cvt_pk_bf16_f32 v35, v36, v37
	v_cvt_pk_bf16_f32 v36, v38, v39
	v_cvt_pk_bf16_f32 v37, v40, v41
	global_store_dwordx2 v[114:115], v[34:35], off offset:8
	global_store_dwordx2 v[108:109], v[36:37], off offset:8
	s_nop 0
	v_add_f32_e32 v37, v30, v30
	v_cmp_ngt_f32_e32 vcc, s33, v37
	s_and_saveexec_b64 s[0:1], vcc
	s_xor_b64 s[0:1], exec, s[0:1]
	v_fmamk_f32 v36, v37, 0x39500d01, v224
	v_fmaak_f32 v36, v37, v36, 0x3c088889
	v_fmaak_f32 v36, v37, v36, 0x3d2aaaab
	v_fmaak_f32 v36, v37, v36, 0x3e2aaaab
	v_fma_f32 v36, v37, v36, 0.5
	v_fma_f32 v36, v37, v36, 1.0
	v_mul_f32_e64 v36, v36, -v37
	s_andn2_saveexec_b64 s[0:1], s[0:1]
	v_mul_f32_e32 v36, 0x3fb8aa3b, v37
	v_exp_f32_e32 v36, v36
	s_nop 0
	v_sub_f32_e32 v36, 1.0, v36
	s_or_b64 exec, exec, s[0:1]
	v_add_f32_e32 v31, v31, v71
	v_mul_f32_e32 v31, 0xbfb8aa3b, v31
	v_exp_f32_e32 v31, v31
	s_nop 0
	v_add_f32_e32 v31, 1.0, v31
	v_rcp_f32_e32 v31, v31
	s_nop 0
	v_mul_f32_e32 v31, v31, v62
	v_add_f32_e32 v38, v31, v31
	v_cmp_ngt_f32_e32 vcc, s33, v38
	s_and_saveexec_b64 s[0:1], vcc
	s_xor_b64 s[0:1], exec, s[0:1]
	v_fmamk_f32 v37, v38, 0x39500d01, v224
	v_fmaak_f32 v37, v38, v37, 0x3c088889
	v_fmaak_f32 v37, v38, v37, 0x3d2aaaab
	v_fmaak_f32 v37, v38, v37, 0x3e2aaaab
	v_fma_f32 v37, v38, v37, 0.5
	v_fma_f32 v37, v38, v37, 1.0
	v_mul_f32_e64 v37, v37, -v38
	s_andn2_saveexec_b64 s[0:1], s[0:1]
	v_mul_f32_e32 v37, 0x3fb8aa3b, v38
	v_exp_f32_e32 v37, v37
	s_nop 0
	v_sub_f32_e32 v37, 1.0, v37
	s_or_b64 exec, exec, s[0:1]
	v_add_f32_e32 v32, v32, v72
	v_mul_f32_e32 v32, 0xbfb8aa3b, v32
	v_exp_f32_e32 v32, v32
	s_nop 0
	v_add_f32_e32 v32, 1.0, v32
	v_rcp_f32_e32 v32, v32
	s_nop 0
	v_mul_f32_e32 v32, v32, v63
	v_add_f32_e32 v38, v32, v32
	v_cmp_ngt_f32_e32 vcc, s33, v38
	s_and_saveexec_b64 s[0:1], vcc
	s_xor_b64 s[0:1], exec, s[0:1]
	v_fmamk_f32 v39, v38, 0x39500d01, v224
	v_fmaak_f32 v39, v38, v39, 0x3c088889
	v_fmaak_f32 v39, v38, v39, 0x3d2aaaab
	v_fmaak_f32 v39, v38, v39, 0x3e2aaaab
	v_fma_f32 v39, v38, v39, 0.5
	v_fma_f32 v39, v38, v39, 1.0
	v_mul_f32_e64 v39, v39, -v38
	s_andn2_saveexec_b64 s[0:1], s[0:1]
	v_mul_f32_e32 v38, 0x3fb8aa3b, v38
	v_exp_f32_e32 v38, v38
	s_nop 0
	v_sub_f32_e32 v39, 1.0, v38
	s_or_b64 exec, exec, s[0:1]
	v_add_f32_e32 v33, v33, v73
	v_mul_f32_e32 v33, 0xbfb8aa3b, v33
	v_exp_f32_e32 v33, v33
	s_nop 0
	v_add_f32_e32 v33, 1.0, v33
	v_rcp_f32_e32 v33, v33
	s_nop 0
	v_mul_f32_e32 v33, v33, v64
	v_add_f32_e32 v40, v33, v33
	v_cmp_ngt_f32_e32 vcc, s33, v40
	s_and_saveexec_b64 s[0:1], vcc
	s_xor_b64 s[0:1], exec, s[0:1]
	v_fmamk_f32 v38, v40, 0x39500d01, v224
	v_fmaak_f32 v38, v40, v38, 0x3c088889
	v_fmaak_f32 v38, v40, v38, 0x3d2aaaab
	v_fmaak_f32 v38, v40, v38, 0x3e2aaaab
	v_fma_f32 v38, v40, v38, 0.5
	v_fma_f32 v38, v40, v38, 1.0
	v_mul_f32_e64 v38, v38, -v40
	s_andn2_saveexec_b64 s[0:1], s[0:1]
	v_mul_f32_e32 v38, 0x3fb8aa3b, v40
	v_exp_f32_e32 v38, v38
	s_nop 0
	v_sub_f32_e32 v38, 1.0, v38
	s_or_b64 exec, exec, s[0:1]
	v_mul_f32_e32 v40, 0x4f800000, v39
	v_cmp_gt_f32_e32 vcc, s30, v39
	v_add_f32_e32 v28, v28, v68
	v_mul_f32_e32 v28, 0xbfb8aa3b, v28
	v_cndmask_b32_e32 v39, v39, v40, vcc
	v_sqrt_f32_e32 v40, v39
	v_exp_f32_e32 v28, v28
	s_nop 0
	v_lshlrev_b32_e32 v41, 16, v221
	v_add_f32_e32 v27, v27, v67
	v_add_u32_e32 v42, -1, v40
	v_fma_f32 v43, -v42, v40, v39
	v_cmp_ge_f32_e64 s[6:7], 0, v43
	v_add_u32_e32 v43, 1, v40
	v_add_f32_e32 v28, 1.0, v28
	v_cndmask_b32_e64 v42, v40, v42, s[6:7]
	v_fma_f32 v40, -v43, v40, v39
	v_cmp_lt_f32_e64 s[6:7], 0, v40
	v_rcp_f32_e32 v28, v28
	v_mul_f32_e32 v27, 0xbfb8aa3b, v27
	v_cndmask_b32_e64 v40, v42, v43, s[6:7]
	v_mul_f32_e32 v42, 0x37800000, v40
	v_cndmask_b32_e32 v40, v40, v42, vcc
	v_cmp_class_f32_e32 vcc, v39, v225
	v_mul_f32_e32 v28, v28, v41
	v_exp_f32_e32 v27, v27
	v_cndmask_b32_e32 v39, v40, v39, vcc
	v_mul_f32_e32 v28, v28, v39
	v_mul_f32_e32 v39, 0x4f800000, v37
	v_cmp_gt_f32_e32 vcc, s30, v37
	v_add_f32_e32 v27, 1.0, v27
	v_rcp_f32_e32 v27, v27
	v_cndmask_b32_e32 v37, v37, v39, vcc
	v_sqrt_f32_e32 v39, v37
	v_and_b32_e32 v40, 0xffff0000, v220
	v_mul_f32_e32 v27, v27, v40
	v_add_f32_e32 v26, v26, v66
	v_add_u32_e32 v41, -1, v39
	v_fma_f32 v42, -v41, v39, v37
	v_cmp_ge_f32_e64 s[6:7], 0, v42
	v_add_u32_e32 v42, 1, v39
	v_mul_f32_e32 v26, 0xbfb8aa3b, v26
	v_cndmask_b32_e64 v41, v39, v41, s[6:7]
	v_fma_f32 v39, -v42, v39, v37
	v_cmp_lt_f32_e64 s[6:7], 0, v39
	v_exp_f32_e32 v26, v26
	v_add_f32_e32 v29, v29, v69
	v_cndmask_b32_e64 v39, v41, v42, s[6:7]
	v_mul_f32_e32 v41, 0x37800000, v39
	v_cndmask_b32_e32 v39, v39, v41, vcc
	v_cmp_class_f32_e32 vcc, v37, v225
	v_add_f32_e32 v26, 1.0, v26
	v_rcp_f32_e32 v26, v26
	v_cndmask_b32_e32 v37, v39, v37, vcc
	v_mul_f32_e32 v39, 0x4f800000, v36
	v_cmp_gt_f32_e32 vcc, s30, v36
	v_mul_f32_e32 v27, v27, v37
	v_mul_f32_e32 v29, 0xbfb8aa3b, v29
	v_cndmask_b32_e32 v36, v36, v39, vcc
	v_sqrt_f32_e32 v39, v36
	v_lshlrev_b32_e32 v34, 16, v220
; __device__ __forceinline__ unsigned cvt_pk_bf16(float lo, float hi) { unsigned r; asm("v_cvt_pk_bf16_f32 %0, %1, %2" : "=v"(r) : "v"(lo), "v"(hi)); return r; }
; __device__ __forceinline__ float sigmoidf_(float x) { return __builtin_amdgcn_rcpf(1.f + __builtin_amdgcn_exp2f(-1.4426950408889634f * x)); }
;     __device__ __forceinline__ void operator()(AccRef acc, const Unit& u, int wr, int wc, int fr, int fq) const {
;     ...
;                 for (int e = 0; e < 4; ++e) {
;                     const float rr = acc[ai][0][m][n][e] + ba[e], ii = acc[ai][1][m][n][e] + bi[e];
;                     const float log_a = sp[e] * sigmoidf_(rr);
;                     const float mult = sqrtf(one_minus_exp(2.f * log_a));
;                     uo[e] = xc[e] * sigmoidf_(ii) * mult; lo[e] = log_a;
;                 }
;                 u32x2 w0, w1; w0.x = cvt_pk_bf16(uo[0], uo[1]); w0.y = cvt_pk_bf16(uo[2], uo[3]); w1.x = cvt_pk_bf16(lo[0], lo[1]); w1.y = cvt_pk_bf16(lo[2], lo[3]);
;                 *(u32x2*)xp = w0;
;                 *(u32x2*)(la + (size_t)row * 512 + ch0) = w1;
;                 asm volatile("" ::: "memory");
	v_exp_f32_e32 v29, v29
	v_mul_f32_e32 v26, v26, v34
	v_add_u32_e32 v37, -1, v39
	v_fma_f32 v40, -v37, v39, v36
	v_cmp_ge_f32_e64 s[6:7], 0, v40
	v_add_u32_e32 v40, 1, v39
	v_and_b32_e32 v34, 0xffff0000, v221
	v_cndmask_b32_e64 v37, v39, v37, s[6:7]
	v_fma_f32 v39, -v40, v39, v36
	v_cmp_lt_f32_e64 s[6:7], 0, v39
	v_add_f32_e32 v29, 1.0, v29
	v_rcp_f32_e32 v29, v29
	v_cndmask_b32_e64 v37, v37, v40, s[6:7]
	v_mul_f32_e32 v39, 0x37800000, v37
	v_cndmask_b32_e32 v37, v37, v39, vcc
	v_cmp_class_f32_e32 vcc, v36, v225
	v_mul_f32_e32 v29, v29, v34
	v_add_f32_e32 v22, v22, v70
	v_cndmask_b32_e32 v36, v37, v36, vcc
	v_mul_f32_e32 v37, 0x4f800000, v38
	v_cmp_gt_f32_e32 vcc, s30, v38
	v_mul_f32_e32 v26, v26, v36
	v_cvt_pk_bf16_f32 v26, v26, v27
	v_mul_f32_e32 v22, 0xbfb8aa3b, v22
	v_cndmask_b32_e32 v37, v38, v37, vcc
	v_sqrt_f32_e32 v38, v37
	v_exp_f32_e32 v22, v22
	v_add_u32_e32 v35, -1, v38
	v_fma_f32 v36, -v35, v38, v37
	v_cmp_ge_f32_e64 s[6:7], 0, v36
	v_add_u32_e32 v36, 1, v38
	v_add_f32_e32 v22, 1.0, v22
	v_cndmask_b32_e64 v35, v38, v35, s[6:7]
	v_fma_f32 v38, -v36, v38, v37
	v_cmp_lt_f32_e64 s[6:7], 0, v38
	v_rcp_f32_e32 v22, v22
	s_nop 0
	v_cndmask_b32_e64 v35, v35, v36, s[6:7]
	v_mul_f32_e32 v36, 0x37800000, v35
	v_cndmask_b32_e32 v35, v35, v36, vcc
	v_cmp_class_f32_e32 vcc, v37, v225
	v_mul_f32_e32 v22, v22, v74
	s_nop 0
	v_cndmask_b32_e32 v35, v35, v37, vcc
	v_mul_f32_e32 v29, v29, v35
	v_cvt_pk_bf16_f32 v27, v28, v29
	v_cvt_pk_bf16_f32 v28, v30, v31
	v_cvt_pk_bf16_f32 v29, v32, v33
	global_store_dwordx2 v[106:107], v[26:27], off offset:8
	global_store_dwordx2 v[96:97], v[28:29], off offset:8
	s_nop 0
	v_add_f32_e32 v29, v22, v22
	v_cmp_ngt_f32_e32 vcc, s33, v29
	s_and_saveexec_b64 s[0:1], vcc
	s_xor_b64 s[0:1], exec, s[0:1]
	v_fmamk_f32 v28, v29, 0x39500d01, v224
	v_fmaak_f32 v28, v29, v28, 0x3c088889
	v_fmaak_f32 v28, v29, v28, 0x3d2aaaab
	v_fmaak_f32 v28, v29, v28, 0x3e2aaaab
	v_fma_f32 v28, v29, v28, 0.5
	v_fma_f32 v28, v29, v28, 1.0
	v_mul_f32_e64 v28, v28, -v29
	s_andn2_saveexec_b64 s[0:1], s[0:1]
	v_mul_f32_e32 v28, 0x3fb8aa3b, v29
	v_exp_f32_e32 v28, v28
	s_nop 0
	v_sub_f32_e32 v28, 1.0, v28
	s_or_b64 exec, exec, s[0:1]
	v_add_f32_e32 v23, v23, v71
	v_mul_f32_e32 v23, 0xbfb8aa3b, v23
	v_exp_f32_e32 v23, v23
	s_nop 0
	v_add_f32_e32 v23, 1.0, v23
	v_rcp_f32_e32 v23, v23
	s_nop 0
	v_mul_f32_e32 v23, v23, v62
	v_add_f32_e32 v30, v23, v23
	v_cmp_ngt_f32_e32 vcc, s33, v30
	s_and_saveexec_b64 s[0:1], vcc
	s_xor_b64 s[0:1], exec, s[0:1]
	v_fmamk_f32 v29, v30, 0x39500d01, v224
	v_fmaak_f32 v29, v30, v29, 0x3c088889
	v_fmaak_f32 v29, v30, v29, 0x3d2aaaab
	v_fmaak_f32 v29, v30, v29, 0x3e2aaaab
	v_fma_f32 v29, v30, v29, 0.5
	v_fma_f32 v29, v30, v29, 1.0
	v_mul_f32_e64 v29, v29, -v30
	s_andn2_saveexec_b64 s[0:1], s[0:1]
	v_mul_f32_e32 v29, 0x3fb8aa3b, v30
	v_exp_f32_e32 v29, v29
	s_nop 0
	v_sub_f32_e32 v29, 1.0, v29
	s_or_b64 exec, exec, s[0:1]
	v_add_f32_e32 v24, v24, v72
	v_mul_f32_e32 v24, 0xbfb8aa3b, v24
	v_exp_f32_e32 v24, v24
	s_nop 0
	v_add_f32_e32 v24, 1.0, v24
	v_rcp_f32_e32 v24, v24
	s_nop 0
	v_mul_f32_e32 v24, v24, v63
	v_add_f32_e32 v30, v24, v24
	v_cmp_ngt_f32_e32 vcc, s33, v30
	s_and_saveexec_b64 s[0:1], vcc
	s_xor_b64 s[0:1], exec, s[0:1]
	v_fmamk_f32 v31, v30, 0x39500d01, v224
	v_fmaak_f32 v31, v30, v31, 0x3c088889
	v_fmaak_f32 v31, v30, v31, 0x3d2aaaab
	v_fmaak_f32 v31, v30, v31, 0x3e2aaaab
	v_fma_f32 v31, v30, v31, 0.5
	v_fma_f32 v31, v30, v31, 1.0
	v_mul_f32_e64 v31, v31, -v30
	s_andn2_saveexec_b64 s[0:1], s[0:1]
	v_mul_f32_e32 v30, 0x3fb8aa3b, v30
	v_exp_f32_e32 v30, v30
	s_nop 0
	v_sub_f32_e32 v31, 1.0, v30
	s_or_b64 exec, exec, s[0:1]
	v_add_f32_e32 v25, v25, v73
	v_mul_f32_e32 v25, 0xbfb8aa3b, v25
	v_exp_f32_e32 v25, v25
	s_nop 0
	v_add_f32_e32 v25, 1.0, v25
	v_rcp_f32_e32 v25, v25
	s_nop 0
	v_mul_f32_e32 v25, v25, v64
	v_add_f32_e32 v32, v25, v25
	v_cmp_ngt_f32_e32 vcc, s33, v32
	s_and_saveexec_b64 s[0:1], vcc
	s_xor_b64 s[0:1], exec, s[0:1]
	v_fmamk_f32 v30, v32, 0x39500d01, v224
	v_fmaak_f32 v30, v32, v30, 0x3c088889
	v_fmaak_f32 v30, v32, v30, 0x3d2aaaab
	v_fmaak_f32 v30, v32, v30, 0x3e2aaaab
	v_fma_f32 v30, v32, v30, 0.5
	v_fma_f32 v30, v32, v30, 1.0
	v_mul_f32_e64 v30, v30, -v32
	s_andn2_saveexec_b64 s[0:1], s[0:1]
	v_mul_f32_e32 v30, 0x3fb8aa3b, v32
	v_exp_f32_e32 v30, v30
	s_nop 0
	v_sub_f32_e32 v30, 1.0, v30
	s_or_b64 exec, exec, s[0:1]
	v_mul_f32_e32 v32, 0x4f800000, v31
	v_cmp_gt_f32_e32 vcc, s30, v31
	v_add_f32_e32 v20, v20, v68
	v_mul_f32_e32 v20, 0xbfb8aa3b, v20
	v_cndmask_b32_e32 v31, v31, v32, vcc
	v_sqrt_f32_e32 v32, v31
	v_exp_f32_e32 v20, v20
	s_nop 0
	v_lshlrev_b32_e32 v33, 16, v199
	v_add_f32_e32 v19, v19, v67
	v_add_u32_e32 v34, -1, v32
	v_fma_f32 v35, -v34, v32, v31
	v_cmp_ge_f32_e64 s[6:7], 0, v35
	v_add_u32_e32 v35, 1, v32
	v_add_f32_e32 v20, 1.0, v20
	v_cndmask_b32_e64 v34, v32, v34, s[6:7]
	v_fma_f32 v32, -v35, v32, v31
	v_cmp_lt_f32_e64 s[6:7], 0, v32
	v_rcp_f32_e32 v20, v20
	v_mul_f32_e32 v19, 0xbfb8aa3b, v19
	v_cndmask_b32_e64 v32, v34, v35, s[6:7]
	v_mul_f32_e32 v34, 0x37800000, v32
	v_cndmask_b32_e32 v32, v32, v34, vcc
	v_cmp_class_f32_e32 vcc, v31, v225
	v_mul_f32_e32 v20, v20, v33
	v_exp_f32_e32 v19, v19
	v_cndmask_b32_e32 v31, v32, v31, vcc
	v_mul_f32_e32 v20, v20, v31
	v_mul_f32_e32 v31, 0x4f800000, v29
	v_cmp_gt_f32_e32 vcc, s30, v29
	v_add_f32_e32 v19, 1.0, v19
	v_rcp_f32_e32 v19, v19
	v_cndmask_b32_e32 v29, v29, v31, vcc
	v_sqrt_f32_e32 v31, v29
	v_and_b32_e32 v32, 0xffff0000, v198
	v_mul_f32_e32 v19, v19, v32
	v_add_f32_e32 v18, v18, v66
	v_add_u32_e32 v33, -1, v31
	v_fma_f32 v34, -v33, v31, v29
	v_cmp_ge_f32_e64 s[6:7], 0, v34
	v_add_u32_e32 v34, 1, v31
	v_mul_f32_e32 v18, 0xbfb8aa3b, v18
; __device__ __forceinline__ unsigned cvt_pk_bf16(float lo, float hi) { unsigned r; asm("v_cvt_pk_bf16_f32 %0, %1, %2" : "=v"(r) : "v"(lo), "v"(hi)); return r; }
; __device__ __forceinline__ float sigmoidf_(float x) { return __builtin_amdgcn_rcpf(1.f + __builtin_amdgcn_exp2f(-1.4426950408889634f * x)); }
;     __device__ __forceinline__ void operator()(AccRef acc, const Unit& u, int wr, int wc, int fr, int fq) const {
;     ...
;                 for (int e = 0; e < 4; ++e) {
;                     const float rr = acc[ai][0][m][n][e] + ba[e], ii = acc[ai][1][m][n][e] + bi[e];
;                     const float log_a = sp[e] * sigmoidf_(rr);
;                     const float mult = sqrtf(one_minus_exp(2.f * log_a));
;                     uo[e] = xc[e] * sigmoidf_(ii) * mult; lo[e] = log_a;
;                 }
;                 u32x2 w0, w1; w0.x = cvt_pk_bf16(uo[0], uo[1]); w0.y = cvt_pk_bf16(uo[2], uo[3]); w1.x = cvt_pk_bf16(lo[0], lo[1]); w1.y = cvt_pk_bf16(lo[2], lo[3]);
;                 *(u32x2*)xp = w0;
;                 *(u32x2*)(la + (size_t)row * 512 + ch0) = w1;
;                 asm volatile("" ::: "memory");
	v_cndmask_b32_e64 v33, v31, v33, s[6:7]
	v_fma_f32 v31, -v34, v31, v29
	v_cmp_lt_f32_e64 s[6:7], 0, v31
	v_exp_f32_e32 v18, v18
	v_add_f32_e32 v21, v21, v69
	v_cndmask_b32_e64 v31, v33, v34, s[6:7]
	v_mul_f32_e32 v33, 0x37800000, v31
	v_cndmask_b32_e32 v31, v31, v33, vcc
	v_cmp_class_f32_e32 vcc, v29, v225
	v_add_f32_e32 v18, 1.0, v18
	v_rcp_f32_e32 v18, v18
	v_cndmask_b32_e32 v29, v31, v29, vcc
	v_mul_f32_e32 v31, 0x4f800000, v28
	v_cmp_gt_f32_e32 vcc, s30, v28
	v_mul_f32_e32 v19, v19, v29
	v_mul_f32_e32 v21, 0xbfb8aa3b, v21
	v_cndmask_b32_e32 v28, v28, v31, vcc
	v_sqrt_f32_e32 v31, v28
	v_lshlrev_b32_e32 v26, 16, v198
	v_exp_f32_e32 v21, v21
	v_mul_f32_e32 v18, v18, v26
	v_add_u32_e32 v29, -1, v31
	v_fma_f32 v32, -v29, v31, v28
	v_cmp_ge_f32_e64 s[6:7], 0, v32
	v_add_u32_e32 v32, 1, v31
	v_and_b32_e32 v26, 0xffff0000, v199
	v_cndmask_b32_e64 v29, v31, v29, s[6:7]
	v_fma_f32 v31, -v32, v31, v28
	v_cmp_lt_f32_e64 s[6:7], 0, v31
	v_add_f32_e32 v21, 1.0, v21
	v_rcp_f32_e32 v21, v21
	v_cndmask_b32_e64 v29, v29, v32, s[6:7]
	v_mul_f32_e32 v31, 0x37800000, v29
	v_cndmask_b32_e32 v29, v29, v31, vcc
	v_cmp_class_f32_e32 vcc, v28, v225
	v_mul_f32_e32 v21, v21, v26
	v_add_f32_e32 v14, v14, v70
	v_cndmask_b32_e32 v28, v29, v28, vcc
	v_mul_f32_e32 v29, 0x4f800000, v30
	v_cmp_gt_f32_e32 vcc, s30, v30
	v_mul_f32_e32 v18, v18, v28
	v_cvt_pk_bf16_f32 v18, v18, v19
	v_mul_f32_e32 v14, 0xbfb8aa3b, v14
	v_cndmask_b32_e32 v29, v30, v29, vcc
	v_sqrt_f32_e32 v30, v29
	v_exp_f32_e32 v14, v14
	v_add_u32_e32 v27, -1, v30
	v_fma_f32 v28, -v27, v30, v29
	v_cmp_ge_f32_e64 s[6:7], 0, v28
	v_add_u32_e32 v28, 1, v30
	v_add_f32_e32 v14, 1.0, v14
	v_cndmask_b32_e64 v27, v30, v27, s[6:7]
	v_fma_f32 v30, -v28, v30, v29
	v_cmp_lt_f32_e64 s[6:7], 0, v30
	v_rcp_f32_e32 v14, v14
	s_nop 0
	v_cndmask_b32_e64 v27, v27, v28, s[6:7]
	v_mul_f32_e32 v28, 0x37800000, v27
	v_cndmask_b32_e32 v27, v27, v28, vcc
	v_cmp_class_f32_e32 vcc, v29, v225
	v_mul_f32_e32 v14, v14, v74
	s_nop 0
	v_cndmask_b32_e32 v27, v27, v29, vcc
	v_mul_f32_e32 v21, v21, v27
	v_cvt_pk_bf16_f32 v19, v20, v21
	v_cvt_pk_bf16_f32 v20, v22, v23
	v_cvt_pk_bf16_f32 v21, v24, v25
	global_store_dwordx2 v[94:95], v[18:19], off offset:8
	global_store_dwordx2 v[84:85], v[20:21], off offset:8
	s_nop 0
	v_add_f32_e32 v21, v14, v14
	v_cmp_ngt_f32_e32 vcc, s33, v21
	s_and_saveexec_b64 s[0:1], vcc
	s_xor_b64 s[0:1], exec, s[0:1]
	v_fmamk_f32 v20, v21, 0x39500d01, v224
	v_fmaak_f32 v20, v21, v20, 0x3c088889
	v_fmaak_f32 v20, v21, v20, 0x3d2aaaab
	v_fmaak_f32 v20, v21, v20, 0x3e2aaaab
	v_fma_f32 v20, v21, v20, 0.5
	v_fma_f32 v20, v21, v20, 1.0
	v_mul_f32_e64 v20, v20, -v21
	s_andn2_saveexec_b64 s[0:1], s[0:1]
	v_mul_f32_e32 v20, 0x3fb8aa3b, v21
	v_exp_f32_e32 v20, v20
	s_nop 0
	v_sub_f32_e32 v20, 1.0, v20
	s_or_b64 exec, exec, s[0:1]
	v_add_f32_e32 v15, v15, v71
	v_mul_f32_e32 v15, 0xbfb8aa3b, v15
	v_exp_f32_e32 v15, v15
	s_nop 0
	v_add_f32_e32 v15, 1.0, v15
	v_rcp_f32_e32 v15, v15
	s_nop 0
	v_mul_f32_e32 v15, v15, v62
	v_add_f32_e32 v22, v15, v15
	v_cmp_ngt_f32_e32 vcc, s33, v22
	s_and_saveexec_b64 s[0:1], vcc
	s_xor_b64 s[0:1], exec, s[0:1]
	v_fmamk_f32 v21, v22, 0x39500d01, v224
	v_fmaak_f32 v21, v22, v21, 0x3c088889
	v_fmaak_f32 v21, v22, v21, 0x3d2aaaab
	v_fmaak_f32 v21, v22, v21, 0x3e2aaaab
	v_fma_f32 v21, v22, v21, 0.5
	v_fma_f32 v21, v22, v21, 1.0
	v_mul_f32_e64 v21, v21, -v22
	s_andn2_saveexec_b64 s[0:1], s[0:1]
	v_mul_f32_e32 v21, 0x3fb8aa3b, v22
	v_exp_f32_e32 v21, v21
	s_nop 0
	v_sub_f32_e32 v21, 1.0, v21
	s_or_b64 exec, exec, s[0:1]
	v_add_f32_e32 v16, v16, v72
	v_mul_f32_e32 v16, 0xbfb8aa3b, v16
	v_exp_f32_e32 v16, v16
	s_nop 0
	v_add_f32_e32 v16, 1.0, v16
	v_rcp_f32_e32 v16, v16
	s_nop 0
	v_mul_f32_e32 v16, v16, v63
	v_add_f32_e32 v22, v16, v16
	v_cmp_ngt_f32_e32 vcc, s33, v22
	s_and_saveexec_b64 s[0:1], vcc
	s_xor_b64 s[0:1], exec, s[0:1]
	v_fmamk_f32 v23, v22, 0x39500d01, v224
	v_fmaak_f32 v23, v22, v23, 0x3c088889
	v_fmaak_f32 v23, v22, v23, 0x3d2aaaab
	v_fmaak_f32 v23, v22, v23, 0x3e2aaaab
	v_fma_f32 v23, v22, v23, 0.5
	v_fma_f32 v23, v22, v23, 1.0
	v_mul_f32_e64 v23, v23, -v22
	s_andn2_saveexec_b64 s[0:1], s[0:1]
	v_mul_f32_e32 v22, 0x3fb8aa3b, v22
	v_exp_f32_e32 v22, v22
	s_nop 0
	v_sub_f32_e32 v23, 1.0, v22
	s_or_b64 exec, exec, s[0:1]
	v_add_f32_e32 v17, v17, v73
	v_mul_f32_e32 v17, 0xbfb8aa3b, v17
	v_exp_f32_e32 v17, v17
	s_nop 0
	v_add_f32_e32 v17, 1.0, v17
	v_rcp_f32_e32 v17, v17
	s_nop 0
	v_mul_f32_e32 v17, v17, v64
	v_add_f32_e32 v24, v17, v17
	v_cmp_ngt_f32_e32 vcc, s33, v24
	s_and_saveexec_b64 s[0:1], vcc
	s_xor_b64 s[0:1], exec, s[0:1]
	v_fmamk_f32 v22, v24, 0x39500d01, v224
	v_fmaak_f32 v22, v24, v22, 0x3c088889
	v_fmaak_f32 v22, v24, v22, 0x3d2aaaab
	v_fmaak_f32 v22, v24, v22, 0x3e2aaaab
	v_fma_f32 v22, v24, v22, 0.5
	v_fma_f32 v22, v24, v22, 1.0
	v_mul_f32_e64 v22, v22, -v24
	s_andn2_saveexec_b64 s[0:1], s[0:1]
	v_mul_f32_e32 v22, 0x3fb8aa3b, v24
	v_exp_f32_e32 v22, v22
	s_nop 0
	v_sub_f32_e32 v22, 1.0, v22
	s_or_b64 exec, exec, s[0:1]
	v_mul_f32_e32 v24, 0x4f800000, v23
	v_cmp_gt_f32_e32 vcc, s30, v23
	v_add_f32_e32 v12, v12, v68
	v_mul_f32_e32 v12, 0xbfb8aa3b, v12
	v_cndmask_b32_e32 v23, v23, v24, vcc
	v_sqrt_f32_e32 v24, v23
	v_exp_f32_e32 v12, v12
	s_nop 0
	v_lshlrev_b32_e32 v25, 16, v201
	v_add_f32_e32 v11, v11, v67
	v_add_u32_e32 v26, -1, v24
	v_fma_f32 v27, -v26, v24, v23
	v_cmp_ge_f32_e64 s[6:7], 0, v27
	v_add_u32_e32 v27, 1, v24
	v_add_f32_e32 v12, 1.0, v12
	v_cndmask_b32_e64 v26, v24, v26, s[6:7]
	v_fma_f32 v24, -v27, v24, v23
	v_cmp_lt_f32_e64 s[6:7], 0, v24
	v_rcp_f32_e32 v12, v12
	v_mul_f32_e32 v11, 0xbfb8aa3b, v11
	v_cndmask_b32_e64 v24, v26, v27, s[6:7]
	v_mul_f32_e32 v26, 0x37800000, v24
; __device__ __forceinline__ unsigned cvt_pk_bf16(float lo, float hi) { unsigned r; asm("v_cvt_pk_bf16_f32 %0, %1, %2" : "=v"(r) : "v"(lo), "v"(hi)); return r; }
; __device__ __forceinline__ float sigmoidf_(float x) { return __builtin_amdgcn_rcpf(1.f + __builtin_amdgcn_exp2f(-1.4426950408889634f * x)); }
;     __device__ __forceinline__ void operator()(AccRef acc, const Unit& u, int wr, int wc, int fr, int fq) const {
;     ...
;                 for (int e = 0; e < 4; ++e) {
;                     const float rr = acc[ai][0][m][n][e] + ba[e], ii = acc[ai][1][m][n][e] + bi[e];
;                     const float log_a = sp[e] * sigmoidf_(rr);
;                     const float mult = sqrtf(one_minus_exp(2.f * log_a));
;                     uo[e] = xc[e] * sigmoidf_(ii) * mult; lo[e] = log_a;
;                 }
;                 u32x2 w0, w1; w0.x = cvt_pk_bf16(uo[0], uo[1]); w0.y = cvt_pk_bf16(uo[2], uo[3]); w1.x = cvt_pk_bf16(lo[0], lo[1]); w1.y = cvt_pk_bf16(lo[2], lo[3]);
;                 *(u32x2*)xp = w0;
;                 *(u32x2*)(la + (size_t)row * 512 + ch0) = w1;
;                 asm volatile("" ::: "memory");
	v_cndmask_b32_e32 v24, v24, v26, vcc
	v_cmp_class_f32_e32 vcc, v23, v225
	v_mul_f32_e32 v12, v12, v25
	v_exp_f32_e32 v11, v11
	v_cndmask_b32_e32 v23, v24, v23, vcc
	v_mul_f32_e32 v12, v12, v23
	v_mul_f32_e32 v23, 0x4f800000, v21
	v_cmp_gt_f32_e32 vcc, s30, v21
	v_add_f32_e32 v11, 1.0, v11
	v_rcp_f32_e32 v11, v11
	v_cndmask_b32_e32 v21, v21, v23, vcc
	v_sqrt_f32_e32 v23, v21
	v_and_b32_e32 v24, 0xffff0000, v200
	v_mul_f32_e32 v11, v11, v24
	v_add_f32_e32 v10, v10, v66
	v_add_u32_e32 v25, -1, v23
	v_fma_f32 v26, -v25, v23, v21
	v_cmp_ge_f32_e64 s[6:7], 0, v26
	v_add_u32_e32 v26, 1, v23
	v_mul_f32_e32 v10, 0xbfb8aa3b, v10
	v_cndmask_b32_e64 v25, v23, v25, s[6:7]
	v_fma_f32 v23, -v26, v23, v21
	v_cmp_lt_f32_e64 s[6:7], 0, v23
	v_exp_f32_e32 v10, v10
	v_add_f32_e32 v13, v13, v69
	v_cndmask_b32_e64 v23, v25, v26, s[6:7]
	v_mul_f32_e32 v25, 0x37800000, v23
	v_cndmask_b32_e32 v23, v23, v25, vcc
	v_cmp_class_f32_e32 vcc, v21, v225
	v_add_f32_e32 v10, 1.0, v10
	v_rcp_f32_e32 v10, v10
	v_cndmask_b32_e32 v21, v23, v21, vcc
	v_mul_f32_e32 v23, 0x4f800000, v20
	v_cmp_gt_f32_e32 vcc, s30, v20
	v_mul_f32_e32 v11, v11, v21
	v_mul_f32_e32 v13, 0xbfb8aa3b, v13
	v_cndmask_b32_e32 v20, v20, v23, vcc
	v_sqrt_f32_e32 v23, v20
	v_lshlrev_b32_e32 v18, 16, v200
	v_exp_f32_e32 v13, v13
	v_mul_f32_e32 v10, v10, v18
	v_add_u32_e32 v21, -1, v23
	v_fma_f32 v24, -v21, v23, v20
	v_cmp_ge_f32_e64 s[6:7], 0, v24
	v_add_u32_e32 v24, 1, v23
	v_and_b32_e32 v18, 0xffff0000, v201
	v_cndmask_b32_e64 v21, v23, v21, s[6:7]
	v_fma_f32 v23, -v24, v23, v20
	v_cmp_lt_f32_e64 s[6:7], 0, v23
	v_add_f32_e32 v13, 1.0, v13
	v_rcp_f32_e32 v13, v13
	v_cndmask_b32_e64 v21, v21, v24, s[6:7]
	v_mul_f32_e32 v23, 0x37800000, v21
	v_cndmask_b32_e32 v21, v21, v23, vcc
	v_cmp_class_f32_e32 vcc, v20, v225
	v_mul_f32_e32 v13, v13, v18
	v_add_f32_e32 v6, v6, v70
	v_cndmask_b32_e32 v20, v21, v20, vcc
	v_mul_f32_e32 v21, 0x4f800000, v22
	v_cmp_gt_f32_e32 vcc, s30, v22
	v_mul_f32_e32 v10, v10, v20
	v_cvt_pk_bf16_f32 v10, v10, v11
	v_mul_f32_e32 v6, 0xbfb8aa3b, v6
	v_cndmask_b32_e32 v21, v22, v21, vcc
	v_sqrt_f32_e32 v22, v21
	v_exp_f32_e32 v6, v6
	v_add_u32_e32 v19, -1, v22
	v_fma_f32 v20, -v19, v22, v21
	v_cmp_ge_f32_e64 s[6:7], 0, v20
	v_add_u32_e32 v20, 1, v22
	v_add_f32_e32 v6, 1.0, v6
	v_cndmask_b32_e64 v19, v22, v19, s[6:7]
	v_fma_f32 v22, -v20, v22, v21
	v_cmp_lt_f32_e64 s[6:7], 0, v22
	v_rcp_f32_e32 v6, v6
	s_nop 0
	v_cndmask_b32_e64 v19, v19, v20, s[6:7]
	v_mul_f32_e32 v20, 0x37800000, v19
	v_cndmask_b32_e32 v19, v19, v20, vcc
	v_cmp_class_f32_e32 vcc, v21, v225
	v_mul_f32_e32 v6, v6, v74
	s_nop 0
	v_cndmask_b32_e32 v19, v19, v21, vcc
	v_mul_f32_e32 v13, v13, v19
	v_cvt_pk_bf16_f32 v11, v12, v13
	v_cvt_pk_bf16_f32 v12, v14, v15
	v_cvt_pk_bf16_f32 v13, v16, v17
	global_store_dwordx2 v[82:83], v[10:11], off offset:8
	global_store_dwordx2 v[80:81], v[12:13], off offset:8
	s_nop 0
	v_add_f32_e32 v13, v6, v6
	v_cmp_ngt_f32_e32 vcc, s33, v13
	s_and_saveexec_b64 s[0:1], vcc
	s_xor_b64 s[0:1], exec, s[0:1]
	v_fmamk_f32 v12, v13, 0x39500d01, v224
	v_fmaak_f32 v12, v13, v12, 0x3c088889
	v_fmaak_f32 v12, v13, v12, 0x3d2aaaab
	v_fmaak_f32 v12, v13, v12, 0x3e2aaaab
	v_fma_f32 v12, v13, v12, 0.5
	v_fma_f32 v12, v13, v12, 1.0
	v_mul_f32_e64 v12, v12, -v13
	s_andn2_saveexec_b64 s[0:1], s[0:1]
	v_mul_f32_e32 v12, 0x3fb8aa3b, v13
	v_exp_f32_e32 v12, v12
	s_nop 0
	v_sub_f32_e32 v12, 1.0, v12
	s_or_b64 exec, exec, s[0:1]
	v_add_f32_e32 v7, v7, v71
	v_mul_f32_e32 v7, 0xbfb8aa3b, v7
	v_exp_f32_e32 v7, v7
	s_nop 0
	v_add_f32_e32 v7, 1.0, v7
	v_rcp_f32_e32 v7, v7
	s_nop 0
	v_mul_f32_e32 v7, v7, v62
	v_add_f32_e32 v14, v7, v7
	v_cmp_ngt_f32_e32 vcc, s33, v14
	s_and_saveexec_b64 s[0:1], vcc
	s_xor_b64 s[0:1], exec, s[0:1]
	v_fmamk_f32 v13, v14, 0x39500d01, v224
	v_fmaak_f32 v13, v14, v13, 0x3c088889
	v_fmaak_f32 v13, v14, v13, 0x3d2aaaab
	v_fmaak_f32 v13, v14, v13, 0x3e2aaaab
	v_fma_f32 v13, v14, v13, 0.5
	v_fma_f32 v13, v14, v13, 1.0
	v_mul_f32_e64 v13, v13, -v14
	s_andn2_saveexec_b64 s[0:1], s[0:1]
	v_mul_f32_e32 v13, 0x3fb8aa3b, v14
	v_exp_f32_e32 v13, v13
	s_nop 0
	v_sub_f32_e32 v13, 1.0, v13
	s_or_b64 exec, exec, s[0:1]
	v_add_f32_e32 v8, v8, v72
	v_mul_f32_e32 v8, 0xbfb8aa3b, v8
	v_exp_f32_e32 v8, v8
	s_nop 0
	v_add_f32_e32 v8, 1.0, v8
	v_rcp_f32_e32 v8, v8
	s_nop 0
	v_mul_f32_e32 v8, v8, v63
	v_add_f32_e32 v14, v8, v8
	v_cmp_ngt_f32_e32 vcc, s33, v14
	s_and_saveexec_b64 s[0:1], vcc
	s_xor_b64 s[0:1], exec, s[0:1]
	v_fmamk_f32 v15, v14, 0x39500d01, v224
	v_fmaak_f32 v15, v14, v15, 0x3c088889
	v_fmaak_f32 v15, v14, v15, 0x3d2aaaab
; __device__ __forceinline__ unsigned cvt_pk_bf16(float lo, float hi) { unsigned r; asm("v_cvt_pk_bf16_f32 %0, %1, %2" : "=v"(r) : "v"(lo), "v"(hi)); return r; }
; __device__ __forceinline__ float sigmoidf_(float x) { return __builtin_amdgcn_rcpf(1.f + __builtin_amdgcn_exp2f(-1.4426950408889634f * x)); }
; #define PG8_BAR __builtin_amdgcn_s_barrier()
; #define PG8_BAR __builtin_amdgcn_s_barrier()
; template <class Epi, class Sched>
; __device__ __forceinline__ void gemm_phase(LAS unsigned char* lds, const Gemm g, const Sched& S, const Epi& E) {
;     ...
;         if (!has_next) break;
; #pragma unroll
;         for (int a = 0; a < 2; ++a)
; #pragma unroll
;             for (int b = 0; b < 2; ++b)
; #pragma unroll
;                 for (int m = 0; m < 4; ++m)
; #pragma unroll
;                     for (int n = 0; n < 2; ++n) acc[a][b][m][n] = (f32x4){0.f, 0.f, 0.f, 0.f};
;         cur = nxt; cA = nA; cB = nB; ++ui;
;         if (wr == 1) PG8_BAR;
;     __device__ __forceinline__ void operator()(AccRef acc, const Unit& u, int wr, int wc, int fr, int fq) const {
;     ...
;                 for (int e = 0; e < 4; ++e) {
;                     const float rr = acc[ai][0][m][n][e] + ba[e], ii = acc[ai][1][m][n][e] + bi[e];
;                     const float log_a = sp[e] * sigmoidf_(rr);
;                     const float mult = sqrtf(one_minus_exp(2.f * log_a));
;                     uo[e] = xc[e] * sigmoidf_(ii) * mult; lo[e] = log_a;
;                 }
;                 u32x2 w0, w1; w0.x = cvt_pk_bf16(uo[0], uo[1]); w0.y = cvt_pk_bf16(uo[2], uo[3]); w1.x = cvt_pk_bf16(lo[0], lo[1]); w1.y = cvt_pk_bf16(lo[2], lo[3]);
;                 *(u32x2*)xp = w0;
;                 *(u32x2*)(la + (size_t)row * 512 + ch0) = w1;
;                 asm volatile("" ::: "memory");
	v_fmaak_f32 v15, v14, v15, 0x3e2aaaab
	v_fma_f32 v15, v14, v15, 0.5
	v_fma_f32 v15, v14, v15, 1.0
	v_mul_f32_e64 v15, v15, -v14
	s_andn2_saveexec_b64 s[0:1], s[0:1]
	v_mul_f32_e32 v14, 0x3fb8aa3b, v14
	v_exp_f32_e32 v14, v14
	s_nop 0
	v_sub_f32_e32 v15, 1.0, v14
	s_or_b64 exec, exec, s[0:1]
	v_add_f32_e32 v9, v9, v73
	v_mul_f32_e32 v9, 0xbfb8aa3b, v9
	v_exp_f32_e32 v9, v9
	s_nop 0
	v_add_f32_e32 v9, 1.0, v9
	v_rcp_f32_e32 v9, v9
	s_nop 0
	v_mul_f32_e32 v9, v9, v64
	v_add_f32_e32 v16, v9, v9
	v_cmp_ngt_f32_e32 vcc, s33, v16
	s_and_saveexec_b64 s[0:1], vcc
	s_xor_b64 s[0:1], exec, s[0:1]
	v_fmamk_f32 v14, v16, 0x39500d01, v224
	v_fmaak_f32 v14, v16, v14, 0x3c088889
	v_fmaak_f32 v14, v16, v14, 0x3d2aaaab
	v_fmaak_f32 v14, v16, v14, 0x3e2aaaab
	v_fma_f32 v14, v16, v14, 0.5
	v_fma_f32 v14, v16, v14, 1.0
	v_mul_f32_e64 v14, v14, -v16
	s_andn2_saveexec_b64 s[0:1], s[0:1]
	v_mul_f32_e32 v14, 0x3fb8aa3b, v16
	v_exp_f32_e32 v14, v14
	s_nop 0
	v_sub_f32_e32 v14, 1.0, v14
	s_or_b64 exec, exec, s[0:1]
	v_add_f32_e32 v4, v4, v68
	v_mul_f32_e32 v4, 0xbfb8aa3b, v4
	v_exp_f32_e32 v4, v4
	v_mul_f32_e32 v16, 0x4f800000, v15
	v_cmp_gt_f32_e32 vcc, s30, v15
	s_nop 0
	v_lshlrev_b32_e32 v17, 16, v203
	v_add_f32_e32 v4, 1.0, v4
	v_cndmask_b32_e32 v15, v15, v16, vcc
	v_rcp_f32_e32 v4, v4
	v_sqrt_f32_e32 v16, v15
	v_add_f32_e32 v3, v3, v67
	v_mul_f32_e32 v3, 0xbfb8aa3b, v3
	v_mul_f32_e32 v4, v4, v17
	v_add_u32_e32 v17, -1, v16
	v_fma_f32 v18, -v17, v16, v15
	v_cmp_ge_f32_e64 s[6:7], 0, v18
	v_add_u32_e32 v18, 1, v16
	v_exp_f32_e32 v3, v3
	v_cndmask_b32_e64 v17, v16, v17, s[6:7]
	v_fma_f32 v16, -v18, v16, v15
	v_cmp_lt_f32_e64 s[6:7], 0, v16
	v_add_f32_e32 v3, 1.0, v3
	v_rcp_f32_e32 v3, v3
	v_cndmask_b32_e64 v16, v17, v18, s[6:7]
	v_mul_f32_e32 v17, 0x37800000, v16
	v_cndmask_b32_e32 v16, v16, v17, vcc
	v_cmp_class_f32_e32 vcc, v15, v225
	v_add_f32_e32 v2, v2, v66
	v_mul_f32_e32 v2, 0xbfb8aa3b, v2
	v_cndmask_b32_e32 v15, v16, v15, vcc
	v_mul_f32_e32 v16, 0x4f800000, v13
	v_cmp_gt_f32_e32 vcc, s30, v13
	v_mul_f32_e32 v4, v4, v15
	v_and_b32_e32 v15, 0xffff0000, v202
	v_cndmask_b32_e32 v13, v13, v16, vcc
	v_sqrt_f32_e32 v16, v13
	v_mul_f32_e32 v3, v3, v15
	v_exp_f32_e32 v2, v2
	v_lshlrev_b32_e32 v10, 16, v202
	v_add_u32_e32 v15, -1, v16
	v_fma_f32 v17, -v15, v16, v13
	v_cmp_ge_f32_e64 s[6:7], 0, v17
	v_add_u32_e32 v17, 1, v16
	v_add_f32_e32 v2, 1.0, v2
	v_cndmask_b32_e64 v15, v16, v15, s[6:7]
	v_fma_f32 v16, -v17, v16, v13
	v_cmp_lt_f32_e64 s[6:7], 0, v16
	v_rcp_f32_e32 v2, v2
	v_add_f32_e32 v5, v5, v69
	v_cndmask_b32_e64 v15, v15, v17, s[6:7]
	v_mul_f32_e32 v16, 0x37800000, v15
	v_cndmask_b32_e32 v15, v15, v16, vcc
	v_cmp_class_f32_e32 vcc, v13, v225
	v_mul_f32_e32 v2, v2, v10
	v_mul_f32_e32 v5, 0xbfb8aa3b, v5
	v_cndmask_b32_e32 v13, v15, v13, vcc
	v_mul_f32_e32 v15, 0x4f800000, v12
	v_cmp_gt_f32_e32 vcc, s30, v12
	v_mul_f32_e32 v3, v3, v13
	v_exp_f32_e32 v5, v5
	v_cndmask_b32_e32 v12, v12, v15, vcc
	v_sqrt_f32_e32 v15, v12
	s_mov_b64 s[0:1], -1
	v_add_f32_e32 v5, 1.0, v5
	v_rcp_f32_e32 v5, v5
	v_add_u32_e32 v10, -1, v15
	v_fma_f32 v13, -v10, v15, v12
	v_cmp_ge_f32_e64 s[6:7], 0, v13
	v_add_u32_e32 v13, 1, v15
	s_nop 0
	v_cndmask_b32_e64 v10, v15, v10, s[6:7]
	v_fma_f32 v15, -v13, v15, v12
	v_cmp_lt_f32_e64 s[6:7], 0, v15
	s_nop 1
	v_cndmask_b32_e64 v10, v10, v13, s[6:7]
	v_mul_f32_e32 v13, 0x37800000, v10
	v_cndmask_b32_e32 v10, v10, v13, vcc
	v_mul_f32_e32 v13, 0x4f800000, v14
	v_cmp_gt_f32_e32 vcc, s30, v14
	v_cmp_class_f32_e64 s[6:7], v12, v225
	s_nop 0
	v_cndmask_b32_e32 v13, v14, v13, vcc
	v_sqrt_f32_e32 v14, v13
	v_cndmask_b32_e64 v10, v10, v12, s[6:7]
	v_mul_f32_e32 v2, v2, v10
	v_and_b32_e32 v10, 0xffff0000, v203
	v_add_u32_e32 v11, -1, v14
	v_fma_f32 v12, -v11, v14, v13
	v_cmp_ge_f32_e64 s[6:7], 0, v12
	v_add_u32_e32 v12, 1, v14
	v_mul_f32_e32 v5, v5, v10
	v_cndmask_b32_e64 v11, v14, v11, s[6:7]
	v_fma_f32 v14, -v12, v14, v13
	v_cmp_lt_f32_e64 s[6:7], 0, v14
	v_cvt_pk_bf16_f32 v2, v2, v3
	s_nop 1
	v_cndmask_b32_e64 v11, v11, v12, s[6:7]
	v_mul_f32_e32 v12, 0x37800000, v11
	v_cndmask_b32_e32 v11, v11, v12, vcc
	v_cmp_class_f32_e32 vcc, v13, v225
	s_nop 1
	v_cndmask_b32_e32 v11, v11, v13, vcc
	v_mul_f32_e32 v5, v5, v11
	v_cvt_pk_bf16_f32 v3, v4, v5
	v_cvt_pk_bf16_f32 v4, v6, v7
	v_cvt_pk_bf16_f32 v5, v8, v9
	global_store_dwordx2 v[78:79], v[2:3], off offset:8
	global_store_dwordx2 v[86:87], v[4:5], off offset:8
	s_and_b64 vcc, exec, s[44:45]
	s_cbranch_vccnz .LBB0_777
	s_andn2_b64 vcc, exec, s[24:25]
	s_cbranch_vccnz .LBB0_776
	s_barrier
	s_branch .LBB0_776

; template <class Epi>
; __device__ __forceinline__ void gemm_merge_fused(LAS unsigned char* lds, const bf16_t* Yb, const bf16_t* XBb, const bf16_t* WBR, const bf16_t* WG, const MergeOrder& S, const Epi& E) {
;     ...
;         const int nt = ck ? nt1 : nt0;
;         for (int t = 0; t < nt; t += 2) {
;             const bool last = (t == nt - 2);
;             const int kx = last ? nk : ck;
;             const unsigned la1 = MF_LA(ck), lax = MF_LA(kx), lbx = MF_LB(kx);
;             unsigned voffA1[2] = {Ra0 * la1 + C2, Ra0 * la1 + C2 + 64u * la1};
;             unsigned voffA[2] = {Ra0 * lax + C2, Ra0 * lax + C2 + 64u * lax};
;             unsigned voffB[2] = {Rb0 * lbx + C2, Rb0 * lbx + C2 + 64u * lbx};
;             const size_t hsA1 = (size_t)128 * la1, hsA = (size_t)128 * lax, hsB = (size_t)128 * lbx;
;             const char* a1 = cA + (size_t)(t + 1) * kstep;
;             const char* a2 = last ? nA : cA + (size_t)(t + 2) * kstep; const char* b2 = last ? nB : cB + (size_t)(t + 2) * kstep;
;             const char* a3 = a2 + kstep; const char* b3 = b2 + kstep;
;     ...
; #pragma unroll
;         for (int a = 0; a < 2; ++a)
; #pragma unroll
;             for (int b = 0; b < 2; ++b)
; #pragma unroll
;                 for (int m = 0; m < 4; ++m)
; #pragma unroll
;                     for (int n = 0; n < 2; ++n) acc[a][b][m][n] = (f32x4){0.f, 0.f, 0.f, 0.f};
.LBB0_1329:
	s_cmp_eq_u32 s69, 0
	s_cselect_b64 s[6:7], -1, 0
	s_and_b64 s[8:9], s[6:7], exec
	s_cselect_b32 s21, s49, s48
	s_cmp_lt_i32 s21, 1
	s_cbranch_scc1 .LBB0_1388
	s_add_i32 s23, s21, -2
	s_and_b64 s[6:7], s[6:7], exec
	s_cselect_b32 s36, s12, s46
	s_lshl_b64 s[8:9], s[36:37], 7
	s_add_u32 s6, s40, 0x80
	s_addc_u32 s7, s41, 0
	s_add_u32 s70, s38, 0x100
	s_addc_u32 s71, s39, 0
	v_mad_u64_u32 v[2:3], s[38:39], s36, v197, v[204:205]
	v_mov_b32_e32 v3, v1
	v_lshl_add_u64 v[130:131], s[8:9], 0, v[2:3]
	v_mad_u64_u32 v[2:3], s[38:39], v248, s36, v[204:205]
	v_mov_b32_e32 v3, v1
	v_mov_b32_e32 v26, 0
	v_mov_b64_e32 v[230:231], 0x200
	v_lshl_add_u64 v[132:133], s[8:9], 0, v[2:3]
	s_mov_b32 s72, 0
	v_mov_b32_e32 v27, v26
	v_mov_b32_e32 v28, v26
	v_mov_b32_e32 v29, v26
	v_mov_b32_e32 v30, v26
	v_mov_b32_e32 v31, v26
	v_mov_b32_e32 v32, v26
	v_mov_b32_e32 v33, v26
	s_nop 0
	v_mov_b32_e32 v42, v26
	v_mov_b32_e32 v43, v26
	v_mov_b32_e32 v44, v26
	v_mov_b32_e32 v45, v26
	v_mov_b32_e32 v46, v26
	v_mov_b32_e32 v47, v26
	v_mov_b32_e32 v48, v26
	v_mov_b32_e32 v49, v26
	v_mov_b32_e32 v58, v26
	v_mov_b32_e32 v59, v26
	v_mov_b32_e32 v60, v26
	v_mov_b32_e32 v61, v26
	v_mov_b32_e32 v62, v26
	v_mov_b32_e32 v63, v26
	v_mov_b32_e32 v64, v26
	v_mov_b32_e32 v65, v26
	v_mov_b32_e32 v66, v26
	v_mov_b32_e32 v67, v26
	v_mov_b32_e32 v68, v26
	v_mov_b32_e32 v69, v26
	v_mov_b32_e32 v70, v26
	v_mov_b32_e32 v71, v26
	v_mov_b32_e32 v72, v26
	v_mov_b32_e32 v73, v26
	v_mov_b32_e32 v82, v26
	v_mov_b32_e32 v83, v26
	v_mov_b32_e32 v84, v26
	v_mov_b32_e32 v85, v26
	v_mov_b32_e32 v86, v26
	v_mov_b32_e32 v87, v26
	v_mov_b32_e32 v88, v26
	v_mov_b32_e32 v89, v26
	v_mov_b32_e32 v98, v26
	v_mov_b32_e32 v99, v26
	v_mov_b32_e32 v100, v26
	v_mov_b32_e32 v101, v26
	v_mov_b32_e32 v102, v26
	v_mov_b32_e32 v103, v26
	v_mov_b32_e32 v104, v26
	v_mov_b32_e32 v105, v26
	v_mov_b32_e32 v114, v26
	v_mov_b32_e32 v115, v26
	v_mov_b32_e32 v116, v26
	v_mov_b32_e32 v117, v26
	v_mov_b32_e32 v118, v26
	v_mov_b32_e32 v119, v26
	v_mov_b32_e32 v120, v26
	v_mov_b32_e32 v121, v26
	v_mov_b32_e32 v74, v26
	v_mov_b32_e32 v75, v26
	v_mov_b32_e32 v76, v26
	v_mov_b32_e32 v77, v26
	v_mov_b32_e32 v78, v26
	v_mov_b32_e32 v79, v26
	v_mov_b32_e32 v80, v26
	v_mov_b32_e32 v81, v26
	v_mov_b32_e32 v90, v26
	v_mov_b32_e32 v91, v26
	v_mov_b32_e32 v92, v26
	v_mov_b32_e32 v93, v26
	v_mov_b32_e32 v94, v26
	v_mov_b32_e32 v95, v26
	v_mov_b32_e32 v96, v26
	v_mov_b32_e32 v97, v26
	v_mov_b32_e32 v106, v26
	v_mov_b32_e32 v107, v26
	v_mov_b32_e32 v108, v26
	v_mov_b32_e32 v109, v26
	v_mov_b32_e32 v110, v26
	v_mov_b32_e32 v111, v26
	v_mov_b32_e32 v112, v26
	v_mov_b32_e32 v113, v26
	v_mov_b32_e32 v122, v26
	v_mov_b32_e32 v123, v26
	v_mov_b32_e32 v124, v26
	v_mov_b32_e32 v125, v26
	v_mov_b32_e32 v126, v26
	v_mov_b32_e32 v127, v26
	v_mov_b32_e32 v128, v26
	v_mov_b32_e32 v129, v26
	v_mov_b32_e32 v14, v26
	v_mov_b32_e32 v15, v26
	v_mov_b32_e32 v16, v26
	v_mov_b32_e32 v17, v26
	v_mov_b32_e32 v10, v26
	v_mov_b32_e32 v11, v26
	v_mov_b32_e32 v12, v26
	v_mov_b32_e32 v13, v26
	v_mov_b32_e32 v54, v26
	v_mov_b32_e32 v55, v26
	v_mov_b32_e32 v56, v26
	v_mov_b32_e32 v57, v26
	v_mov_b32_e32 v50, v26
	v_mov_b32_e32 v51, v26
	v_mov_b32_e32 v52, v26
	v_mov_b32_e32 v53, v26
	v_mov_b32_e32 v38, v26
	v_mov_b32_e32 v39, v26
	v_mov_b32_e32 v40, v26
	v_mov_b32_e32 v41, v26
	v_mov_b32_e32 v34, v26
	v_mov_b32_e32 v35, v26
	v_mov_b32_e32 v36, v26
	v_mov_b32_e32 v37, v26
	v_mov_b32_e32 v22, v26
	v_mov_b32_e32 v23, v26
	v_mov_b32_e32 v24, v26
	v_mov_b32_e32 v25, v26
	v_mov_b32_e32 v18, v26
	v_mov_b32_e32 v19, v26
	v_mov_b32_e32 v20, v26
	v_mov_b32_e32 v21, v26
	v_mov_b32_e32 v6, v26
	v_mov_b32_e32 v7, v26
	v_mov_b32_e32 v8, v26
	v_mov_b32_e32 v9, v26
	v_mov_b32_e32 v2, v26
	v_mov_b32_e32 v3, v26
	v_mov_b32_e32 v4, v26
	v_mov_b32_e32 v5, v26

; template <class Epi>
; __device__ __forceinline__ void gemm_merge_fused(LAS unsigned char* lds, const bf16_t* Yb, const bf16_t* XBb, const bf16_t* WBR, const bf16_t* WG, const MergeOrder& S, const Epi& E) {
;     ...
; #pragma unroll
;         for (int a = 0; a < 2; ++a)
; #pragma unroll
;             for (int b = 0; b < 2; ++b)
; #pragma unroll
;                 for (int m = 0; m < 4; ++m)
; #pragma unroll
;                     for (int n = 0; n < 2; ++n) acc[a][b][m][n] = (f32x4){0.f, 0.f, 0.f, 0.f};
;         cur = nxt; cA = nA; cB = nB; ck = nk; ++ui;
.LBB0_1388:
	v_mov_b32_e32 v5, 0
	v_mov_b32_e32 v4, v5
	v_mov_b32_e32 v3, v5
	v_mov_b32_e32 v2, v5
	v_mov_b32_e32 v9, v5
	v_mov_b32_e32 v8, v5
	v_mov_b32_e32 v7, v5
	v_mov_b32_e32 v6, v5
	v_mov_b32_e32 v21, v5
	v_mov_b32_e32 v20, v5
	v_mov_b32_e32 v19, v5
	v_mov_b32_e32 v18, v5
	v_mov_b32_e32 v25, v5
	v_mov_b32_e32 v24, v5
	v_mov_b32_e32 v23, v5
	v_mov_b32_e32 v22, v5
	s_nop 0
	v_mov_b32_e32 v37, v5
	v_mov_b32_e32 v36, v5
	v_mov_b32_e32 v35, v5
	v_mov_b32_e32 v34, v5
	v_mov_b32_e32 v41, v5
	v_mov_b32_e32 v40, v5
	v_mov_b32_e32 v39, v5
	v_mov_b32_e32 v38, v5
	v_mov_b32_e32 v53, v5
	v_mov_b32_e32 v52, v5
	v_mov_b32_e32 v51, v5
	v_mov_b32_e32 v50, v5
	v_mov_b32_e32 v57, v5
	v_mov_b32_e32 v56, v5
	v_mov_b32_e32 v55, v5
	v_mov_b32_e32 v54, v5
	v_mov_b32_e32 v13, v5
	v_mov_b32_e32 v12, v5
	v_mov_b32_e32 v11, v5
	v_mov_b32_e32 v10, v5
	v_mov_b32_e32 v17, v5
	v_mov_b32_e32 v16, v5
	v_mov_b32_e32 v15, v5
	v_mov_b32_e32 v14, v5
	v_mov_b32_e32 v129, v5
	v_mov_b32_e32 v128, v5
	v_mov_b32_e32 v127, v5
	v_mov_b32_e32 v126, v5
	v_mov_b32_e32 v125, v5
	v_mov_b32_e32 v124, v5
	v_mov_b32_e32 v123, v5
	v_mov_b32_e32 v122, v5
	v_mov_b32_e32 v113, v5
	v_mov_b32_e32 v112, v5
	v_mov_b32_e32 v111, v5
	v_mov_b32_e32 v110, v5
	v_mov_b32_e32 v109, v5
	v_mov_b32_e32 v108, v5
	v_mov_b32_e32 v107, v5
	v_mov_b32_e32 v106, v5
	v_mov_b32_e32 v97, v5
	v_mov_b32_e32 v96, v5
	v_mov_b32_e32 v95, v5
	v_mov_b32_e32 v94, v5
	v_mov_b32_e32 v93, v5
	v_mov_b32_e32 v92, v5
	v_mov_b32_e32 v91, v5
	v_mov_b32_e32 v90, v5
	v_mov_b32_e32 v81, v5
	v_mov_b32_e32 v80, v5
	v_mov_b32_e32 v79, v5
	v_mov_b32_e32 v78, v5
	v_mov_b32_e32 v77, v5
	v_mov_b32_e32 v76, v5
	v_mov_b32_e32 v75, v5
	v_mov_b32_e32 v74, v5
	v_mov_b32_e32 v121, v5
	v_mov_b32_e32 v120, v5
	v_mov_b32_e32 v119, v5
	v_mov_b32_e32 v118, v5
	v_mov_b32_e32 v117, v5
	v_mov_b32_e32 v116, v5
	v_mov_b32_e32 v115, v5
	v_mov_b32_e32 v114, v5
	v_mov_b32_e32 v105, v5
	v_mov_b32_e32 v104, v5
	v_mov_b32_e32 v103, v5
	v_mov_b32_e32 v102, v5
	v_mov_b32_e32 v101, v5
	v_mov_b32_e32 v100, v5
	v_mov_b32_e32 v99, v5
	v_mov_b32_e32 v98, v5
	v_mov_b32_e32 v89, v5
	v_mov_b32_e32 v88, v5
	v_mov_b32_e32 v87, v5
	v_mov_b32_e32 v86, v5
	v_mov_b32_e32 v85, v5
	v_mov_b32_e32 v84, v5
	v_mov_b32_e32 v83, v5
	v_mov_b32_e32 v82, v5
	v_mov_b32_e32 v73, v5
	v_mov_b32_e32 v72, v5
	v_mov_b32_e32 v71, v5
	v_mov_b32_e32 v70, v5
	v_mov_b32_e32 v69, v5
	v_mov_b32_e32 v68, v5
	v_mov_b32_e32 v67, v5
	v_mov_b32_e32 v66, v5
	v_mov_b32_e32 v65, v5
	v_mov_b32_e32 v64, v5
	v_mov_b32_e32 v63, v5
	v_mov_b32_e32 v62, v5
	v_mov_b32_e32 v61, v5
	v_mov_b32_e32 v60, v5
	v_mov_b32_e32 v59, v5
	v_mov_b32_e32 v58, v5
	v_mov_b32_e32 v49, v5
	v_mov_b32_e32 v48, v5
	v_mov_b32_e32 v47, v5
	v_mov_b32_e32 v46, v5
	v_mov_b32_e32 v45, v5
	v_mov_b32_e32 v44, v5
	v_mov_b32_e32 v43, v5
	v_mov_b32_e32 v42, v5
	v_mov_b32_e32 v33, v5
	v_mov_b32_e32 v32, v5
	v_mov_b32_e32 v31, v5
	v_mov_b32_e32 v30, v5
	v_mov_b32_e32 v29, v5
	v_mov_b32_e32 v28, v5
	v_mov_b32_e32 v27, v5
	v_mov_b32_e32 v26, v5
	v_mov_b64_e32 v[222:223], 0x1ff
	s_and_b64 vcc, exec, s[18:19]
	s_cbranch_vccnz .LBB0_1333
	s_branch .LBB0_1334
